# GEMM K-loops: LDS-DMA loader role moved to the priority-raised waves 4-7
# baseline (speedup 1.0000x reference)
; template <class AL, class BL>
; DEV void gemm_mainloop_p(Acc& acc, const AL& al, const BL& bl, int m0, int n0, int m0n, int n0n, int K, char* lds,
;                          GemmPipe& gp) {
;   const int tid = tidx_full();
;   const int wave = tid >> 6, lane = tid & 63;
;   const int wm = (wave >> 2) * 128, wn = (wave & 3) * 64;
;   const int lr = lane & 31, lh = lane >> 5;
;   const int nk = K / BK;
;   if (!gp.primed) {
;     gp.ra = al.load(tid, m0, 0);
;     gp.rb = bl.load(tid, n0, 0);
;     __syncthreads();
;     al.store(tid, lds, gp.ra);
;     bl.store(tid, lds + TILE_BYTES, gp.rb);
;     gp.ra = al.load(tid, m0, BK);
;     gp.rb = bl.load(tid, n0, BK);
;     __syncthreads();
;   }
.LBB0_278:
	s_and_b64 vcc, exec, s[2:3]
	s_lshl_b32 s5, s7, 8
	s_lshl_b32 s4, s8, 8
	v_lshrrev_b32_e32 v149, 6, v202
	v_and_b32_e32 v148, 63, v202
	s_nop 0
	v_readfirstlane_b32 s13, v149
	v_lshrrev_b32_e32 v150, 3, v148
	v_and_b32_e32 v151, 3, v149
	v_lshl_add_u32 v150, v151, 5, v150
	v_and_b32_e32 v151, 7, v148
	v_lshrrev_b32_e32 v128, 4, v148
	v_xor_b32_e32 v151, v128, v151
	v_lshlrev_b32_e32 v151, 4, v151
	s_lshl_b32 s13, s13, 12
	v_add_u32_e32 v128, s5, v150
	v_lshlrev_b32_e32 v128, 11, v128
	v_add_u32_e32 v128, v128, v151
	v_add_u32_e32 v129, 0x3c00, v128
	v_add_u32_e32 v130, 0x7800, v128
	v_add_u32_e32 v131, 0xb400, v128
	v_xor_b32_e32 v129, 0x40, v129
	v_xor_b32_e32 v131, 0x40, v131
	v_add_u32_e32 v132, s4, v150
	v_lshlrev_b32_e32 v132, 11, v132
	v_add_u32_e32 v132, v132, v151
	v_add_u32_e32 v133, 0x3c00, v132
	v_add_u32_e32 v134, 0x7800, v132
	v_add_u32_e32 v135, 0xb400, v132
	v_xor_b32_e32 v133, 0x40, v133
	v_xor_b32_e32 v135, 0x40, v135
	v_add_u32_e32 v136, 0x40000, v128
	v_add_u32_e32 v137, 0x40000, v129
	v_add_u32_e32 v138, 0x40000, v130
	v_add_u32_e32 v139, 0x40000, v131
	v_add_u32_e32 v140, 0x40000, v132
	v_add_u32_e32 v141, 0x40000, v133
	v_add_u32_e32 v142, 0x40000, v134
	v_add_u32_e32 v143, 0x40000, v135
	v_lshrrev_b32_e32 v161, 6, v202
	v_and_b32_e32 v160, 63, v202
	v_bfe_u32 v242, v160, 1, 3
	v_lshrrev_b32_e32 v243, 4, v160
	v_xor_b32_e32 v242, v242, v243
	v_lshlrev_b32_e32 v242, 4, v242
	v_and_b32_e32 v243, 15, v160
	v_lshlrev_b32_e32 v243, 7, v243
	v_lshrrev_b32_e32 v144, 2, v161
	v_lshl_add_u32 v144, v144, 14, v243
	v_and_b32_e32 v146, 3, v161
	v_lshl_add_u32 v146, v146, 13, v243
	v_add_u32_e32 v146, 0x10000, v146
	v_xor_b32_e32 v145, 0x40, v242
	v_add_u32_e32 v145, v144, v145
	v_add_u32_e32 v144, v144, v242
	v_xor_b32_e32 v147, 0x40, v242
	v_add_u32_e32 v147, v146, v147
	v_add_u32_e32 v146, v146, v242
	s_mov_b64 s[14:15], s[64:65]
	s_mov_b64 s[16:17], s[24:25]
	s_cbranch_vccnz .Lp1a_primed
	s_cmp_ge_u32 s13, 0x4000
	s_cbranch_scc0 .Lp1a_d1
	s_add_u32 m0, s13, 0xffffc000
	s_nop 0
	global_load_lds_dwordx4 v128, s[14:15]
	global_load_lds_dwordx4 v129, s[14:15] offset:1024
	global_load_lds_dwordx4 v130, s[14:15] offset:2048
	global_load_lds_dwordx4 v131, s[14:15] offset:3072
	s_add_u32 m0, s13, 0xc000
	s_nop 0
	global_load_lds_dwordx4 v132, s[16:17]
	global_load_lds_dwordx4 v133, s[16:17] offset:1024
	global_load_lds_dwordx4 v134, s[16:17] offset:2048
	global_load_lds_dwordx4 v135, s[16:17] offset:3072
	s_add_u32 m0, s13, 0x0
	s_nop 0
	global_load_lds_dwordx4 v136, s[14:15]
	global_load_lds_dwordx4 v137, s[14:15] offset:1024
	global_load_lds_dwordx4 v138, s[14:15] offset:2048
	global_load_lds_dwordx4 v139, s[14:15] offset:3072
	s_add_u32 m0, s13, 0x10000
	s_nop 0
	global_load_lds_dwordx4 v140, s[16:17]
	global_load_lds_dwordx4 v141, s[16:17] offset:1024
	global_load_lds_dwordx4 v142, s[16:17] offset:2048
	global_load_lds_dwordx4 v143, s[16:17] offset:3072

; template <class AL, class BL>
; DEV void gemm_mainloop_p(Acc& acc, const AL& al, const BL& bl, int m0, int n0, int m0n, int n0n, int K, char* lds,
;                          GemmPipe& gp) {
;     ...
;   for (int kt = 0; kt < nk; ++kt) {
;     const char* cur = lds + (kt & 1) * 2 * TILE_BYTES;
;     char* nxt = lds + ((kt + 1) & 1) * 2 * TILE_BYTES;
;     const bool wrap = (kt + 2 >= nk);
;     const int kk = (wrap ? kt + 2 - nk : kt + 2) * BK;
;     const int mr = wrap ? m0n : m0, nr = wrap ? n0n : n0;
;     __builtin_amdgcn_sched_barrier(0);
;     gemm_ktile(acc, cur, cur + TILE_BYTES, wm, wn, lr, lh, al, bl, tid, mr, nr, kk, nxt, gp.ra, gp.rb);
.Lp1a_kloop:
	s_cmp_ge_u32 s13, 0x4000
	s_cbranch_scc0 .Lp1a_d2
	s_add_u32 m0, s13, 0x4000
	s_nop 0
	global_load_lds_dwordx4 v128, s[14:15]
	global_load_lds_dwordx4 v129, s[14:15] offset:1024
	global_load_lds_dwordx4 v130, s[14:15] offset:2048
	global_load_lds_dwordx4 v131, s[14:15] offset:3072
	s_add_u32 m0, s13, 0x14000
	s_nop 0
	global_load_lds_dwordx4 v132, s[16:17]
	global_load_lds_dwordx4 v133, s[16:17] offset:1024
	global_load_lds_dwordx4 v134, s[16:17] offset:2048
	global_load_lds_dwordx4 v135, s[16:17] offset:3072
	s_add_u32 m0, s13, 0x8000
	s_nop 0
	global_load_lds_dwordx4 v136, s[14:15]
	global_load_lds_dwordx4 v137, s[14:15] offset:1024
	global_load_lds_dwordx4 v138, s[14:15] offset:2048
	global_load_lds_dwordx4 v139, s[14:15] offset:3072
	s_add_u32 m0, s13, 0x18000
	s_nop 0
	global_load_lds_dwordx4 v140, s[16:17]
	global_load_lds_dwordx4 v141, s[16:17] offset:1024
	global_load_lds_dwordx4 v142, s[16:17] offset:2048
	global_load_lds_dwordx4 v143, s[16:17] offset:3072
; template <class AL, class BL>
; DEV void gemm_ktile(Acc& acc, const char* A, const char* B, int wm, int wn, int lr, int lh, const AL& al, const BL& bl,
;                     int tid, int m0, int n0, int knext, char* nxt, R4& ra, R4& rb) {
;   bf16x8 a[2][4], b[2][2];
;   const char* pa = A + (wm + lr) * LDSROW + lh * 16;
;   const char* pb = B + (wn + lr) * LDSROW + lh * 16;
; #pragma unroll
;   for (int i = 0; i < 4; ++i) a[0][i] = *(const bf16x8*)(pa + 32 * i * LDSROW);
; #pragma unroll
;   for (int j = 0; j < 2; ++j) b[0][j] = *(const bf16x8*)(pb + 32 * j * LDSROW);
; #pragma unroll
;   for (int ks = 0; ks < 4; ++ks) {
;     const int cur = ks & 1, nx = cur ^ 1;
;     if (ks < 3) {
; #pragma unroll
;       for (int i = 0; i < 4; ++i) a[nx][i] = *(const bf16x8*)(pa + 32 * i * LDSROW + (ks + 1) * 32);
; #pragma unroll
;       for (int j = 0; j < 2; ++j) b[nx][j] = *(const bf16x8*)(pb + 32 * j * LDSROW + (ks + 1) * 32);
;     }
;     __builtin_amdgcn_sched_barrier(0);
; #pragma unroll
;     for (int i = 0; i < 4; ++i)
; #pragma unroll
;       for (int j = 0; j < 2; ++j)
;         acc[i][j] = __builtin_amdgcn_mfma_f32_32x32x16_bf16(a[cur][i], b[cur][j], acc[i][j], 0, 0, 0);
;     __builtin_amdgcn_sched_barrier(0);
;     if (ks == 1) {
;       al.store(tid, nxt, ra);
;       bl.store(tid, nxt + TILE_BYTES, rb);
;       __builtin_amdgcn_sched_barrier(0);
;       ra = al.load(tid, m0, knext);
;       rb = bl.load(tid, n0, knext);
;       __builtin_amdgcn_sched_barrier(0);
;     }
; template <class AL, class BL>
; DEV void gemm_mainloop_p(Acc& acc, const AL& al, const BL& bl, int m0, int n0, int m0n, int n0n, int K, char* lds,
;                          GemmPipe& gp) {
;     ...
;   for (int kt = 0; kt < nk; ++kt) {
;     const char* cur = lds + (kt & 1) * 2 * TILE_BYTES;
;     char* nxt = lds + ((kt + 1) & 1) * 2 * TILE_BYTES;
;     const bool wrap = (kt + 2 >= nk);
;     const int kk = (wrap ? kt + 2 - nk : kt + 2) * BK;
;     const int mr = wrap ? m0n : m0, nr = wrap ? n0n : n0;
;     __builtin_amdgcn_sched_barrier(0);
;     gemm_ktile(acc, cur, cur + TILE_BYTES, wm, wn, lr, lh, al, bl, tid, mr, nr, kk, nxt, gp.ra, gp.rb);
;     __builtin_amdgcn_sched_barrier(0);
;     __syncthreads();
;   }
.Lp1a_d2:
	s_add_u32 s14, s14, 0x80
	s_addc_u32 s15, s15, 0
	s_add_u32 s16, s16, 0x80
	s_addc_u32 s17, s17, 0
	ds_read_b128 v[166:169], v146
	ds_read_b128 v[170:173], v146 offset:2048
	ds_read_b128 v[174:177], v146 offset:4096
	ds_read_b128 v[178:181], v146 offset:6144
	ds_read_b128 v[222:225], v144
	ds_read_b128 v[226:229], v144 offset:2048
	ds_read_b128 v[230:233], v144 offset:4096
	ds_read_b128 v[234:237], v144 offset:6144
	ds_read_b128 v[238:241], v144 offset:8192
	ds_read_b128 v[198:201], v144 offset:10240
	ds_read_b128 v[152:155], v144 offset:12288
	ds_read_b128 v[156:159], v144 offset:14336
	ds_read_b128 v[182:185], v147
	ds_read_b128 v[186:189], v147 offset:2048
	ds_read_b128 v[190:193], v147 offset:4096
	ds_read_b128 v[194:197], v147 offset:6144
	s_waitcnt lgkmcnt(8)
	v_mfma_f32_16x16x32_bf16 v[0:3], v[166:169], v[222:225], v[0:3]
	v_mfma_f32_16x16x32_bf16 v[4:7], v[170:173], v[222:225], v[4:7]
	v_mfma_f32_16x16x32_bf16 v[8:11], v[174:177], v[222:225], v[8:11]
	v_mfma_f32_16x16x32_bf16 v[12:15], v[178:181], v[222:225], v[12:15]
	v_mfma_f32_16x16x32_bf16 v[16:19], v[166:169], v[226:229], v[16:19]
	v_mfma_f32_16x16x32_bf16 v[20:23], v[170:173], v[226:229], v[20:23]
	v_mfma_f32_16x16x32_bf16 v[24:27], v[174:177], v[226:229], v[24:27]
	v_mfma_f32_16x16x32_bf16 v[28:31], v[178:181], v[226:229], v[28:31]
	v_mfma_f32_16x16x32_bf16 v[32:35], v[166:169], v[230:233], v[32:35]
	v_mfma_f32_16x16x32_bf16 v[36:39], v[170:173], v[230:233], v[36:39]
	v_mfma_f32_16x16x32_bf16 v[40:43], v[174:177], v[230:233], v[40:43]
	v_mfma_f32_16x16x32_bf16 v[44:47], v[178:181], v[230:233], v[44:47]
	v_mfma_f32_16x16x32_bf16 v[48:51], v[166:169], v[234:237], v[48:51]
	v_mfma_f32_16x16x32_bf16 v[52:55], v[170:173], v[234:237], v[52:55]
	v_mfma_f32_16x16x32_bf16 v[56:59], v[174:177], v[234:237], v[56:59]
	v_mfma_f32_16x16x32_bf16 v[60:63], v[178:181], v[234:237], v[60:63]
	ds_read_b128 v[222:225], v145
	ds_read_b128 v[226:229], v145 offset:2048
	ds_read_b128 v[230:233], v145 offset:4096
	ds_read_b128 v[234:237], v145 offset:6144
	s_waitcnt lgkmcnt(8)
	v_mfma_f32_16x16x32_bf16 v[64:67], v[166:169], v[238:241], v[64:67]
	v_mfma_f32_16x16x32_bf16 v[68:71], v[170:173], v[238:241], v[68:71]
	v_mfma_f32_16x16x32_bf16 v[72:75], v[174:177], v[238:241], v[72:75]
	v_mfma_f32_16x16x32_bf16 v[76:79], v[178:181], v[238:241], v[76:79]
	v_mfma_f32_16x16x32_bf16 v[80:83], v[166:169], v[198:201], v[80:83]
	v_mfma_f32_16x16x32_bf16 v[84:87], v[170:173], v[198:201], v[84:87]
	v_mfma_f32_16x16x32_bf16 v[88:91], v[174:177], v[198:201], v[88:91]
	v_mfma_f32_16x16x32_bf16 v[92:95], v[178:181], v[198:201], v[92:95]
	v_mfma_f32_16x16x32_bf16 v[96:99], v[166:169], v[152:155], v[96:99]
	v_mfma_f32_16x16x32_bf16 v[100:103], v[170:173], v[152:155], v[100:103]
	v_mfma_f32_16x16x32_bf16 v[104:107], v[174:177], v[152:155], v[104:107]
	v_mfma_f32_16x16x32_bf16 v[108:111], v[178:181], v[152:155], v[108:111]
	v_mfma_f32_16x16x32_bf16 v[112:115], v[166:169], v[156:159], v[112:115]
	v_mfma_f32_16x16x32_bf16 v[116:119], v[170:173], v[156:159], v[116:119]
	v_mfma_f32_16x16x32_bf16 v[120:123], v[174:177], v[156:159], v[120:123]
	v_mfma_f32_16x16x32_bf16 v[124:127], v[178:181], v[156:159], v[124:127]
	ds_read_b128 v[238:241], v145 offset:8192
	ds_read_b128 v[198:201], v145 offset:10240
	ds_read_b128 v[152:155], v145 offset:12288
	ds_read_b128 v[156:159], v145 offset:14336
	s_waitcnt lgkmcnt(4)
	v_mfma_f32_16x16x32_bf16 v[0:3], v[182:185], v[222:225], v[0:3]
	v_mfma_f32_16x16x32_bf16 v[4:7], v[186:189], v[222:225], v[4:7]
	v_mfma_f32_16x16x32_bf16 v[8:11], v[190:193], v[222:225], v[8:11]
	v_mfma_f32_16x16x32_bf16 v[12:15], v[194:197], v[222:225], v[12:15]
	v_mfma_f32_16x16x32_bf16 v[16:19], v[182:185], v[226:229], v[16:19]
	v_mfma_f32_16x16x32_bf16 v[20:23], v[186:189], v[226:229], v[20:23]
	v_mfma_f32_16x16x32_bf16 v[24:27], v[190:193], v[226:229], v[24:27]
	v_mfma_f32_16x16x32_bf16 v[28:31], v[194:197], v[226:229], v[28:31]
	v_mfma_f32_16x16x32_bf16 v[32:35], v[182:185], v[230:233], v[32:35]
	v_mfma_f32_16x16x32_bf16 v[36:39], v[186:189], v[230:233], v[36:39]
	v_mfma_f32_16x16x32_bf16 v[40:43], v[190:193], v[230:233], v[40:43]
	v_mfma_f32_16x16x32_bf16 v[44:47], v[194:197], v[230:233], v[44:47]
	v_mfma_f32_16x16x32_bf16 v[48:51], v[182:185], v[234:237], v[48:51]
	v_mfma_f32_16x16x32_bf16 v[52:55], v[186:189], v[234:237], v[52:55]
	v_mfma_f32_16x16x32_bf16 v[56:59], v[190:193], v[234:237], v[56:59]
	v_mfma_f32_16x16x32_bf16 v[60:63], v[194:197], v[234:237], v[60:63]
	s_waitcnt lgkmcnt(0)
	v_mfma_f32_16x16x32_bf16 v[64:67], v[182:185], v[238:241], v[64:67]
	v_mfma_f32_16x16x32_bf16 v[68:71], v[186:189], v[238:241], v[68:71]
	v_mfma_f32_16x16x32_bf16 v[72:75], v[190:193], v[238:241], v[72:75]
	v_mfma_f32_16x16x32_bf16 v[76:79], v[194:197], v[238:241], v[76:79]
	v_mfma_f32_16x16x32_bf16 v[80:83], v[182:185], v[198:201], v[80:83]
	v_mfma_f32_16x16x32_bf16 v[84:87], v[186:189], v[198:201], v[84:87]
	v_mfma_f32_16x16x32_bf16 v[88:91], v[190:193], v[198:201], v[88:91]
	v_mfma_f32_16x16x32_bf16 v[92:95], v[194:197], v[198:201], v[92:95]
	v_mfma_f32_16x16x32_bf16 v[96:99], v[182:185], v[152:155], v[96:99]
	v_mfma_f32_16x16x32_bf16 v[100:103], v[186:189], v[152:155], v[100:103]
	v_mfma_f32_16x16x32_bf16 v[104:107], v[190:193], v[152:155], v[104:107]
	v_mfma_f32_16x16x32_bf16 v[108:111], v[194:197], v[152:155], v[108:111]
	v_mfma_f32_16x16x32_bf16 v[112:115], v[182:185], v[156:159], v[112:115]
	v_mfma_f32_16x16x32_bf16 v[116:119], v[186:189], v[156:159], v[116:119]
	v_mfma_f32_16x16x32_bf16 v[120:123], v[190:193], v[156:159], v[120:123]
	v_mfma_f32_16x16x32_bf16 v[124:127], v[194:197], v[156:159], v[124:127]
	s_waitcnt vmcnt(0)
	s_barrier
	s_cmp_eq_u32 s18, 7
	s_cbranch_scc1 .Lp1a_last
	s_cmp_ge_u32 s13, 0x4000
	s_cbranch_scc0 .Lp1a_d3
	s_add_u32 m0, s13, 0xffffc000
	s_nop 0
	global_load_lds_dwordx4 v128, s[14:15]
	global_load_lds_dwordx4 v129, s[14:15] offset:1024
	global_load_lds_dwordx4 v130, s[14:15] offset:2048
	global_load_lds_dwordx4 v131, s[14:15] offset:3072
	s_add_u32 m0, s13, 0xc000
	s_nop 0
	global_load_lds_dwordx4 v132, s[16:17]
	global_load_lds_dwordx4 v133, s[16:17] offset:1024
	global_load_lds_dwordx4 v134, s[16:17] offset:2048
	global_load_lds_dwordx4 v135, s[16:17] offset:3072
	s_add_u32 m0, s13, 0x0
	s_nop 0
	global_load_lds_dwordx4 v136, s[14:15]
	global_load_lds_dwordx4 v137, s[14:15] offset:1024
	global_load_lds_dwordx4 v138, s[14:15] offset:2048
	global_load_lds_dwordx4 v139, s[14:15] offset:3072
	s_add_u32 m0, s13, 0x10000
	s_nop 0
	global_load_lds_dwordx4 v140, s[16:17]
	global_load_lds_dwordx4 v141, s[16:17] offset:1024
	global_load_lds_dwordx4 v142, s[16:17] offset:2048
	global_load_lds_dwordx4 v143, s[16:17] offset:3072

; template <class AL, class BL>
; DEV void gemm_ktile(Acc& acc, const char* A, const char* B, int wm, int wn, int lr, int lh, const AL& al, const BL& bl,
;                     int tid, int m0, int n0, int knext, char* nxt, R4& ra, R4& rb) {
;     ...
;   for (int ks = 0; ks < 4; ++ks) {
;     const int cur = ks & 1, nx = cur ^ 1;
;     if (ks < 3) {
; #pragma unroll
;       for (int i = 0; i < 4; ++i) a[nx][i] = *(const bf16x8*)(pa + 32 * i * LDSROW + (ks + 1) * 32);
; #pragma unroll
;       for (int j = 0; j < 2; ++j) b[nx][j] = *(const bf16x8*)(pb + 32 * j * LDSROW + (ks + 1) * 32);
;     }
;     __builtin_amdgcn_sched_barrier(0);
; #pragma unroll
;     for (int i = 0; i < 4; ++i)
; #pragma unroll
;       for (int j = 0; j < 2; ++j)
;         acc[i][j] = __builtin_amdgcn_mfma_f32_32x32x16_bf16(a[cur][i], b[cur][j], acc[i][j], 0, 0, 0);
;     __builtin_amdgcn_sched_barrier(0);
.Lp1a_last:
	ds_read_b128 v[166:169], v146 offset:32768
	ds_read_b128 v[170:173], v146 offset:34816
	ds_read_b128 v[174:177], v146 offset:36864
	ds_read_b128 v[178:181], v146 offset:38912
	ds_read_b128 v[222:225], v144 offset:32768
	ds_read_b128 v[226:229], v144 offset:34816
	ds_read_b128 v[230:233], v144 offset:36864
	ds_read_b128 v[234:237], v144 offset:38912
	ds_read_b128 v[238:241], v144 offset:40960
	ds_read_b128 v[198:201], v144 offset:43008
	ds_read_b128 v[152:155], v144 offset:45056
	ds_read_b128 v[156:159], v144 offset:47104
	ds_read_b128 v[182:185], v147 offset:32768
	ds_read_b128 v[186:189], v147 offset:34816
	ds_read_b128 v[190:193], v147 offset:36864
	ds_read_b128 v[194:197], v147 offset:38912
	s_waitcnt lgkmcnt(8)
	v_mfma_f32_16x16x32_bf16 v[0:3], v[166:169], v[222:225], v[0:3]
	v_mfma_f32_16x16x32_bf16 v[4:7], v[170:173], v[222:225], v[4:7]
	v_mfma_f32_16x16x32_bf16 v[8:11], v[174:177], v[222:225], v[8:11]
	v_mfma_f32_16x16x32_bf16 v[12:15], v[178:181], v[222:225], v[12:15]
	v_mfma_f32_16x16x32_bf16 v[16:19], v[166:169], v[226:229], v[16:19]
	v_mfma_f32_16x16x32_bf16 v[20:23], v[170:173], v[226:229], v[20:23]
	v_mfma_f32_16x16x32_bf16 v[24:27], v[174:177], v[226:229], v[24:27]
	v_mfma_f32_16x16x32_bf16 v[28:31], v[178:181], v[226:229], v[28:31]
	v_mfma_f32_16x16x32_bf16 v[32:35], v[166:169], v[230:233], v[32:35]
	v_mfma_f32_16x16x32_bf16 v[36:39], v[170:173], v[230:233], v[36:39]
	v_mfma_f32_16x16x32_bf16 v[40:43], v[174:177], v[230:233], v[40:43]
	v_mfma_f32_16x16x32_bf16 v[44:47], v[178:181], v[230:233], v[44:47]
	v_mfma_f32_16x16x32_bf16 v[48:51], v[166:169], v[234:237], v[48:51]
	v_mfma_f32_16x16x32_bf16 v[52:55], v[170:173], v[234:237], v[52:55]
	v_mfma_f32_16x16x32_bf16 v[56:59], v[174:177], v[234:237], v[56:59]
	v_mfma_f32_16x16x32_bf16 v[60:63], v[178:181], v[234:237], v[60:63]
	ds_read_b128 v[222:225], v145 offset:32768
	ds_read_b128 v[226:229], v145 offset:34816
	ds_read_b128 v[230:233], v145 offset:36864
	ds_read_b128 v[234:237], v145 offset:38912
	s_waitcnt lgkmcnt(8)
	v_mfma_f32_16x16x32_bf16 v[64:67], v[166:169], v[238:241], v[64:67]
	v_mfma_f32_16x16x32_bf16 v[68:71], v[170:173], v[238:241], v[68:71]
	v_mfma_f32_16x16x32_bf16 v[72:75], v[174:177], v[238:241], v[72:75]
	v_mfma_f32_16x16x32_bf16 v[76:79], v[178:181], v[238:241], v[76:79]
	v_mfma_f32_16x16x32_bf16 v[80:83], v[166:169], v[198:201], v[80:83]
	v_mfma_f32_16x16x32_bf16 v[84:87], v[170:173], v[198:201], v[84:87]
	v_mfma_f32_16x16x32_bf16 v[88:91], v[174:177], v[198:201], v[88:91]
	v_mfma_f32_16x16x32_bf16 v[92:95], v[178:181], v[198:201], v[92:95]
	v_mfma_f32_16x16x32_bf16 v[96:99], v[166:169], v[152:155], v[96:99]
	v_mfma_f32_16x16x32_bf16 v[100:103], v[170:173], v[152:155], v[100:103]
	v_mfma_f32_16x16x32_bf16 v[104:107], v[174:177], v[152:155], v[104:107]
	v_mfma_f32_16x16x32_bf16 v[108:111], v[178:181], v[152:155], v[108:111]
	v_mfma_f32_16x16x32_bf16 v[112:115], v[166:169], v[156:159], v[112:115]
	v_mfma_f32_16x16x32_bf16 v[116:119], v[170:173], v[156:159], v[116:119]
	v_mfma_f32_16x16x32_bf16 v[120:123], v[174:177], v[156:159], v[120:123]
	v_mfma_f32_16x16x32_bf16 v[124:127], v[178:181], v[156:159], v[124:127]
	ds_read_b128 v[238:241], v145 offset:40960
	ds_read_b128 v[198:201], v145 offset:43008
	ds_read_b128 v[152:155], v145 offset:45056
	ds_read_b128 v[156:159], v145 offset:47104
	s_waitcnt lgkmcnt(4)
	v_mfma_f32_16x16x32_bf16 v[0:3], v[182:185], v[222:225], v[0:3]
	v_mfma_f32_16x16x32_bf16 v[4:7], v[186:189], v[222:225], v[4:7]
	v_mfma_f32_16x16x32_bf16 v[8:11], v[190:193], v[222:225], v[8:11]
	v_mfma_f32_16x16x32_bf16 v[12:15], v[194:197], v[222:225], v[12:15]
	v_mfma_f32_16x16x32_bf16 v[16:19], v[182:185], v[226:229], v[16:19]
	v_mfma_f32_16x16x32_bf16 v[20:23], v[186:189], v[226:229], v[20:23]
	v_mfma_f32_16x16x32_bf16 v[24:27], v[190:193], v[226:229], v[24:27]
	v_mfma_f32_16x16x32_bf16 v[28:31], v[194:197], v[226:229], v[28:31]
	v_mfma_f32_16x16x32_bf16 v[32:35], v[182:185], v[230:233], v[32:35]
	v_mfma_f32_16x16x32_bf16 v[36:39], v[186:189], v[230:233], v[36:39]
	v_mfma_f32_16x16x32_bf16 v[40:43], v[190:193], v[230:233], v[40:43]
	v_mfma_f32_16x16x32_bf16 v[44:47], v[194:197], v[230:233], v[44:47]
	v_mfma_f32_16x16x32_bf16 v[48:51], v[182:185], v[234:237], v[48:51]
	v_mfma_f32_16x16x32_bf16 v[52:55], v[186:189], v[234:237], v[52:55]
	v_mfma_f32_16x16x32_bf16 v[56:59], v[190:193], v[234:237], v[56:59]
	v_mfma_f32_16x16x32_bf16 v[60:63], v[194:197], v[234:237], v[60:63]
	s_waitcnt lgkmcnt(0)
	v_mfma_f32_16x16x32_bf16 v[64:67], v[182:185], v[238:241], v[64:67]
	v_mfma_f32_16x16x32_bf16 v[68:71], v[186:189], v[238:241], v[68:71]
	v_mfma_f32_16x16x32_bf16 v[72:75], v[190:193], v[238:241], v[72:75]
	v_mfma_f32_16x16x32_bf16 v[76:79], v[194:197], v[238:241], v[76:79]
	v_mfma_f32_16x16x32_bf16 v[80:83], v[182:185], v[198:201], v[80:83]
	v_mfma_f32_16x16x32_bf16 v[84:87], v[186:189], v[198:201], v[84:87]
	v_mfma_f32_16x16x32_bf16 v[88:91], v[190:193], v[198:201], v[88:91]
	v_mfma_f32_16x16x32_bf16 v[92:95], v[194:197], v[198:201], v[92:95]
	v_mfma_f32_16x16x32_bf16 v[96:99], v[182:185], v[152:155], v[96:99]
	v_mfma_f32_16x16x32_bf16 v[100:103], v[186:189], v[152:155], v[100:103]
	v_mfma_f32_16x16x32_bf16 v[104:107], v[190:193], v[152:155], v[104:107]
	v_mfma_f32_16x16x32_bf16 v[108:111], v[194:197], v[152:155], v[108:111]
	v_mfma_f32_16x16x32_bf16 v[112:115], v[182:185], v[156:159], v[112:115]
	v_mfma_f32_16x16x32_bf16 v[116:119], v[186:189], v[156:159], v[116:119]
	v_mfma_f32_16x16x32_bf16 v[120:123], v[190:193], v[156:159], v[120:123]
	v_mfma_f32_16x16x32_bf16 v[124:127], v[194:197], v[156:159], v[124:127]
	s_barrier
; template <class AL, class BL>
; DEV void gemm_mainloop_p(Acc& acc, const AL& al, const BL& bl, int m0, int n0, int m0n, int n0n, int K, char* lds,
;                          GemmPipe& gp) {
;     ...
;   if (!gp.primed) {
;     gp.ra = al.load(tid, m0, 0);
;     gp.rb = bl.load(tid, n0, 0);
;     __syncthreads();
;     al.store(tid, lds, gp.ra);
;     bl.store(tid, lds + TILE_BYTES, gp.rb);
;     gp.ra = al.load(tid, m0, BK);
;     gp.rb = bl.load(tid, n0, BK);
;     __syncthreads();
;   }
;   for (int kt = 0; kt < nk; ++kt) {
;     const char* cur = lds + (kt & 1) * 2 * TILE_BYTES;
;     char* nxt = lds + ((kt + 1) & 1) * 2 * TILE_BYTES;
;     const bool wrap = (kt + 2 >= nk);
;     const int kk = (wrap ? kt + 2 - nk : kt + 2) * BK;
;     const int mr = wrap ? m0n : m0, nr = wrap ? n0n : n0;
;     __builtin_amdgcn_sched_barrier(0);
;     gemm_ktile(acc, cur, cur + TILE_BYTES, wm, wn, lr, lh, al, bl, tid, mr, nr, kk, nxt, gp.ra, gp.rb);
	s_and_b64 vcc, exec, s[0:1]
	s_cbranch_vccz .Lp1a_nomore
	s_lshl_b32 s9, s11, 8
	s_lshl_b32 s10, s12, 8
	v_add_u32_e32 v128, s9, v150
	v_lshlrev_b32_e32 v128, 11, v128
	v_add_u32_e32 v128, v128, v151
	v_add_u32_e32 v129, 0x3c00, v128
	v_add_u32_e32 v130, 0x7800, v128
	v_add_u32_e32 v131, 0xb400, v128
	v_xor_b32_e32 v129, 0x40, v129
	v_xor_b32_e32 v131, 0x40, v131
	v_add_u32_e32 v132, s10, v150
	v_lshlrev_b32_e32 v132, 11, v132
	v_add_u32_e32 v132, v132, v151
	v_add_u32_e32 v133, 0x3c00, v132
	v_add_u32_e32 v134, 0x7800, v132
	v_add_u32_e32 v135, 0xb400, v132
	v_xor_b32_e32 v133, 0x40, v133
	v_xor_b32_e32 v135, 0x40, v135
	v_add_u32_e32 v136, 0x40000, v128
	v_add_u32_e32 v137, 0x40000, v129
	v_add_u32_e32 v138, 0x40000, v130
	v_add_u32_e32 v139, 0x40000, v131
	v_add_u32_e32 v140, 0x40000, v132
	v_add_u32_e32 v141, 0x40000, v133
	v_add_u32_e32 v142, 0x40000, v134
	v_add_u32_e32 v143, 0x40000, v135
	s_mov_b64 s[14:15], s[64:65]
	s_mov_b64 s[16:17], s[24:25]
	s_cmp_ge_u32 s13, 0x4000
	s_cbranch_scc0 .Lp1a_d4
	s_add_u32 m0, s13, 0xffffc000
	s_nop 0
	global_load_lds_dwordx4 v128, s[14:15]
	global_load_lds_dwordx4 v129, s[14:15] offset:1024
	global_load_lds_dwordx4 v130, s[14:15] offset:2048
	global_load_lds_dwordx4 v131, s[14:15] offset:3072
	s_add_u32 m0, s13, 0xc000
	s_nop 0
	global_load_lds_dwordx4 v132, s[16:17]
	global_load_lds_dwordx4 v133, s[16:17] offset:1024
	global_load_lds_dwordx4 v134, s[16:17] offset:2048
	global_load_lds_dwordx4 v135, s[16:17] offset:3072
	s_add_u32 m0, s13, 0x0
	s_nop 0
	global_load_lds_dwordx4 v136, s[14:15]
	global_load_lds_dwordx4 v137, s[14:15] offset:1024
	global_load_lds_dwordx4 v138, s[14:15] offset:2048
	global_load_lds_dwordx4 v139, s[14:15] offset:3072
	s_add_u32 m0, s13, 0x10000
	s_nop 0
	global_load_lds_dwordx4 v140, s[16:17]
	global_load_lds_dwordx4 v141, s[16:17] offset:1024
	global_load_lds_dwordx4 v142, s[16:17] offset:2048
	global_load_lds_dwordx4 v143, s[16:17] offset:3072

; template <class AL, class BL>
; DEV void gemm_mainloop_p(Acc& acc, const AL& al, const BL& bl, int m0, int n0, int m0n, int n0n, int K, char* lds,
;                          GemmPipe& gp) {
;   const int tid = tidx_full();
;   const int wave = tid >> 6, lane = tid & 63;
;   const int wm = (wave >> 2) * 128, wn = (wave & 3) * 64;
;   const int lr = lane & 31, lh = lane >> 5;
;   const int nk = K / BK;
;   if (!gp.primed) {
;     gp.ra = al.load(tid, m0, 0);
;     gp.rb = bl.load(tid, n0, 0);
;     __syncthreads();
;     al.store(tid, lds, gp.ra);
;     bl.store(tid, lds + TILE_BYTES, gp.rb);
;     gp.ra = al.load(tid, m0, BK);
;     gp.rb = bl.load(tid, n0, BK);
;     __syncthreads();
;   }
.LBB0_560:
	s_and_b64 vcc, exec, s[2:3]
	s_lshl_b32 s11, s7, 8
	s_lshl_b32 s2, s8, 8
	v_lshrrev_b32_e32 v149, 6, v202
	v_and_b32_e32 v148, 63, v202
	s_nop 0
	v_readfirstlane_b32 s9, v149
	v_lshrrev_b32_e32 v150, 3, v148
	v_and_b32_e32 v151, 3, v149
	v_lshl_add_u32 v150, v151, 5, v150
	v_and_b32_e32 v151, 7, v148
	v_lshrrev_b32_e32 v128, 4, v148
	v_xor_b32_e32 v151, v128, v151
	v_lshlrev_b32_e32 v151, 4, v151
	s_lshl_b32 s9, s9, 12
	v_add_u32_e32 v128, s11, v150
	v_lshlrev_b32_e32 v128, 11, v128
	v_add_u32_e32 v128, v128, v151
	v_add_u32_e32 v129, 0x3c00, v128
	v_add_u32_e32 v130, 0x7800, v128
	v_add_u32_e32 v131, 0xb400, v128
	v_xor_b32_e32 v129, 0x40, v129
	v_xor_b32_e32 v131, 0x40, v131
	v_add_u32_e32 v132, s2, v150
	v_lshlrev_b32_e32 v132, 11, v132
	v_add_u32_e32 v132, v132, v151
	v_add_u32_e32 v133, 0x3c00, v132
	v_add_u32_e32 v134, 0x7800, v132
	v_add_u32_e32 v135, 0xb400, v132
	v_xor_b32_e32 v133, 0x40, v133
	v_xor_b32_e32 v135, 0x40, v135
	v_add_u32_e32 v136, 0x40000, v128
	v_add_u32_e32 v137, 0x40000, v129
	v_add_u32_e32 v138, 0x40000, v130
	v_add_u32_e32 v139, 0x40000, v131
	v_add_u32_e32 v140, 0x40000, v132
	v_add_u32_e32 v141, 0x40000, v133
	v_add_u32_e32 v142, 0x40000, v134
	v_add_u32_e32 v143, 0x40000, v135
	v_lshrrev_b32_e32 v161, 6, v202
	v_and_b32_e32 v160, 63, v202
	v_bfe_u32 v242, v160, 1, 3
	v_lshrrev_b32_e32 v243, 4, v160
	v_xor_b32_e32 v242, v242, v243
	v_lshlrev_b32_e32 v242, 4, v242
	v_and_b32_e32 v243, 15, v160
	v_lshlrev_b32_e32 v243, 7, v243
	v_lshrrev_b32_e32 v144, 2, v161
	v_lshl_add_u32 v144, v144, 14, v243
	v_and_b32_e32 v146, 3, v161
	v_lshl_add_u32 v146, v146, 13, v243
	v_add_u32_e32 v146, 0x10000, v146
	v_xor_b32_e32 v145, 0x40, v242
	v_add_u32_e32 v145, v144, v145
	v_add_u32_e32 v144, v144, v242
	v_xor_b32_e32 v147, 0x40, v242
	v_add_u32_e32 v147, v146, v147
	v_add_u32_e32 v146, v146, v242
	s_mov_b64 s[14:15], s[88:89]
	s_mov_b64 s[16:17], s[64:65]
	s_cbranch_vccnz .Lp1b_primed
	s_cmp_ge_u32 s9, 0x4000
	s_cbranch_scc0 .Lp1b_d1
	s_add_u32 m0, s9, 0xffffc000
	s_nop 0
	global_load_lds_dwordx4 v128, s[14:15]
	global_load_lds_dwordx4 v129, s[14:15] offset:1024
	global_load_lds_dwordx4 v130, s[14:15] offset:2048
	global_load_lds_dwordx4 v131, s[14:15] offset:3072
	s_add_u32 m0, s9, 0xc000
	s_nop 0
	global_load_lds_dwordx4 v132, s[16:17]
	global_load_lds_dwordx4 v133, s[16:17] offset:1024
	global_load_lds_dwordx4 v134, s[16:17] offset:2048
	global_load_lds_dwordx4 v135, s[16:17] offset:3072
	s_add_u32 m0, s9, 0x0
	s_nop 0
	global_load_lds_dwordx4 v136, s[14:15]
	global_load_lds_dwordx4 v137, s[14:15] offset:1024
	global_load_lds_dwordx4 v138, s[14:15] offset:2048
	global_load_lds_dwordx4 v139, s[14:15] offset:3072
	s_add_u32 m0, s9, 0x10000
	s_nop 0
	global_load_lds_dwordx4 v140, s[16:17]
	global_load_lds_dwordx4 v141, s[16:17] offset:1024
	global_load_lds_dwordx4 v142, s[16:17] offset:2048
	global_load_lds_dwordx4 v143, s[16:17] offset:3072

; template <class AL, class BL>
; DEV void gemm_mainloop_p(Acc& acc, const AL& al, const BL& bl, int m0, int n0, int m0n, int n0n, int K, char* lds,
;                          GemmPipe& gp) {
;     ...
;   for (int kt = 0; kt < nk; ++kt) {
;     const char* cur = lds + (kt & 1) * 2 * TILE_BYTES;
;     char* nxt = lds + ((kt + 1) & 1) * 2 * TILE_BYTES;
;     const bool wrap = (kt + 2 >= nk);
;     const int kk = (wrap ? kt + 2 - nk : kt + 2) * BK;
;     const int mr = wrap ? m0n : m0, nr = wrap ? n0n : n0;
;     __builtin_amdgcn_sched_barrier(0);
;     gemm_ktile(acc, cur, cur + TILE_BYTES, wm, wn, lr, lh, al, bl, tid, mr, nr, kk, nxt, gp.ra, gp.rb);
.Lp1b_kloop:
	s_cmp_ge_u32 s9, 0x4000
	s_cbranch_scc0 .Lp1b_d2
	s_add_u32 m0, s9, 0x4000
	s_nop 0
	global_load_lds_dwordx4 v128, s[14:15]
	global_load_lds_dwordx4 v129, s[14:15] offset:1024
	global_load_lds_dwordx4 v130, s[14:15] offset:2048
	global_load_lds_dwordx4 v131, s[14:15] offset:3072
	s_add_u32 m0, s9, 0x14000
	s_nop 0
	global_load_lds_dwordx4 v132, s[16:17]
	global_load_lds_dwordx4 v133, s[16:17] offset:1024
	global_load_lds_dwordx4 v134, s[16:17] offset:2048
	global_load_lds_dwordx4 v135, s[16:17] offset:3072
	s_add_u32 m0, s9, 0x8000
	s_nop 0
	global_load_lds_dwordx4 v136, s[14:15]
	global_load_lds_dwordx4 v137, s[14:15] offset:1024
	global_load_lds_dwordx4 v138, s[14:15] offset:2048
	global_load_lds_dwordx4 v139, s[14:15] offset:3072
	s_add_u32 m0, s9, 0x18000
	s_nop 0
	global_load_lds_dwordx4 v140, s[16:17]
	global_load_lds_dwordx4 v141, s[16:17] offset:1024
	global_load_lds_dwordx4 v142, s[16:17] offset:2048
	global_load_lds_dwordx4 v143, s[16:17] offset:3072
; template <class AL, class BL>
; DEV void gemm_ktile(Acc& acc, const char* A, const char* B, int wm, int wn, int lr, int lh, const AL& al, const BL& bl,
;                     int tid, int m0, int n0, int knext, char* nxt, R4& ra, R4& rb) {
;   bf16x8 a[2][4], b[2][2];
;   const char* pa = A + (wm + lr) * LDSROW + lh * 16;
;   const char* pb = B + (wn + lr) * LDSROW + lh * 16;
; #pragma unroll
;   for (int i = 0; i < 4; ++i) a[0][i] = *(const bf16x8*)(pa + 32 * i * LDSROW);
; #pragma unroll
;   for (int j = 0; j < 2; ++j) b[0][j] = *(const bf16x8*)(pb + 32 * j * LDSROW);
; #pragma unroll
;   for (int ks = 0; ks < 4; ++ks) {
;     const int cur = ks & 1, nx = cur ^ 1;
;     if (ks < 3) {
; #pragma unroll
;       for (int i = 0; i < 4; ++i) a[nx][i] = *(const bf16x8*)(pa + 32 * i * LDSROW + (ks + 1) * 32);
; #pragma unroll
;       for (int j = 0; j < 2; ++j) b[nx][j] = *(const bf16x8*)(pb + 32 * j * LDSROW + (ks + 1) * 32);
;     }
;     __builtin_amdgcn_sched_barrier(0);
; #pragma unroll
;     for (int i = 0; i < 4; ++i)
; #pragma unroll
;       for (int j = 0; j < 2; ++j)
;         acc[i][j] = __builtin_amdgcn_mfma_f32_32x32x16_bf16(a[cur][i], b[cur][j], acc[i][j], 0, 0, 0);
;     __builtin_amdgcn_sched_barrier(0);
;     if (ks == 1) {
;       al.store(tid, nxt, ra);
;       bl.store(tid, nxt + TILE_BYTES, rb);
;       __builtin_amdgcn_sched_barrier(0);
;       ra = al.load(tid, m0, knext);
;       rb = bl.load(tid, n0, knext);
;       __builtin_amdgcn_sched_barrier(0);
;     }
; template <class AL, class BL>
; DEV void gemm_mainloop_p(Acc& acc, const AL& al, const BL& bl, int m0, int n0, int m0n, int n0n, int K, char* lds,
;                          GemmPipe& gp) {
;     ...
;   for (int kt = 0; kt < nk; ++kt) {
;     const char* cur = lds + (kt & 1) * 2 * TILE_BYTES;
;     char* nxt = lds + ((kt + 1) & 1) * 2 * TILE_BYTES;
;     const bool wrap = (kt + 2 >= nk);
;     const int kk = (wrap ? kt + 2 - nk : kt + 2) * BK;
;     const int mr = wrap ? m0n : m0, nr = wrap ? n0n : n0;
;     __builtin_amdgcn_sched_barrier(0);
;     gemm_ktile(acc, cur, cur + TILE_BYTES, wm, wn, lr, lh, al, bl, tid, mr, nr, kk, nxt, gp.ra, gp.rb);
;     __builtin_amdgcn_sched_barrier(0);
;     __syncthreads();
;   }
.Lp1b_d2:
	s_add_u32 s14, s14, 0x80
	s_addc_u32 s15, s15, 0
	s_add_u32 s16, s16, 0x80
	s_addc_u32 s17, s17, 0
	ds_read_b128 v[166:169], v146
	ds_read_b128 v[170:173], v146 offset:2048
	ds_read_b128 v[174:177], v146 offset:4096
	ds_read_b128 v[178:181], v146 offset:6144
	ds_read_b128 v[222:225], v144
	ds_read_b128 v[226:229], v144 offset:2048
	ds_read_b128 v[230:233], v144 offset:4096
	ds_read_b128 v[234:237], v144 offset:6144
	ds_read_b128 v[238:241], v144 offset:8192
	ds_read_b128 v[198:201], v144 offset:10240
	ds_read_b128 v[152:155], v144 offset:12288
	ds_read_b128 v[156:159], v144 offset:14336
	ds_read_b128 v[182:185], v147
	ds_read_b128 v[186:189], v147 offset:2048
	ds_read_b128 v[190:193], v147 offset:4096
	ds_read_b128 v[194:197], v147 offset:6144
	s_waitcnt lgkmcnt(8)
	v_mfma_f32_16x16x32_bf16 v[0:3], v[166:169], v[222:225], v[0:3]
	v_mfma_f32_16x16x32_bf16 v[4:7], v[170:173], v[222:225], v[4:7]
	v_mfma_f32_16x16x32_bf16 v[8:11], v[174:177], v[222:225], v[8:11]
	v_mfma_f32_16x16x32_bf16 v[12:15], v[178:181], v[222:225], v[12:15]
	v_mfma_f32_16x16x32_bf16 v[16:19], v[166:169], v[226:229], v[16:19]
	v_mfma_f32_16x16x32_bf16 v[20:23], v[170:173], v[226:229], v[20:23]
	v_mfma_f32_16x16x32_bf16 v[24:27], v[174:177], v[226:229], v[24:27]
	v_mfma_f32_16x16x32_bf16 v[28:31], v[178:181], v[226:229], v[28:31]
	v_mfma_f32_16x16x32_bf16 v[32:35], v[166:169], v[230:233], v[32:35]
	v_mfma_f32_16x16x32_bf16 v[36:39], v[170:173], v[230:233], v[36:39]
	v_mfma_f32_16x16x32_bf16 v[40:43], v[174:177], v[230:233], v[40:43]
	v_mfma_f32_16x16x32_bf16 v[44:47], v[178:181], v[230:233], v[44:47]
	v_mfma_f32_16x16x32_bf16 v[48:51], v[166:169], v[234:237], v[48:51]
	v_mfma_f32_16x16x32_bf16 v[52:55], v[170:173], v[234:237], v[52:55]
	v_mfma_f32_16x16x32_bf16 v[56:59], v[174:177], v[234:237], v[56:59]
	v_mfma_f32_16x16x32_bf16 v[60:63], v[178:181], v[234:237], v[60:63]
	ds_read_b128 v[222:225], v145
	ds_read_b128 v[226:229], v145 offset:2048
	ds_read_b128 v[230:233], v145 offset:4096
	ds_read_b128 v[234:237], v145 offset:6144
	s_waitcnt lgkmcnt(8)
	v_mfma_f32_16x16x32_bf16 v[64:67], v[166:169], v[238:241], v[64:67]
	v_mfma_f32_16x16x32_bf16 v[68:71], v[170:173], v[238:241], v[68:71]
	v_mfma_f32_16x16x32_bf16 v[72:75], v[174:177], v[238:241], v[72:75]
	v_mfma_f32_16x16x32_bf16 v[76:79], v[178:181], v[238:241], v[76:79]
	v_mfma_f32_16x16x32_bf16 v[80:83], v[166:169], v[198:201], v[80:83]
	v_mfma_f32_16x16x32_bf16 v[84:87], v[170:173], v[198:201], v[84:87]
	v_mfma_f32_16x16x32_bf16 v[88:91], v[174:177], v[198:201], v[88:91]
	v_mfma_f32_16x16x32_bf16 v[92:95], v[178:181], v[198:201], v[92:95]
	v_mfma_f32_16x16x32_bf16 v[96:99], v[166:169], v[152:155], v[96:99]
	v_mfma_f32_16x16x32_bf16 v[100:103], v[170:173], v[152:155], v[100:103]
	v_mfma_f32_16x16x32_bf16 v[104:107], v[174:177], v[152:155], v[104:107]
	v_mfma_f32_16x16x32_bf16 v[108:111], v[178:181], v[152:155], v[108:111]
	v_mfma_f32_16x16x32_bf16 v[112:115], v[166:169], v[156:159], v[112:115]
	v_mfma_f32_16x16x32_bf16 v[116:119], v[170:173], v[156:159], v[116:119]
	v_mfma_f32_16x16x32_bf16 v[120:123], v[174:177], v[156:159], v[120:123]
	v_mfma_f32_16x16x32_bf16 v[124:127], v[178:181], v[156:159], v[124:127]
	ds_read_b128 v[238:241], v145 offset:8192
	ds_read_b128 v[198:201], v145 offset:10240
	ds_read_b128 v[152:155], v145 offset:12288
	ds_read_b128 v[156:159], v145 offset:14336
	s_waitcnt lgkmcnt(4)
	v_mfma_f32_16x16x32_bf16 v[0:3], v[182:185], v[222:225], v[0:3]
	v_mfma_f32_16x16x32_bf16 v[4:7], v[186:189], v[222:225], v[4:7]
	v_mfma_f32_16x16x32_bf16 v[8:11], v[190:193], v[222:225], v[8:11]
	v_mfma_f32_16x16x32_bf16 v[12:15], v[194:197], v[222:225], v[12:15]
	v_mfma_f32_16x16x32_bf16 v[16:19], v[182:185], v[226:229], v[16:19]
	v_mfma_f32_16x16x32_bf16 v[20:23], v[186:189], v[226:229], v[20:23]
	v_mfma_f32_16x16x32_bf16 v[24:27], v[190:193], v[226:229], v[24:27]
	v_mfma_f32_16x16x32_bf16 v[28:31], v[194:197], v[226:229], v[28:31]
	v_mfma_f32_16x16x32_bf16 v[32:35], v[182:185], v[230:233], v[32:35]
	v_mfma_f32_16x16x32_bf16 v[36:39], v[186:189], v[230:233], v[36:39]
	v_mfma_f32_16x16x32_bf16 v[40:43], v[190:193], v[230:233], v[40:43]
	v_mfma_f32_16x16x32_bf16 v[44:47], v[194:197], v[230:233], v[44:47]
	v_mfma_f32_16x16x32_bf16 v[48:51], v[182:185], v[234:237], v[48:51]
	v_mfma_f32_16x16x32_bf16 v[52:55], v[186:189], v[234:237], v[52:55]
	v_mfma_f32_16x16x32_bf16 v[56:59], v[190:193], v[234:237], v[56:59]
	v_mfma_f32_16x16x32_bf16 v[60:63], v[194:197], v[234:237], v[60:63]
	s_waitcnt lgkmcnt(0)
	v_mfma_f32_16x16x32_bf16 v[64:67], v[182:185], v[238:241], v[64:67]
	v_mfma_f32_16x16x32_bf16 v[68:71], v[186:189], v[238:241], v[68:71]
	v_mfma_f32_16x16x32_bf16 v[72:75], v[190:193], v[238:241], v[72:75]
	v_mfma_f32_16x16x32_bf16 v[76:79], v[194:197], v[238:241], v[76:79]
	v_mfma_f32_16x16x32_bf16 v[80:83], v[182:185], v[198:201], v[80:83]
	v_mfma_f32_16x16x32_bf16 v[84:87], v[186:189], v[198:201], v[84:87]
	v_mfma_f32_16x16x32_bf16 v[88:91], v[190:193], v[198:201], v[88:91]
	v_mfma_f32_16x16x32_bf16 v[92:95], v[194:197], v[198:201], v[92:95]
	v_mfma_f32_16x16x32_bf16 v[96:99], v[182:185], v[152:155], v[96:99]
	v_mfma_f32_16x16x32_bf16 v[100:103], v[186:189], v[152:155], v[100:103]
	v_mfma_f32_16x16x32_bf16 v[104:107], v[190:193], v[152:155], v[104:107]
	v_mfma_f32_16x16x32_bf16 v[108:111], v[194:197], v[152:155], v[108:111]
	v_mfma_f32_16x16x32_bf16 v[112:115], v[182:185], v[156:159], v[112:115]
	v_mfma_f32_16x16x32_bf16 v[116:119], v[186:189], v[156:159], v[116:119]
	v_mfma_f32_16x16x32_bf16 v[120:123], v[190:193], v[156:159], v[120:123]
	v_mfma_f32_16x16x32_bf16 v[124:127], v[194:197], v[156:159], v[124:127]
	s_waitcnt vmcnt(0)
	s_barrier
	s_cmp_eq_u32 s10, 7
	s_cbranch_scc1 .Lp1b_last
	s_cmp_ge_u32 s9, 0x4000
	s_cbranch_scc0 .Lp1b_d3
	s_add_u32 m0, s9, 0xffffc000
	s_nop 0
	global_load_lds_dwordx4 v128, s[14:15]
	global_load_lds_dwordx4 v129, s[14:15] offset:1024
	global_load_lds_dwordx4 v130, s[14:15] offset:2048
	global_load_lds_dwordx4 v131, s[14:15] offset:3072
	s_add_u32 m0, s9, 0xc000
	s_nop 0
	global_load_lds_dwordx4 v132, s[16:17]
	global_load_lds_dwordx4 v133, s[16:17] offset:1024
	global_load_lds_dwordx4 v134, s[16:17] offset:2048
	global_load_lds_dwordx4 v135, s[16:17] offset:3072
	s_add_u32 m0, s9, 0x0
	s_nop 0
	global_load_lds_dwordx4 v136, s[14:15]
	global_load_lds_dwordx4 v137, s[14:15] offset:1024
	global_load_lds_dwordx4 v138, s[14:15] offset:2048
	global_load_lds_dwordx4 v139, s[14:15] offset:3072
	s_add_u32 m0, s9, 0x10000
	s_nop 0
	global_load_lds_dwordx4 v140, s[16:17]
	global_load_lds_dwordx4 v141, s[16:17] offset:1024
	global_load_lds_dwordx4 v142, s[16:17] offset:2048
	global_load_lds_dwordx4 v143, s[16:17] offset:3072

; template <class AL, class BL>
; DEV void gemm_ktile(Acc& acc, const char* A, const char* B, int wm, int wn, int lr, int lh, const AL& al, const BL& bl,
;                     int tid, int m0, int n0, int knext, char* nxt, R4& ra, R4& rb) {
;     ...
;   for (int ks = 0; ks < 4; ++ks) {
;     const int cur = ks & 1, nx = cur ^ 1;
;     if (ks < 3) {
; #pragma unroll
;       for (int i = 0; i < 4; ++i) a[nx][i] = *(const bf16x8*)(pa + 32 * i * LDSROW + (ks + 1) * 32);
; #pragma unroll
;       for (int j = 0; j < 2; ++j) b[nx][j] = *(const bf16x8*)(pb + 32 * j * LDSROW + (ks + 1) * 32);
;     }
;     __builtin_amdgcn_sched_barrier(0);
; #pragma unroll
;     for (int i = 0; i < 4; ++i)
; #pragma unroll
;       for (int j = 0; j < 2; ++j)
;         acc[i][j] = __builtin_amdgcn_mfma_f32_32x32x16_bf16(a[cur][i], b[cur][j], acc[i][j], 0, 0, 0);
;     __builtin_amdgcn_sched_barrier(0);
.Lp1b_last:
	ds_read_b128 v[166:169], v146 offset:32768
	ds_read_b128 v[170:173], v146 offset:34816
	ds_read_b128 v[174:177], v146 offset:36864
	ds_read_b128 v[178:181], v146 offset:38912
	ds_read_b128 v[222:225], v144 offset:32768
	ds_read_b128 v[226:229], v144 offset:34816
	ds_read_b128 v[230:233], v144 offset:36864
	ds_read_b128 v[234:237], v144 offset:38912
	ds_read_b128 v[238:241], v144 offset:40960
	ds_read_b128 v[198:201], v144 offset:43008
	ds_read_b128 v[152:155], v144 offset:45056
	ds_read_b128 v[156:159], v144 offset:47104
	ds_read_b128 v[182:185], v147 offset:32768
	ds_read_b128 v[186:189], v147 offset:34816
	ds_read_b128 v[190:193], v147 offset:36864
	ds_read_b128 v[194:197], v147 offset:38912
	s_waitcnt lgkmcnt(8)
	v_mfma_f32_16x16x32_bf16 v[0:3], v[166:169], v[222:225], v[0:3]
	v_mfma_f32_16x16x32_bf16 v[4:7], v[170:173], v[222:225], v[4:7]
	v_mfma_f32_16x16x32_bf16 v[8:11], v[174:177], v[222:225], v[8:11]
	v_mfma_f32_16x16x32_bf16 v[12:15], v[178:181], v[222:225], v[12:15]
	v_mfma_f32_16x16x32_bf16 v[16:19], v[166:169], v[226:229], v[16:19]
	v_mfma_f32_16x16x32_bf16 v[20:23], v[170:173], v[226:229], v[20:23]
	v_mfma_f32_16x16x32_bf16 v[24:27], v[174:177], v[226:229], v[24:27]
	v_mfma_f32_16x16x32_bf16 v[28:31], v[178:181], v[226:229], v[28:31]
	v_mfma_f32_16x16x32_bf16 v[32:35], v[166:169], v[230:233], v[32:35]
	v_mfma_f32_16x16x32_bf16 v[36:39], v[170:173], v[230:233], v[36:39]
	v_mfma_f32_16x16x32_bf16 v[40:43], v[174:177], v[230:233], v[40:43]
	v_mfma_f32_16x16x32_bf16 v[44:47], v[178:181], v[230:233], v[44:47]
	v_mfma_f32_16x16x32_bf16 v[48:51], v[166:169], v[234:237], v[48:51]
	v_mfma_f32_16x16x32_bf16 v[52:55], v[170:173], v[234:237], v[52:55]
	v_mfma_f32_16x16x32_bf16 v[56:59], v[174:177], v[234:237], v[56:59]
	v_mfma_f32_16x16x32_bf16 v[60:63], v[178:181], v[234:237], v[60:63]
	ds_read_b128 v[222:225], v145 offset:32768
	ds_read_b128 v[226:229], v145 offset:34816
	ds_read_b128 v[230:233], v145 offset:36864
	ds_read_b128 v[234:237], v145 offset:38912
	s_waitcnt lgkmcnt(8)
	v_mfma_f32_16x16x32_bf16 v[64:67], v[166:169], v[238:241], v[64:67]
	v_mfma_f32_16x16x32_bf16 v[68:71], v[170:173], v[238:241], v[68:71]
	v_mfma_f32_16x16x32_bf16 v[72:75], v[174:177], v[238:241], v[72:75]
	v_mfma_f32_16x16x32_bf16 v[76:79], v[178:181], v[238:241], v[76:79]
	v_mfma_f32_16x16x32_bf16 v[80:83], v[166:169], v[198:201], v[80:83]
	v_mfma_f32_16x16x32_bf16 v[84:87], v[170:173], v[198:201], v[84:87]
	v_mfma_f32_16x16x32_bf16 v[88:91], v[174:177], v[198:201], v[88:91]
	v_mfma_f32_16x16x32_bf16 v[92:95], v[178:181], v[198:201], v[92:95]
	v_mfma_f32_16x16x32_bf16 v[96:99], v[166:169], v[152:155], v[96:99]
	v_mfma_f32_16x16x32_bf16 v[100:103], v[170:173], v[152:155], v[100:103]
	v_mfma_f32_16x16x32_bf16 v[104:107], v[174:177], v[152:155], v[104:107]
	v_mfma_f32_16x16x32_bf16 v[108:111], v[178:181], v[152:155], v[108:111]
	v_mfma_f32_16x16x32_bf16 v[112:115], v[166:169], v[156:159], v[112:115]
	v_mfma_f32_16x16x32_bf16 v[116:119], v[170:173], v[156:159], v[116:119]
	v_mfma_f32_16x16x32_bf16 v[120:123], v[174:177], v[156:159], v[120:123]
	v_mfma_f32_16x16x32_bf16 v[124:127], v[178:181], v[156:159], v[124:127]
	ds_read_b128 v[238:241], v145 offset:40960
	ds_read_b128 v[198:201], v145 offset:43008
	ds_read_b128 v[152:155], v145 offset:45056
	ds_read_b128 v[156:159], v145 offset:47104
	s_waitcnt lgkmcnt(4)
	v_mfma_f32_16x16x32_bf16 v[0:3], v[182:185], v[222:225], v[0:3]
	v_mfma_f32_16x16x32_bf16 v[4:7], v[186:189], v[222:225], v[4:7]
	v_mfma_f32_16x16x32_bf16 v[8:11], v[190:193], v[222:225], v[8:11]
	v_mfma_f32_16x16x32_bf16 v[12:15], v[194:197], v[222:225], v[12:15]
	v_mfma_f32_16x16x32_bf16 v[16:19], v[182:185], v[226:229], v[16:19]
	v_mfma_f32_16x16x32_bf16 v[20:23], v[186:189], v[226:229], v[20:23]
	v_mfma_f32_16x16x32_bf16 v[24:27], v[190:193], v[226:229], v[24:27]
	v_mfma_f32_16x16x32_bf16 v[28:31], v[194:197], v[226:229], v[28:31]
	v_mfma_f32_16x16x32_bf16 v[32:35], v[182:185], v[230:233], v[32:35]
	v_mfma_f32_16x16x32_bf16 v[36:39], v[186:189], v[230:233], v[36:39]
	v_mfma_f32_16x16x32_bf16 v[40:43], v[190:193], v[230:233], v[40:43]
	v_mfma_f32_16x16x32_bf16 v[44:47], v[194:197], v[230:233], v[44:47]
	v_mfma_f32_16x16x32_bf16 v[48:51], v[182:185], v[234:237], v[48:51]
	v_mfma_f32_16x16x32_bf16 v[52:55], v[186:189], v[234:237], v[52:55]
	v_mfma_f32_16x16x32_bf16 v[56:59], v[190:193], v[234:237], v[56:59]
	v_mfma_f32_16x16x32_bf16 v[60:63], v[194:197], v[234:237], v[60:63]
	s_waitcnt lgkmcnt(0)
	v_mfma_f32_16x16x32_bf16 v[64:67], v[182:185], v[238:241], v[64:67]
	v_mfma_f32_16x16x32_bf16 v[68:71], v[186:189], v[238:241], v[68:71]
	v_mfma_f32_16x16x32_bf16 v[72:75], v[190:193], v[238:241], v[72:75]
	v_mfma_f32_16x16x32_bf16 v[76:79], v[194:197], v[238:241], v[76:79]
	v_mfma_f32_16x16x32_bf16 v[80:83], v[182:185], v[198:201], v[80:83]
	v_mfma_f32_16x16x32_bf16 v[84:87], v[186:189], v[198:201], v[84:87]
	v_mfma_f32_16x16x32_bf16 v[88:91], v[190:193], v[198:201], v[88:91]
	v_mfma_f32_16x16x32_bf16 v[92:95], v[194:197], v[198:201], v[92:95]
	v_mfma_f32_16x16x32_bf16 v[96:99], v[182:185], v[152:155], v[96:99]
	v_mfma_f32_16x16x32_bf16 v[100:103], v[186:189], v[152:155], v[100:103]
	v_mfma_f32_16x16x32_bf16 v[104:107], v[190:193], v[152:155], v[104:107]
	v_mfma_f32_16x16x32_bf16 v[108:111], v[194:197], v[152:155], v[108:111]
	v_mfma_f32_16x16x32_bf16 v[112:115], v[182:185], v[156:159], v[112:115]
	v_mfma_f32_16x16x32_bf16 v[116:119], v[186:189], v[156:159], v[116:119]
	v_mfma_f32_16x16x32_bf16 v[120:123], v[190:193], v[156:159], v[120:123]
	v_mfma_f32_16x16x32_bf16 v[124:127], v[194:197], v[156:159], v[124:127]
	s_barrier
; template <class AL, class BL>
; DEV void gemm_mainloop_p(Acc& acc, const AL& al, const BL& bl, int m0, int n0, int m0n, int n0n, int K, char* lds,
;                          GemmPipe& gp) {
;     ...
;   if (!gp.primed) {
;     gp.ra = al.load(tid, m0, 0);
;     gp.rb = bl.load(tid, n0, 0);
;     __syncthreads();
;     al.store(tid, lds, gp.ra);
;     bl.store(tid, lds + TILE_BYTES, gp.rb);
;     gp.ra = al.load(tid, m0, BK);
;     gp.rb = bl.load(tid, n0, BK);
;     __syncthreads();
;   }
;   for (int kt = 0; kt < nk; ++kt) {
;     const char* cur = lds + (kt & 1) * 2 * TILE_BYTES;
;     char* nxt = lds + ((kt + 1) & 1) * 2 * TILE_BYTES;
;     const bool wrap = (kt + 2 >= nk);
;     const int kk = (wrap ? kt + 2 - nk : kt + 2) * BK;
;     const int mr = wrap ? m0n : m0, nr = wrap ? n0n : n0;
;     __builtin_amdgcn_sched_barrier(0);
;     gemm_ktile(acc, cur, cur + TILE_BYTES, wm, wn, lr, lh, al, bl, tid, mr, nr, kk, nxt, gp.ra, gp.rb);
	s_and_b64 vcc, exec, s[0:1]
	s_cbranch_vccz .Lp1b_nomore
	s_lshl_b32 s4, s12, 8
	s_lshl_b32 s5, s13, 8
	v_add_u32_e32 v128, s4, v150
	v_lshlrev_b32_e32 v128, 11, v128
	v_add_u32_e32 v128, v128, v151
	v_add_u32_e32 v129, 0x3c00, v128
	v_add_u32_e32 v130, 0x7800, v128
	v_add_u32_e32 v131, 0xb400, v128
	v_xor_b32_e32 v129, 0x40, v129
	v_xor_b32_e32 v131, 0x40, v131
	v_add_u32_e32 v132, s5, v150
	v_lshlrev_b32_e32 v132, 11, v132
	v_add_u32_e32 v132, v132, v151
	v_add_u32_e32 v133, 0x3c00, v132
	v_add_u32_e32 v134, 0x7800, v132
	v_add_u32_e32 v135, 0xb400, v132
	v_xor_b32_e32 v133, 0x40, v133
	v_xor_b32_e32 v135, 0x40, v135
	v_add_u32_e32 v136, 0x40000, v128
	v_add_u32_e32 v137, 0x40000, v129
	v_add_u32_e32 v138, 0x40000, v130
	v_add_u32_e32 v139, 0x40000, v131
	v_add_u32_e32 v140, 0x40000, v132
	v_add_u32_e32 v141, 0x40000, v133
	v_add_u32_e32 v142, 0x40000, v134
	v_add_u32_e32 v143, 0x40000, v135
	s_mov_b64 s[14:15], s[88:89]
	s_mov_b64 s[16:17], s[64:65]
	s_cmp_ge_u32 s9, 0x4000
	s_cbranch_scc0 .Lp1b_d4
	s_add_u32 m0, s9, 0xffffc000
	s_nop 0
	global_load_lds_dwordx4 v128, s[14:15]
	global_load_lds_dwordx4 v129, s[14:15] offset:1024
	global_load_lds_dwordx4 v130, s[14:15] offset:2048
	global_load_lds_dwordx4 v131, s[14:15] offset:3072
	s_add_u32 m0, s9, 0xc000
	s_nop 0
	global_load_lds_dwordx4 v132, s[16:17]
	global_load_lds_dwordx4 v133, s[16:17] offset:1024
	global_load_lds_dwordx4 v134, s[16:17] offset:2048
	global_load_lds_dwordx4 v135, s[16:17] offset:3072
	s_add_u32 m0, s9, 0x0
	s_nop 0
	global_load_lds_dwordx4 v136, s[14:15]
	global_load_lds_dwordx4 v137, s[14:15] offset:1024
	global_load_lds_dwordx4 v138, s[14:15] offset:2048
	global_load_lds_dwordx4 v139, s[14:15] offset:3072
	s_add_u32 m0, s9, 0x10000
	s_nop 0
	global_load_lds_dwordx4 v140, s[16:17]
	global_load_lds_dwordx4 v141, s[16:17] offset:1024
	global_load_lds_dwordx4 v142, s[16:17] offset:2048
	global_load_lds_dwordx4 v143, s[16:17] offset:3072

; DEV int tidx() { return tidx_full() & 255; }
; DEV void norm_adaln_rows(const float* __restrict__ X, const float* __restrict__ gvec, const float* __restrict__ mod,
;                          int bg0, int L, int sh_off, int sc_off, u16* __restrict__ H, int rbeg) {
;   const int tid = tidx();
;   const int wave = tid >> 6, lane = tid & 63;
;   for (int jb = 0; jb < 16; jb += 4) {
;     float4 v[4][4];
;     float ss[4];
; #pragma unroll
;     for (int j = 0; j < 4; ++j) {
;       const float* x = X + (long)(rbeg + wave + 4 * (jb + j)) * D;
; #pragma unroll
;       for (int i = 0; i < 4; ++i) v[j][i] = *(const float4*)(x + lane * 4 + 256 * i);
;     }
; #pragma unroll
;     for (int j = 0; j < 4; ++j) {
;       float t = 0.f;
; #pragma unroll
;       for (int i = 0; i < 4; ++i) t += v[j][i].x * v[j][i].x + v[j][i].y * v[j][i].y + v[j][i].z * v[j][i].z + v[j][i].w * v[j][i].w;
;       ss[j] = wave_sum(t);
;     }
; #pragma unroll
;     for (int j = 0; j < 4; ++j) {
;       const int row = rbeg + wave + 4 * (jb + j);
;       const float rstd = rsqrtf(ss[j] * (1.f / 1024.f) + EPSF);
;       const float* mrow = mod + (long)(bg0 + row / L) * DIN;
; #pragma unroll
;       for (int i = 0; i < 4; ++i) {
;         const int k = lane * 4 + 256 * i;
;         const float4 g = *(const float4*)(gvec + k);
;         const float4 sc = *(const float4*)(mrow + sc_off + k);
;         const float4 sh = *(const float4*)(mrow + sh_off + k);
;         const float o0 = v[j][i].x * rstd * g.x * (1.f + sc.x) + sh.x;
;         const float o1 = v[j][i].y * rstd * g.y * (1.f + sc.y) + sh.y;
;         const float o2 = v[j][i].z * rstd * g.z * (1.f + sc.z) + sh.z;
;         const float o3 = v[j][i].w * rstd * g.w * (1.f + sc.w) + sh.w;
;         *(uint2*)(H + (long)row * D + k) = make_uint2(pack2(o0, o1), pack2(o2, o3));
;       }
;     }
;   }
; }
.LBB0_818:
	s_and_b64 vcc, exec, s[0:1]
	s_mov_b64 s[0:1], 0x1000
	s_mov_b32 s36, 0x3a800000
	s_mov_b32 s38, 0x358637bd
	s_cbranch_vccz .LBB0_807
	v_readfirstlane_b32 s12, v202
	v_readlane_b32 s14, v249, 12
	v_readlane_b32 s15, v249, 13
	v_readlane_b32 s16, v249, 2
	v_readlane_b32 s17, v249, 3
	s_bfe_u32 s12, s12, 0x20006
	s_add_u32 s12, s12, s4
	v_mov_b32_e32 v118, 0x358637bd
	v_and_b32_e32 v115, 63, v202
	v_lshlrev_b32_e32 v116, 3, v115
	v_lshlrev_b32_e32 v115, 4, v115
	global_load_dwordx4 v[96:99], v115, s[14:15]
	global_load_dwordx4 v[100:103], v115, s[14:15] offset:1024
	global_load_dwordx4 v[104:107], v115, s[14:15] offset:2048
	global_load_dwordx4 v[108:111], v115, s[14:15] offset:3072
	s_lshl_b32 s13, s12, 11
	s_add_u32 s10, s28, s13
	s_addc_u32 s11, s29, 0
	s_lshl_b32 s13, s12, 12
	s_add_u32 s0, s16, s13
	s_addc_u32 s1, s17, 0
	s_lshr_b32 s13, s12, 13
	s_add_u32 s13, s13, 8
	s_mul_i32 s13, s13, 0x6000
	s_add_u32 s18, s86, s13
	s_addc_u32 s19, s87, 0
	s_add_u32 s6, s18, 0x1000
	s_addc_u32 s7, s19, 0
	s_add_u32 s8, s18, 0x0
	s_addc_u32 s9, s19, 0
	global_load_dwordx4 v[0:3], v115, s[0:1]
	global_load_dwordx4 v[4:7], v115, s[0:1] offset:1024
	global_load_dwordx4 v[8:11], v115, s[0:1] offset:2048
	global_load_dwordx4 v[12:15], v115, s[0:1] offset:3072
	global_load_dwordx4 v[32:35], v115, s[6:7]
	global_load_dwordx4 v[36:39], v115, s[6:7] offset:1024
	global_load_dwordx4 v[40:43], v115, s[6:7] offset:2048
	global_load_dwordx4 v[44:47], v115, s[6:7] offset:3072
	global_load_dwordx4 v[48:51], v115, s[8:9]
	global_load_dwordx4 v[52:55], v115, s[8:9] offset:1024
	global_load_dwordx4 v[56:59], v115, s[8:9] offset:2048
	global_load_dwordx4 v[60:63], v115, s[8:9] offset:3072
	s_add_u32 s12, s12, 0x4
	s_lshl_b32 s13, s12, 12
	s_add_u32 s0, s16, s13
	s_addc_u32 s1, s17, 0
	s_lshr_b32 s13, s12, 13
	s_add_u32 s13, s13, 8
	s_mul_i32 s13, s13, 0x6000
	s_add_u32 s18, s86, s13
	s_addc_u32 s19, s87, 0
	s_add_u32 s6, s18, 0x1000
	s_addc_u32 s7, s19, 0
	s_add_u32 s8, s18, 0x0
	s_addc_u32 s9, s19, 0
	global_load_dwordx4 v[16:19], v115, s[0:1]
	global_load_dwordx4 v[20:23], v115, s[0:1] offset:1024
	global_load_dwordx4 v[24:27], v115, s[0:1] offset:2048
	global_load_dwordx4 v[28:31], v115, s[0:1] offset:3072
	global_load_dwordx4 v[64:67], v115, s[6:7]
	global_load_dwordx4 v[68:71], v115, s[6:7] offset:1024
	global_load_dwordx4 v[72:75], v115, s[6:7] offset:2048
	global_load_dwordx4 v[76:79], v115, s[6:7] offset:3072
	global_load_dwordx4 v[80:83], v115, s[8:9]
	global_load_dwordx4 v[84:87], v115, s[8:9] offset:1024
	global_load_dwordx4 v[88:91], v115, s[8:9] offset:2048
	global_load_dwordx4 v[92:95], v115, s[8:9] offset:3072
	s_add_u32 s12, s12, 0x4
	s_mov_b32 s20, 0
.Lnfill_loop:
	s_waitcnt vmcnt(12)
	v_mul_f32_e32 v112, v0, v0
	v_fmac_f32_e32 v112, v1, v1
	v_fmac_f32_e32 v112, v2, v2
	v_fmac_f32_e32 v112, v3, v3
	v_fmac_f32_e32 v112, v4, v4
	v_fmac_f32_e32 v112, v5, v5
	v_fmac_f32_e32 v112, v6, v6
	v_fmac_f32_e32 v112, v7, v7
	v_fmac_f32_e32 v112, v8, v8
	v_fmac_f32_e32 v112, v9, v9
	v_fmac_f32_e32 v112, v10, v10
	v_fmac_f32_e32 v112, v11, v11
	v_fmac_f32_e32 v112, v12, v12
	v_fmac_f32_e32 v112, v13, v13
	v_fmac_f32_e32 v112, v14, v14
	v_fmac_f32_e32 v112, v15, v15
	s_nop 1
	v_add_f32_dpp v112, v112, v112 quad_perm:[1,0,3,2] row_mask:0xf bank_mask:0xf
	s_nop 1
	v_add_f32_dpp v112, v112, v112 quad_perm:[2,3,0,1] row_mask:0xf bank_mask:0xf
	s_nop 1
	v_add_f32_dpp v112, v112, v112 row_half_mirror row_mask:0xf bank_mask:0xf
	s_nop 1
	v_add_f32_dpp v112, v112, v112 row_mirror row_mask:0xf bank_mask:0xf
	s_nop 1
	v_add_f32_dpp v112, v112, v112 row_bcast:15 row_mask:0xa bank_mask:0xf
	s_nop 1
	v_add_f32_dpp v112, v112, v112 row_bcast:31 row_mask:0xc bank_mask:0xf
	s_nop 1
	v_readlane_b32 s13, v112, 63
	v_mov_b32_e32 v113, 0x3a800000
	s_nop 1
	v_fma_f32 v117, s13, v113, v118
	v_cmp_gt_f32_e32 vcc, 0x800000, v117
	v_mul_f32_e32 v114, 0x4b800000, v117
	v_cndmask_b32_e32 v117, v117, v114, vcc
	v_rsq_f32_e32 v117, v117
	s_nop 0
	v_mul_f32_e32 v114, 0x45800000, v117
	v_cndmask_b32_e32 v117, v117, v114, vcc
	v_mul_f32_e32 v0, v0, v117
	v_mul_f32_e32 v0, v96, v0
	v_add_f32_e32 v32, 1.0, v32
	v_fma_f32 v0, v0, v32, v48
	v_mul_f32_e32 v1, v1, v117
	v_mul_f32_e32 v1, v97, v1
	v_add_f32_e32 v33, 1.0, v33
	v_fma_f32 v1, v1, v33, v49
	v_mul_f32_e32 v2, v2, v117
	v_mul_f32_e32 v2, v98, v2
	v_add_f32_e32 v34, 1.0, v34
	v_fma_f32 v2, v2, v34, v50
	v_mul_f32_e32 v3, v3, v117
	v_mul_f32_e32 v3, v99, v3
	v_add_f32_e32 v35, 1.0, v35
	v_fma_f32 v3, v3, v35, v51
	v_mul_f32_e32 v4, v4, v117
	v_mul_f32_e32 v4, v100, v4
	v_add_f32_e32 v36, 1.0, v36
	v_fma_f32 v4, v4, v36, v52
	v_mul_f32_e32 v5, v5, v117
	v_mul_f32_e32 v5, v101, v5
	v_add_f32_e32 v37, 1.0, v37
	v_fma_f32 v5, v5, v37, v53
	v_mul_f32_e32 v6, v6, v117
	v_mul_f32_e32 v6, v102, v6
	v_add_f32_e32 v38, 1.0, v38
	v_fma_f32 v6, v6, v38, v54
	v_mul_f32_e32 v7, v7, v117
	v_mul_f32_e32 v7, v103, v7
	v_add_f32_e32 v39, 1.0, v39
	v_fma_f32 v7, v7, v39, v55
	v_mul_f32_e32 v8, v8, v117
	v_mul_f32_e32 v8, v104, v8
	v_add_f32_e32 v40, 1.0, v40
	v_fma_f32 v8, v8, v40, v56
	v_mul_f32_e32 v9, v9, v117
	v_mul_f32_e32 v9, v105, v9
	v_add_f32_e32 v41, 1.0, v41
	v_fma_f32 v9, v9, v41, v57
	v_mul_f32_e32 v10, v10, v117
	v_mul_f32_e32 v10, v106, v10
	v_add_f32_e32 v42, 1.0, v42
	v_fma_f32 v10, v10, v42, v58
	v_mul_f32_e32 v11, v11, v117
	v_mul_f32_e32 v11, v107, v11
	v_add_f32_e32 v43, 1.0, v43
	v_fma_f32 v11, v11, v43, v59
	v_mul_f32_e32 v12, v12, v117
	v_mul_f32_e32 v12, v108, v12
	v_add_f32_e32 v44, 1.0, v44
	v_fma_f32 v12, v12, v44, v60
	v_mul_f32_e32 v13, v13, v117
	v_mul_f32_e32 v13, v109, v13
	v_add_f32_e32 v45, 1.0, v45
	v_fma_f32 v13, v13, v45, v61
	v_mul_f32_e32 v14, v14, v117
	v_mul_f32_e32 v14, v110, v14
	v_add_f32_e32 v46, 1.0, v46
	v_fma_f32 v14, v14, v46, v62
	v_mul_f32_e32 v15, v15, v117
	v_mul_f32_e32 v15, v111, v15
	v_add_f32_e32 v47, 1.0, v47
	v_fma_f32 v15, v15, v47, v63
	v_cvt_pk_bf16_f32 v0, v0, v1
	v_cvt_pk_bf16_f32 v1, v2, v3
	global_store_dwordx2 v116, v[0:1], s[10:11]
	v_cvt_pk_bf16_f32 v4, v4, v5
	v_cvt_pk_bf16_f32 v5, v6, v7
	global_store_dwordx2 v116, v[4:5], s[10:11] offset:512
	v_cvt_pk_bf16_f32 v8, v8, v9
	v_cvt_pk_bf16_f32 v9, v10, v11
	global_store_dwordx2 v116, v[8:9], s[10:11] offset:1024
	v_cvt_pk_bf16_f32 v12, v12, v13
	v_cvt_pk_bf16_f32 v13, v14, v15
	global_store_dwordx2 v116, v[12:13], s[10:11] offset:1536
	s_add_u32 s10, s10, 0x2000
	s_addc_u32 s11, s11, 0
	s_cmp_eq_u32 s20, 7
	s_cbranch_scc1 .Lnfill_tail
; DEV void norm_adaln_rows(const float* __restrict__ X, const float* __restrict__ gvec, const float* __restrict__ mod,
;                          int bg0, int L, int sh_off, int sc_off, u16* __restrict__ H, int rbeg) {
;     ...
;   for (int jb = 0; jb < 16; jb += 4) {
;     float4 v[4][4];
;     float ss[4];
; #pragma unroll
;     for (int j = 0; j < 4; ++j) {
;       const float* x = X + (long)(rbeg + wave + 4 * (jb + j)) * D;
; #pragma unroll
;       for (int i = 0; i < 4; ++i) v[j][i] = *(const float4*)(x + lane * 4 + 256 * i);
;     }
; #pragma unroll
;     for (int j = 0; j < 4; ++j) {
;       float t = 0.f;
; #pragma unroll
;       for (int i = 0; i < 4; ++i) t += v[j][i].x * v[j][i].x + v[j][i].y * v[j][i].y + v[j][i].z * v[j][i].z + v[j][i].w * v[j][i].w;
;       ss[j] = wave_sum(t);
;     }
; #pragma unroll
;     for (int j = 0; j < 4; ++j) {
;       const int row = rbeg + wave + 4 * (jb + j);
;       const float rstd = rsqrtf(ss[j] * (1.f / 1024.f) + EPSF);
;       const float* mrow = mod + (long)(bg0 + row / L) * DIN;
; #pragma unroll
;       for (int i = 0; i < 4; ++i) {
;         const int k = lane * 4 + 256 * i;
;         const float4 g = *(const float4*)(gvec + k);
;         const float4 sc = *(const float4*)(mrow + sc_off + k);
;         const float4 sh = *(const float4*)(mrow + sh_off + k);
;         const float o0 = v[j][i].x * rstd * g.x * (1.f + sc.x) + sh.x;
;         const float o1 = v[j][i].y * rstd * g.y * (1.f + sc.y) + sh.y;
;         const float o2 = v[j][i].z * rstd * g.z * (1.f + sc.z) + sh.z;
;         const float o3 = v[j][i].w * rstd * g.w * (1.f + sc.w) + sh.w;
;         *(uint2*)(H + (long)row * D + k) = make_uint2(pack2(o0, o1), pack2(o2, o3));
;       }
;     }
;   }
; }
	s_lshl_b32 s13, s12, 12
	s_add_u32 s0, s16, s13
	s_addc_u32 s1, s17, 0
	s_lshr_b32 s13, s12, 13
	s_add_u32 s13, s13, 8
	s_mul_i32 s13, s13, 0x6000
	s_add_u32 s18, s86, s13
	s_addc_u32 s19, s87, 0
	s_add_u32 s6, s18, 0x1000
	s_addc_u32 s7, s19, 0
	s_add_u32 s8, s18, 0x0
	s_addc_u32 s9, s19, 0
	global_load_dwordx4 v[0:3], v115, s[0:1]
	global_load_dwordx4 v[4:7], v115, s[0:1] offset:1024
	global_load_dwordx4 v[8:11], v115, s[0:1] offset:2048
	global_load_dwordx4 v[12:15], v115, s[0:1] offset:3072
	global_load_dwordx4 v[32:35], v115, s[6:7]
	global_load_dwordx4 v[36:39], v115, s[6:7] offset:1024
	global_load_dwordx4 v[40:43], v115, s[6:7] offset:2048
	global_load_dwordx4 v[44:47], v115, s[6:7] offset:3072
	global_load_dwordx4 v[48:51], v115, s[8:9]
	global_load_dwordx4 v[52:55], v115, s[8:9] offset:1024
	global_load_dwordx4 v[56:59], v115, s[8:9] offset:2048
	global_load_dwordx4 v[60:63], v115, s[8:9] offset:3072
	s_add_u32 s12, s12, 0x4
	s_waitcnt vmcnt(16)
	v_mul_f32_e32 v112, v16, v16
	v_fmac_f32_e32 v112, v17, v17
	v_fmac_f32_e32 v112, v18, v18
	v_fmac_f32_e32 v112, v19, v19
	v_fmac_f32_e32 v112, v20, v20
	v_fmac_f32_e32 v112, v21, v21
	v_fmac_f32_e32 v112, v22, v22
	v_fmac_f32_e32 v112, v23, v23
	v_fmac_f32_e32 v112, v24, v24
	v_fmac_f32_e32 v112, v25, v25
	v_fmac_f32_e32 v112, v26, v26
	v_fmac_f32_e32 v112, v27, v27
	v_fmac_f32_e32 v112, v28, v28
	v_fmac_f32_e32 v112, v29, v29
	v_fmac_f32_e32 v112, v30, v30
	v_fmac_f32_e32 v112, v31, v31
	s_nop 1
	v_add_f32_dpp v112, v112, v112 quad_perm:[1,0,3,2] row_mask:0xf bank_mask:0xf
	s_nop 1
	v_add_f32_dpp v112, v112, v112 quad_perm:[2,3,0,1] row_mask:0xf bank_mask:0xf
	s_nop 1
	v_add_f32_dpp v112, v112, v112 row_half_mirror row_mask:0xf bank_mask:0xf
	s_nop 1
	v_add_f32_dpp v112, v112, v112 row_mirror row_mask:0xf bank_mask:0xf
	s_nop 1
	v_add_f32_dpp v112, v112, v112 row_bcast:15 row_mask:0xa bank_mask:0xf
	s_nop 1
	v_add_f32_dpp v112, v112, v112 row_bcast:31 row_mask:0xc bank_mask:0xf
	s_nop 1
	v_readlane_b32 s13, v112, 63
	v_mov_b32_e32 v113, 0x3a800000
	s_nop 1
	v_fma_f32 v117, s13, v113, v118
	v_cmp_gt_f32_e32 vcc, 0x800000, v117
	v_mul_f32_e32 v114, 0x4b800000, v117
	v_cndmask_b32_e32 v117, v117, v114, vcc
	v_rsq_f32_e32 v117, v117
	s_nop 0
	v_mul_f32_e32 v114, 0x45800000, v117
	v_cndmask_b32_e32 v117, v117, v114, vcc
	v_mul_f32_e32 v16, v16, v117
	v_mul_f32_e32 v16, v96, v16
	v_add_f32_e32 v64, 1.0, v64
	v_fma_f32 v16, v16, v64, v80
	v_mul_f32_e32 v17, v17, v117
	v_mul_f32_e32 v17, v97, v17
	v_add_f32_e32 v65, 1.0, v65
	v_fma_f32 v17, v17, v65, v81
	v_mul_f32_e32 v18, v18, v117
	v_mul_f32_e32 v18, v98, v18
	v_add_f32_e32 v66, 1.0, v66
	v_fma_f32 v18, v18, v66, v82
	v_mul_f32_e32 v19, v19, v117
	v_mul_f32_e32 v19, v99, v19
	v_add_f32_e32 v67, 1.0, v67
	v_fma_f32 v19, v19, v67, v83
	v_mul_f32_e32 v20, v20, v117
	v_mul_f32_e32 v20, v100, v20
	v_add_f32_e32 v68, 1.0, v68
	v_fma_f32 v20, v20, v68, v84
	v_mul_f32_e32 v21, v21, v117
	v_mul_f32_e32 v21, v101, v21
	v_add_f32_e32 v69, 1.0, v69
	v_fma_f32 v21, v21, v69, v85
	v_mul_f32_e32 v22, v22, v117
	v_mul_f32_e32 v22, v102, v22
	v_add_f32_e32 v70, 1.0, v70
	v_fma_f32 v22, v22, v70, v86
	v_mul_f32_e32 v23, v23, v117
	v_mul_f32_e32 v23, v103, v23
	v_add_f32_e32 v71, 1.0, v71
	v_fma_f32 v23, v23, v71, v87
	v_mul_f32_e32 v24, v24, v117
	v_mul_f32_e32 v24, v104, v24
	v_add_f32_e32 v72, 1.0, v72
	v_fma_f32 v24, v24, v72, v88
	v_mul_f32_e32 v25, v25, v117
	v_mul_f32_e32 v25, v105, v25
	v_add_f32_e32 v73, 1.0, v73
	v_fma_f32 v25, v25, v73, v89
	v_mul_f32_e32 v26, v26, v117
	v_mul_f32_e32 v26, v106, v26
	v_add_f32_e32 v74, 1.0, v74
	v_fma_f32 v26, v26, v74, v90
	v_mul_f32_e32 v27, v27, v117
	v_mul_f32_e32 v27, v107, v27
	v_add_f32_e32 v75, 1.0, v75
	v_fma_f32 v27, v27, v75, v91
	v_mul_f32_e32 v28, v28, v117
	v_mul_f32_e32 v28, v108, v28
	v_add_f32_e32 v76, 1.0, v76
	v_fma_f32 v28, v28, v76, v92
	v_mul_f32_e32 v29, v29, v117
	v_mul_f32_e32 v29, v109, v29
	v_add_f32_e32 v77, 1.0, v77
	v_fma_f32 v29, v29, v77, v93
	v_mul_f32_e32 v30, v30, v117
	v_mul_f32_e32 v30, v110, v30
	v_add_f32_e32 v78, 1.0, v78
	v_fma_f32 v30, v30, v78, v94
	v_mul_f32_e32 v31, v31, v117
	v_mul_f32_e32 v31, v111, v31
	v_add_f32_e32 v79, 1.0, v79
	v_fma_f32 v31, v31, v79, v95
	v_cvt_pk_bf16_f32 v16, v16, v17
	v_cvt_pk_bf16_f32 v17, v18, v19
	global_store_dwordx2 v116, v[16:17], s[10:11]
	v_cvt_pk_bf16_f32 v20, v20, v21
	v_cvt_pk_bf16_f32 v21, v22, v23
	global_store_dwordx2 v116, v[20:21], s[10:11] offset:512
	v_cvt_pk_bf16_f32 v24, v24, v25
	v_cvt_pk_bf16_f32 v25, v26, v27
	global_store_dwordx2 v116, v[24:25], s[10:11] offset:1024
	v_cvt_pk_bf16_f32 v28, v28, v29
	v_cvt_pk_bf16_f32 v29, v30, v31
	global_store_dwordx2 v116, v[28:29], s[10:11] offset:1536
	s_add_u32 s10, s10, 0x2000
	s_addc_u32 s11, s11, 0
	s_lshl_b32 s13, s12, 12
	s_add_u32 s0, s16, s13
	s_addc_u32 s1, s17, 0
	s_lshr_b32 s13, s12, 13
	s_add_u32 s13, s13, 8
	s_mul_i32 s13, s13, 0x6000
	s_add_u32 s18, s86, s13
	s_addc_u32 s19, s87, 0
	s_add_u32 s6, s18, 0x1000
	s_addc_u32 s7, s19, 0
	s_add_u32 s8, s18, 0x0
	s_addc_u32 s9, s19, 0
	global_load_dwordx4 v[16:19], v115, s[0:1]
	global_load_dwordx4 v[20:23], v115, s[0:1] offset:1024
	global_load_dwordx4 v[24:27], v115, s[0:1] offset:2048
	global_load_dwordx4 v[28:31], v115, s[0:1] offset:3072
	global_load_dwordx4 v[64:67], v115, s[6:7]
	global_load_dwordx4 v[68:71], v115, s[6:7] offset:1024
	global_load_dwordx4 v[72:75], v115, s[6:7] offset:2048
	global_load_dwordx4 v[76:79], v115, s[6:7] offset:3072
	global_load_dwordx4 v[80:83], v115, s[8:9]
	global_load_dwordx4 v[84:87], v115, s[8:9] offset:1024
	global_load_dwordx4 v[88:91], v115, s[8:9] offset:2048
	global_load_dwordx4 v[92:95], v115, s[8:9] offset:3072
	s_add_u32 s12, s12, 0x4
	s_add_u32 s20, s20, 1
	s_branch .Lnfill_loop
; DEV void norm_adaln_rows(const float* __restrict__ X, const float* __restrict__ gvec, const float* __restrict__ mod,
;                          int bg0, int L, int sh_off, int sc_off, u16* __restrict__ H, int rbeg) {
;     ...
;     for (int j = 0; j < 4; ++j) {
;       const int row = rbeg + wave + 4 * (jb + j);
;       const float rstd = rsqrtf(ss[j] * (1.f / 1024.f) + EPSF);
;       const float* mrow = mod + (long)(bg0 + row / L) * DIN;
; #pragma unroll
;       for (int i = 0; i < 4; ++i) {
;         const int k = lane * 4 + 256 * i;
;         const float4 g = *(const float4*)(gvec + k);
;         const float4 sc = *(const float4*)(mrow + sc_off + k);
;         const float4 sh = *(const float4*)(mrow + sh_off + k);
;         const float o0 = v[j][i].x * rstd * g.x * (1.f + sc.x) + sh.x;
;         const float o1 = v[j][i].y * rstd * g.y * (1.f + sc.y) + sh.y;
;         const float o2 = v[j][i].z * rstd * g.z * (1.f + sc.z) + sh.z;
;         const float o3 = v[j][i].w * rstd * g.w * (1.f + sc.w) + sh.w;
;         *(uint2*)(H + (long)row * D + k) = make_uint2(pack2(o0, o1), pack2(o2, o3));
;       }
;     }
.Lnfill_tail:
	s_waitcnt vmcnt(4)
	v_mul_f32_e32 v112, v16, v16
	v_fmac_f32_e32 v112, v17, v17
	v_fmac_f32_e32 v112, v18, v18
	v_fmac_f32_e32 v112, v19, v19
	v_fmac_f32_e32 v112, v20, v20
	v_fmac_f32_e32 v112, v21, v21
	v_fmac_f32_e32 v112, v22, v22
	v_fmac_f32_e32 v112, v23, v23
	v_fmac_f32_e32 v112, v24, v24
	v_fmac_f32_e32 v112, v25, v25
	v_fmac_f32_e32 v112, v26, v26
	v_fmac_f32_e32 v112, v27, v27
	v_fmac_f32_e32 v112, v28, v28
	v_fmac_f32_e32 v112, v29, v29
	v_fmac_f32_e32 v112, v30, v30
	v_fmac_f32_e32 v112, v31, v31
	s_nop 1
	v_add_f32_dpp v112, v112, v112 quad_perm:[1,0,3,2] row_mask:0xf bank_mask:0xf
	s_nop 1
	v_add_f32_dpp v112, v112, v112 quad_perm:[2,3,0,1] row_mask:0xf bank_mask:0xf
	s_nop 1
	v_add_f32_dpp v112, v112, v112 row_half_mirror row_mask:0xf bank_mask:0xf
	s_nop 1
	v_add_f32_dpp v112, v112, v112 row_mirror row_mask:0xf bank_mask:0xf
	s_nop 1
	v_add_f32_dpp v112, v112, v112 row_bcast:15 row_mask:0xa bank_mask:0xf
	s_nop 1
	v_add_f32_dpp v112, v112, v112 row_bcast:31 row_mask:0xc bank_mask:0xf
	s_nop 1
	v_readlane_b32 s13, v112, 63
	v_mov_b32_e32 v113, 0x3a800000
	s_nop 1
	v_fma_f32 v117, s13, v113, v118
	v_cmp_gt_f32_e32 vcc, 0x800000, v117
	v_mul_f32_e32 v114, 0x4b800000, v117
	v_cndmask_b32_e32 v117, v117, v114, vcc
	v_rsq_f32_e32 v117, v117
	s_nop 0
	v_mul_f32_e32 v114, 0x45800000, v117
	v_cndmask_b32_e32 v117, v117, v114, vcc
	v_mul_f32_e32 v16, v16, v117
	v_mul_f32_e32 v16, v96, v16
	v_add_f32_e32 v64, 1.0, v64
	v_fma_f32 v16, v16, v64, v80
	v_mul_f32_e32 v17, v17, v117
	v_mul_f32_e32 v17, v97, v17
	v_add_f32_e32 v65, 1.0, v65
	v_fma_f32 v17, v17, v65, v81
	v_mul_f32_e32 v18, v18, v117
	v_mul_f32_e32 v18, v98, v18
	v_add_f32_e32 v66, 1.0, v66
	v_fma_f32 v18, v18, v66, v82
	v_mul_f32_e32 v19, v19, v117
	v_mul_f32_e32 v19, v99, v19
	v_add_f32_e32 v67, 1.0, v67
	v_fma_f32 v19, v19, v67, v83
	v_mul_f32_e32 v20, v20, v117
	v_mul_f32_e32 v20, v100, v20
	v_add_f32_e32 v68, 1.0, v68
	v_fma_f32 v20, v20, v68, v84
	v_mul_f32_e32 v21, v21, v117
	v_mul_f32_e32 v21, v101, v21
	v_add_f32_e32 v69, 1.0, v69
	v_fma_f32 v21, v21, v69, v85
	v_mul_f32_e32 v22, v22, v117
	v_mul_f32_e32 v22, v102, v22
	v_add_f32_e32 v70, 1.0, v70
	v_fma_f32 v22, v22, v70, v86
	v_mul_f32_e32 v23, v23, v117
	v_mul_f32_e32 v23, v103, v23
	v_add_f32_e32 v71, 1.0, v71
	v_fma_f32 v23, v23, v71, v87
	v_mul_f32_e32 v24, v24, v117
	v_mul_f32_e32 v24, v104, v24
	v_add_f32_e32 v72, 1.0, v72
	v_fma_f32 v24, v24, v72, v88
	v_mul_f32_e32 v25, v25, v117
	v_mul_f32_e32 v25, v105, v25
	v_add_f32_e32 v73, 1.0, v73
	v_fma_f32 v25, v25, v73, v89
	v_mul_f32_e32 v26, v26, v117
	v_mul_f32_e32 v26, v106, v26
	v_add_f32_e32 v74, 1.0, v74
	v_fma_f32 v26, v26, v74, v90
	v_mul_f32_e32 v27, v27, v117
	v_mul_f32_e32 v27, v107, v27
	v_add_f32_e32 v75, 1.0, v75
	v_fma_f32 v27, v27, v75, v91
	v_mul_f32_e32 v28, v28, v117
	v_mul_f32_e32 v28, v108, v28
	v_add_f32_e32 v76, 1.0, v76
	v_fma_f32 v28, v28, v76, v92
	v_mul_f32_e32 v29, v29, v117
	v_mul_f32_e32 v29, v109, v29
	v_add_f32_e32 v77, 1.0, v77
	v_fma_f32 v29, v29, v77, v93
	v_mul_f32_e32 v30, v30, v117
	v_mul_f32_e32 v30, v110, v30
	v_add_f32_e32 v78, 1.0, v78
	v_fma_f32 v30, v30, v78, v94
	v_mul_f32_e32 v31, v31, v117
	v_mul_f32_e32 v31, v111, v31
	v_add_f32_e32 v79, 1.0, v79
	v_fma_f32 v31, v31, v79, v95
	v_cvt_pk_bf16_f32 v16, v16, v17
	v_cvt_pk_bf16_f32 v17, v18, v19
	global_store_dwordx2 v116, v[16:17], s[10:11]
	v_cvt_pk_bf16_f32 v20, v20, v21
	v_cvt_pk_bf16_f32 v21, v22, v23
	global_store_dwordx2 v116, v[20:21], s[10:11] offset:512
	v_cvt_pk_bf16_f32 v24, v24, v25
	v_cvt_pk_bf16_f32 v25, v26, v27
	global_store_dwordx2 v116, v[24:25], s[10:11] offset:1024
	v_cvt_pk_bf16_f32 v28, v28, v29
	v_cvt_pk_bf16_f32 v29, v30, v31
	global_store_dwordx2 v116, v[28:29], s[10:11] offset:1536
	s_add_u32 s10, s10, 0x2000
	s_addc_u32 s11, s11, 0
	s_waitcnt vmcnt(0)
	s_branch .LBB0_807

; template <class AL, class BL>
; DEV void gemm_mainloop(Acc& acc, const AL& al, const BL& bl, int m0, int n0, int kbeg, int kend, char* lds) {
;   const int tid = tidx_full();
;   const int wave = tid >> 6, lane = tid & 63;
;   const int wm = (wave >> 2) * 128, wn = (wave & 3) * 64;
;   const int lr = lane & 31, lh = lane >> 5;
;   const int nk = (kend - kbeg) / BK;
;   R4 a0 = al.load(tid, m0, kbeg);
;   R4 b0 = bl.load(tid, n0, kbeg);
;   __syncthreads();
;   al.store(tid, lds, a0);
;   bl.store(tid, lds + TILE_BYTES, b0);
;   a0 = al.load(tid, m0, kbeg + BK);
;   b0 = bl.load(tid, n0, kbeg + BK);
;   __syncthreads();
.LBB0_937:
	s_lshl_b32 s3, s5, 8
	s_lshl_b32 s2, s6, 8
	v_readlane_b32 s11, v252, 18
	v_readlane_b32 s6, v251, 16
	v_readlane_b32 s7, v251, 17
	v_readlane_b32 s12, v249, 48
	v_readlane_b32 s13, v249, 49
	s_lshr_b32 s0, s3, s11
	s_lshl_b32 s1, s0, s11
	s_sub_u32 s1, s3, s1
	s_mulk_i32 s0, 0x600
	s_addk_i32 s0, 0x400
	s_add_u32 s11, s11, 1
	s_lshl_b32 s0, s0, s11
	s_lshl_b32 s1, s1, 1
	s_add_u32 s0, s0, s1
	s_add_u32 s0, s74, s0
	s_addc_u32 s1, s75, 0
	s_lshl_b32 s10, 64, s11
	v_lshrrev_b32_e32 v149, 6, v202
	v_and_b32_e32 v148, 63, v202
	s_nop 0
	v_readfirstlane_b32 s5, v149
	v_lshrrev_b32_e32 v150, 3, v148
	v_and_b32_e32 v151, 3, v149
	v_lshl_add_u32 v150, v151, 5, v150
	v_and_b32_e32 v151, 7, v148
	v_lshrrev_b32_e32 v128, 4, v148
	v_xor_b32_e32 v151, v128, v151
	v_lshlrev_b32_e32 v151, 4, v151
	s_and_b32 s9, s5, 3
	s_mul_i32 s9, s9, 0x2300
	s_lshl_b32 s5, s5, 12
	v_add_u32_e32 v132, s2, v150
	v_lshlrev_b32_e32 v132, 11, v132
	v_add_u32_e32 v132, v132, v151
	v_add_u32_e32 v133, 0x3c00, v132
	v_add_u32_e32 v134, 0x7800, v132
	v_add_u32_e32 v135, 0xb400, v132
	v_xor_b32_e32 v133, 0x40, v133
	v_xor_b32_e32 v135, 0x40, v135
	v_add_u32_e32 v140, 0x40000, v132
	v_add_u32_e32 v141, 0x40000, v133
	v_add_u32_e32 v142, 0x40000, v134
	v_add_u32_e32 v143, 0x40000, v135
	v_lshrrev_b32_e32 v164, 5, v148
	v_bfe_u32 v242, v148, 1, 4
	v_xor_b32_e32 v242, v242, v164
	v_lshlrev_b32_e32 v242, 1, v242
	v_and_b32_e32 v128, 1, v148
	v_or_b32_e32 v242, v242, v128
	v_lshlrev_b32_e32 v242, 4, v242
	v_and_b32_e32 v129, 3, v149
	v_lshl_add_u32 v164, v129, 4, v164
	v_lshlrev_b32_e32 v164, s11, v164
	v_add_u32_e32 v128, v164, v242
	s_lshl_b32 s8, 2, s11
	v_add_u32_e32 v129, s8, v128
	v_add_u32_e32 v130, s8, v129
	v_add_u32_e32 v131, s8, v130
	v_add_u32_e32 v136, s8, v131
	v_add_u32_e32 v137, s8, v136
	v_add_u32_e32 v138, s8, v137
	v_add_u32_e32 v139, s8, v138
	v_add_u32_e32 v129, 0xfffffbc0, v129
	v_add_u32_e32 v130, 0xfffff780, v130
	v_add_u32_e32 v131, 0xfffff340, v131
	v_add_u32_e32 v137, 0xfffffbc0, v137
	v_add_u32_e32 v138, 0xfffff780, v138
	v_add_u32_e32 v139, 0xfffff340, v139
	v_lshrrev_b32_e32 v242, 6, v202
	v_and_b32_e32 v164, 63, v202
	v_bfe_u32 v243, v164, 1, 3
	v_lshrrev_b32_e32 v244, 4, v164
	v_xor_b32_e32 v243, v243, v244
	v_lshlrev_b32_e32 v243, 4, v243
	v_and_b32_e32 v244, 15, v164
	v_lshlrev_b32_e32 v244, 7, v244
	v_lshrrev_b32_e32 v144, 2, v242
	v_lshl_add_u32 v144, v144, 14, v244
	v_and_b32_e32 v146, 3, v242
	v_lshl_add_u32 v146, v146, 13, v244
	v_add_u32_e32 v146, 0x10000, v146
	v_xor_b32_e32 v145, 0x40, v243
	v_add_u32_e32 v145, v144, v145
	v_add_u32_e32 v144, v144, v243
	v_xor_b32_e32 v147, 0x40, v243
	v_add_u32_e32 v147, v146, v147
	v_add_u32_e32 v146, v146, v243
	v_lshrrev_b32_e32 v164, 4, v148
	v_bfe_u32 v242, v148, 2, 2
	v_lshrrev_b32_e32 v243, 1, v242
	v_mul_u32_u24_e32 v244, 0x1180, v164
	v_mul_u32_u24_e32 v243, 0x440, v243
	v_add_u32_e32 v244, v244, v243
	v_and_b32_e32 v243, 1, v242
	v_lshl_add_u32 v244, v243, 9, v244
	v_and_b32_e32 v164, 3, v148
	v_lshl_add_u32 v244, v164, 3, v244
	v_lshrrev_b32_e32 v164, 2, v149
	v_lshl_add_u32 v244, v164, 8, v244
	v_lshl_add_u32 v160, v243, 5, v244
	v_xor_b32_e32 v243, 1, v243
	v_lshl_add_u32 v161, v243, 5, v244
	s_cmp_ge_u32 s5, 0x4000
	s_cbranch_scc0 .Lp3a_t1
	s_add_u32 m0, s9, 0x0
	s_nop 0
	global_load_lds_dwordx4 v128, s[0:1]
	global_load_lds_dwordx4 v129, s[0:1] offset:1088
	global_load_lds_dwordx4 v130, s[0:1] offset:2176
	global_load_lds_dwordx4 v131, s[0:1] offset:3264
	s_add_u32 m0, s9, 0x1180
	s_nop 0
	global_load_lds_dwordx4 v136, s[0:1]
	global_load_lds_dwordx4 v137, s[0:1] offset:1088
	global_load_lds_dwordx4 v138, s[0:1] offset:2176
	global_load_lds_dwordx4 v139, s[0:1] offset:3264
	s_add_u32 m0, s5, 0xd800
	s_nop 0
	global_load_lds_dwordx4 v132, s[6:7]
	global_load_lds_dwordx4 v133, s[6:7] offset:1024
	global_load_lds_dwordx4 v134, s[6:7] offset:2048
	global_load_lds_dwordx4 v135, s[6:7] offset:3072
	s_add_u32 m0, s5, 0x11800
	s_nop 0
	global_load_lds_dwordx4 v140, s[6:7]
	global_load_lds_dwordx4 v141, s[6:7] offset:1024
	global_load_lds_dwordx4 v142, s[6:7] offset:2048
	global_load_lds_dwordx4 v143, s[6:7] offset:3072

; template <class AL, class BL>
; DEV void gemm_ktile(Acc& acc, const char* A, const char* B, int wm, int wn, int lr, int lh, const AL& al, const BL& bl,
;                     int tid, int m0, int n0, int knext, char* nxt, R4& ra, R4& rb) {
;   bf16x8 a[2][4], b[2][2];
;   const char* pa = A + (wm + lr) * LDSROW + lh * 16;
;   const char* pb = B + (wn + lr) * LDSROW + lh * 16;
; #pragma unroll
;   for (int i = 0; i < 4; ++i) a[0][i] = *(const bf16x8*)(pa + 32 * i * LDSROW);
; #pragma unroll
;   for (int j = 0; j < 2; ++j) b[0][j] = *(const bf16x8*)(pb + 32 * j * LDSROW);
; #pragma unroll
;   for (int ks = 0; ks < 4; ++ks) {
;     const int cur = ks & 1, nx = cur ^ 1;
;     if (ks < 3) {
; #pragma unroll
;       for (int i = 0; i < 4; ++i) a[nx][i] = *(const bf16x8*)(pa + 32 * i * LDSROW + (ks + 1) * 32);
; #pragma unroll
;       for (int j = 0; j < 2; ++j) b[nx][j] = *(const bf16x8*)(pb + 32 * j * LDSROW + (ks + 1) * 32);
;     }
;     __builtin_amdgcn_sched_barrier(0);
; #pragma unroll
;     for (int i = 0; i < 4; ++i)
; #pragma unroll
;       for (int j = 0; j < 2; ++j)
;         acc[i][j] = __builtin_amdgcn_mfma_f32_32x32x16_bf16(a[cur][i], b[cur][j], acc[i][j], 0, 0, 0);
; template <class AL, class BL>
; DEV void gemm_mainloop(Acc& acc, const AL& al, const BL& bl, int m0, int n0, int kbeg, int kend, char* lds) {
;     ...
;   for (int kt = 0; kt < nk; ++kt) {
;     const char* cur = lds + (kt & 1) * 2 * TILE_BYTES;
;     char* nxt = lds + ((kt + 1) & 1) * 2 * TILE_BYTES;
;     const int t2 = (kt + 2 < nk) ? kt + 2 : nk - 1;
;     __builtin_amdgcn_sched_barrier(0);
;     gemm_ktile(acc, cur, cur + TILE_BYTES, wm, wn, lr, lh, al, bl, tid, m0, n0, kbeg + t2 * BK, nxt, a0, b0);
;     __builtin_amdgcn_sched_barrier(0);
;     __syncthreads();
.Lp3a_k1loop:
	s_cmp_ge_u32 s5, 0x4000
	s_cbranch_scc0 .Lp3a_t2
	s_add_u32 m0, s9, 0x8c00
	s_nop 0
	global_load_lds_dwordx4 v128, s[0:1]
	global_load_lds_dwordx4 v129, s[0:1] offset:1088
	global_load_lds_dwordx4 v130, s[0:1] offset:2176
	global_load_lds_dwordx4 v131, s[0:1] offset:3264
	s_add_u32 m0, s9, 0x9d80
	s_nop 0
	global_load_lds_dwordx4 v136, s[0:1]
	global_load_lds_dwordx4 v137, s[0:1] offset:1088
	global_load_lds_dwordx4 v138, s[0:1] offset:2176
	global_load_lds_dwordx4 v139, s[0:1] offset:3264
	s_add_u32 m0, s5, 0x15800
	s_nop 0
	global_load_lds_dwordx4 v132, s[6:7]
	global_load_lds_dwordx4 v133, s[6:7] offset:1024
	global_load_lds_dwordx4 v134, s[6:7] offset:2048
	global_load_lds_dwordx4 v135, s[6:7] offset:3072
	s_add_u32 m0, s5, 0x19800
	s_nop 0
	global_load_lds_dwordx4 v140, s[6:7]
	global_load_lds_dwordx4 v141, s[6:7] offset:1024
	global_load_lds_dwordx4 v142, s[6:7] offset:2048
	global_load_lds_dwordx4 v143, s[6:7] offset:3072
.Lp3a_t2:
	s_add_u32 s0, s0, s10
	s_addc_u32 s1, s1, 0
	s_add_u32 s6, s6, 0x80
	s_addc_u32 s7, s7, 0
	ds_read_b128 v[166:169], v146 offset:6144
	ds_read_b128 v[170:173], v146 offset:8192
	ds_read_b128 v[174:177], v146 offset:10240
	ds_read_b128 v[178:181], v146 offset:12288
	ds_read_b64_tr_b16 v[222:223], v160 offset:0
	ds_read_b64_tr_b16 v[224:225], v160 offset:2176
	ds_read_b64_tr_b16 v[226:227], v161 offset:0
	ds_read_b64_tr_b16 v[228:229], v161 offset:2176
	ds_read_b64_tr_b16 v[230:231], v160 offset:64
	ds_read_b64_tr_b16 v[232:233], v160 offset:2240
	ds_read_b64_tr_b16 v[234:235], v161 offset:64
	ds_read_b64_tr_b16 v[236:237], v161 offset:2240
	ds_read_b64_tr_b16 v[238:239], v160 offset:128
	ds_read_b64_tr_b16 v[240:241], v160 offset:2304
	ds_read_b64_tr_b16 v[198:199], v161 offset:128
	ds_read_b64_tr_b16 v[200:201], v161 offset:2304
	ds_read_b64_tr_b16 v[152:153], v160 offset:192
	ds_read_b64_tr_b16 v[154:155], v160 offset:2368
	ds_read_b64_tr_b16 v[156:157], v161 offset:192
	ds_read_b64_tr_b16 v[158:159], v161 offset:2368
	ds_read_b128 v[182:185], v147 offset:6144
	ds_read_b128 v[186:189], v147 offset:8192
	ds_read_b128 v[190:193], v147 offset:10240
	ds_read_b128 v[194:197], v147 offset:12288
	s_waitcnt lgkmcnt(12)
	v_mfma_f32_16x16x32_bf16 v[0:3], v[166:169], v[222:225], v[0:3]
	v_mfma_f32_16x16x32_bf16 v[4:7], v[170:173], v[222:225], v[4:7]
	v_mfma_f32_16x16x32_bf16 v[8:11], v[174:177], v[222:225], v[8:11]
	v_mfma_f32_16x16x32_bf16 v[12:15], v[178:181], v[222:225], v[12:15]
	v_mfma_f32_16x16x32_bf16 v[16:19], v[166:169], v[226:229], v[16:19]
	v_mfma_f32_16x16x32_bf16 v[20:23], v[170:173], v[226:229], v[20:23]
	v_mfma_f32_16x16x32_bf16 v[24:27], v[174:177], v[226:229], v[24:27]
	v_mfma_f32_16x16x32_bf16 v[28:31], v[178:181], v[226:229], v[28:31]
	v_mfma_f32_16x16x32_bf16 v[32:35], v[166:169], v[230:233], v[32:35]
	v_mfma_f32_16x16x32_bf16 v[36:39], v[170:173], v[230:233], v[36:39]
	v_mfma_f32_16x16x32_bf16 v[40:43], v[174:177], v[230:233], v[40:43]
	v_mfma_f32_16x16x32_bf16 v[44:47], v[178:181], v[230:233], v[44:47]
	v_mfma_f32_16x16x32_bf16 v[48:51], v[166:169], v[234:237], v[48:51]
	v_mfma_f32_16x16x32_bf16 v[52:55], v[170:173], v[234:237], v[52:55]
	v_mfma_f32_16x16x32_bf16 v[56:59], v[174:177], v[234:237], v[56:59]
	v_mfma_f32_16x16x32_bf16 v[60:63], v[178:181], v[234:237], v[60:63]
	ds_read_b64_tr_b16 v[222:223], v160 offset:17920
	ds_read_b64_tr_b16 v[224:225], v160 offset:20096
	ds_read_b64_tr_b16 v[226:227], v161 offset:17920
	ds_read_b64_tr_b16 v[228:229], v161 offset:20096
	ds_read_b64_tr_b16 v[230:231], v160 offset:17984
	ds_read_b64_tr_b16 v[232:233], v160 offset:20160
	ds_read_b64_tr_b16 v[234:235], v161 offset:17984
	ds_read_b64_tr_b16 v[236:237], v161 offset:20160
	s_waitcnt lgkmcnt(12)
; template <class AL, class BL>
; DEV void gemm_ktile(Acc& acc, const char* A, const char* B, int wm, int wn, int lr, int lh, const AL& al, const BL& bl,
;                     int tid, int m0, int n0, int knext, char* nxt, R4& ra, R4& rb) {
;     ...
;   for (int ks = 0; ks < 4; ++ks) {
;     const int cur = ks & 1, nx = cur ^ 1;
;     if (ks < 3) {
; #pragma unroll
;       for (int i = 0; i < 4; ++i) a[nx][i] = *(const bf16x8*)(pa + 32 * i * LDSROW + (ks + 1) * 32);
; #pragma unroll
;       for (int j = 0; j < 2; ++j) b[nx][j] = *(const bf16x8*)(pb + 32 * j * LDSROW + (ks + 1) * 32);
;     }
;     __builtin_amdgcn_sched_barrier(0);
; #pragma unroll
;     for (int i = 0; i < 4; ++i)
; #pragma unroll
;       for (int j = 0; j < 2; ++j)
;         acc[i][j] = __builtin_amdgcn_mfma_f32_32x32x16_bf16(a[cur][i], b[cur][j], acc[i][j], 0, 0, 0);
;     __builtin_amdgcn_sched_barrier(0);
;     if (ks == 1) {
;       al.store(tid, nxt, ra);
;       bl.store(tid, nxt + TILE_BYTES, rb);
;       __builtin_amdgcn_sched_barrier(0);
;       ra = al.load(tid, m0, knext);
;       rb = bl.load(tid, n0, knext);
;       __builtin_amdgcn_sched_barrier(0);
;     }
	v_mfma_f32_16x16x32_bf16 v[64:67], v[166:169], v[238:241], v[64:67]
	v_mfma_f32_16x16x32_bf16 v[68:71], v[170:173], v[238:241], v[68:71]
	v_mfma_f32_16x16x32_bf16 v[72:75], v[174:177], v[238:241], v[72:75]
	v_mfma_f32_16x16x32_bf16 v[76:79], v[178:181], v[238:241], v[76:79]
	v_mfma_f32_16x16x32_bf16 v[80:83], v[166:169], v[198:201], v[80:83]
	v_mfma_f32_16x16x32_bf16 v[84:87], v[170:173], v[198:201], v[84:87]
	v_mfma_f32_16x16x32_bf16 v[88:91], v[174:177], v[198:201], v[88:91]
	v_mfma_f32_16x16x32_bf16 v[92:95], v[178:181], v[198:201], v[92:95]
	v_mfma_f32_16x16x32_bf16 v[96:99], v[166:169], v[152:155], v[96:99]
	v_mfma_f32_16x16x32_bf16 v[100:103], v[170:173], v[152:155], v[100:103]
	v_mfma_f32_16x16x32_bf16 v[104:107], v[174:177], v[152:155], v[104:107]
	v_mfma_f32_16x16x32_bf16 v[108:111], v[178:181], v[152:155], v[108:111]
	v_mfma_f32_16x16x32_bf16 v[112:115], v[166:169], v[156:159], v[112:115]
	v_mfma_f32_16x16x32_bf16 v[116:119], v[170:173], v[156:159], v[116:119]
	v_mfma_f32_16x16x32_bf16 v[120:123], v[174:177], v[156:159], v[120:123]
	v_mfma_f32_16x16x32_bf16 v[124:127], v[178:181], v[156:159], v[124:127]
	ds_read_b64_tr_b16 v[238:239], v160 offset:18048
	ds_read_b64_tr_b16 v[240:241], v160 offset:20224
	ds_read_b64_tr_b16 v[198:199], v161 offset:18048
	ds_read_b64_tr_b16 v[200:201], v161 offset:20224
	ds_read_b64_tr_b16 v[152:153], v160 offset:18112
	ds_read_b64_tr_b16 v[154:155], v160 offset:20288
	ds_read_b64_tr_b16 v[156:157], v161 offset:18112
	ds_read_b64_tr_b16 v[158:159], v161 offset:20288
	s_waitcnt lgkmcnt(8)
	v_mfma_f32_16x16x32_bf16 v[0:3], v[182:185], v[222:225], v[0:3]
	v_mfma_f32_16x16x32_bf16 v[4:7], v[186:189], v[222:225], v[4:7]
	v_mfma_f32_16x16x32_bf16 v[8:11], v[190:193], v[222:225], v[8:11]
	v_mfma_f32_16x16x32_bf16 v[12:15], v[194:197], v[222:225], v[12:15]
	v_mfma_f32_16x16x32_bf16 v[16:19], v[182:185], v[226:229], v[16:19]
	v_mfma_f32_16x16x32_bf16 v[20:23], v[186:189], v[226:229], v[20:23]
	v_mfma_f32_16x16x32_bf16 v[24:27], v[190:193], v[226:229], v[24:27]
	v_mfma_f32_16x16x32_bf16 v[28:31], v[194:197], v[226:229], v[28:31]
	v_mfma_f32_16x16x32_bf16 v[32:35], v[182:185], v[230:233], v[32:35]
	v_mfma_f32_16x16x32_bf16 v[36:39], v[186:189], v[230:233], v[36:39]
	v_mfma_f32_16x16x32_bf16 v[40:43], v[190:193], v[230:233], v[40:43]
	v_mfma_f32_16x16x32_bf16 v[44:47], v[194:197], v[230:233], v[44:47]
	v_mfma_f32_16x16x32_bf16 v[48:51], v[182:185], v[234:237], v[48:51]
	v_mfma_f32_16x16x32_bf16 v[52:55], v[186:189], v[234:237], v[52:55]
	v_mfma_f32_16x16x32_bf16 v[56:59], v[190:193], v[234:237], v[56:59]
	v_mfma_f32_16x16x32_bf16 v[60:63], v[194:197], v[234:237], v[60:63]
	s_waitcnt lgkmcnt(0)
	v_mfma_f32_16x16x32_bf16 v[64:67], v[182:185], v[238:241], v[64:67]
	v_mfma_f32_16x16x32_bf16 v[68:71], v[186:189], v[238:241], v[68:71]
	v_mfma_f32_16x16x32_bf16 v[72:75], v[190:193], v[238:241], v[72:75]
	v_mfma_f32_16x16x32_bf16 v[76:79], v[194:197], v[238:241], v[76:79]
	v_mfma_f32_16x16x32_bf16 v[80:83], v[182:185], v[198:201], v[80:83]
	v_mfma_f32_16x16x32_bf16 v[84:87], v[186:189], v[198:201], v[84:87]
	v_mfma_f32_16x16x32_bf16 v[88:91], v[190:193], v[198:201], v[88:91]
	v_mfma_f32_16x16x32_bf16 v[92:95], v[194:197], v[198:201], v[92:95]
	v_mfma_f32_16x16x32_bf16 v[96:99], v[182:185], v[152:155], v[96:99]
	v_mfma_f32_16x16x32_bf16 v[100:103], v[186:189], v[152:155], v[100:103]
	v_mfma_f32_16x16x32_bf16 v[104:107], v[190:193], v[152:155], v[104:107]
	v_mfma_f32_16x16x32_bf16 v[108:111], v[194:197], v[152:155], v[108:111]
	v_mfma_f32_16x16x32_bf16 v[112:115], v[182:185], v[156:159], v[112:115]
	v_mfma_f32_16x16x32_bf16 v[116:119], v[186:189], v[156:159], v[116:119]
	v_mfma_f32_16x16x32_bf16 v[120:123], v[190:193], v[156:159], v[120:123]
	v_mfma_f32_16x16x32_bf16 v[124:127], v[194:197], v[156:159], v[124:127]
	s_waitcnt vmcnt(0)
	s_barrier
	s_cmp_eq_u32 s8, 3
	s_cbranch_scc1 .Lp3a_k1last
	s_cmp_ge_u32 s5, 0x4000
	s_cbranch_scc0 .Lp3a_t3
	s_add_u32 m0, s9, 0x0
	s_nop 0
	global_load_lds_dwordx4 v128, s[0:1]
	global_load_lds_dwordx4 v129, s[0:1] offset:1088
	global_load_lds_dwordx4 v130, s[0:1] offset:2176
	global_load_lds_dwordx4 v131, s[0:1] offset:3264
	s_add_u32 m0, s9, 0x1180
	s_nop 0
	global_load_lds_dwordx4 v136, s[0:1]
	global_load_lds_dwordx4 v137, s[0:1] offset:1088
	global_load_lds_dwordx4 v138, s[0:1] offset:2176
	global_load_lds_dwordx4 v139, s[0:1] offset:3264
	s_add_u32 m0, s5, 0xd800
	s_nop 0
	global_load_lds_dwordx4 v132, s[6:7]
	global_load_lds_dwordx4 v133, s[6:7] offset:1024
	global_load_lds_dwordx4 v134, s[6:7] offset:2048
	global_load_lds_dwordx4 v135, s[6:7] offset:3072
	s_add_u32 m0, s5, 0x11800
	s_nop 0
	global_load_lds_dwordx4 v140, s[6:7]
	global_load_lds_dwordx4 v141, s[6:7] offset:1024
	global_load_lds_dwordx4 v142, s[6:7] offset:2048
	global_load_lds_dwordx4 v143, s[6:7] offset:3072

; template <class AL, class BL>
; DEV void gemm_mainloop(Acc& acc, const AL& al, const BL& bl, int m0, int n0, int kbeg, int kend, char* lds) {
;     ...
;   R4 a0 = al.load(tid, m0, kbeg);
;   R4 b0 = bl.load(tid, n0, kbeg);
;   __syncthreads();
;   al.store(tid, lds, a0);
;   bl.store(tid, lds + TILE_BYTES, b0);
;   a0 = al.load(tid, m0, kbeg + BK);
;   b0 = bl.load(tid, n0, kbeg + BK);
;   __syncthreads();
; DEV void phase_p3a(const Params& p, int g, char* smem) {
;     ...
;     {
;       RowLoader al{PHG - 512, 2560};
;       RowLoader bl{WbrT, 1024};
;       gemm_mainloop(acc, al, bl, m0, n0, 512, 1024, smem);
.Lp3a_mid0:
	v_add_u32_e32 v128, s3, v150
	v_mul_u32_u24_e32 v128, 0x1400, v128
	v_add_u32_e32 v128, v128, v151
	v_add_u32_e32 v129, 0x9c00, v128
	v_add_u32_e32 v130, 0x13800, v128
	v_add_u32_e32 v131, 0x1d400, v128
	v_xor_b32_e32 v129, 0x40, v129
	v_xor_b32_e32 v131, 0x40, v131
	v_add_u32_e32 v136, 0xa0000, v128
	v_add_u32_e32 v137, 0xa0000, v129
	v_add_u32_e32 v138, 0xa0000, v130
	v_add_u32_e32 v139, 0xa0000, v131
	s_mov_b64 s[0:1], s[56:57]
	v_readlane_b32 s6, v251, 16
	v_readlane_b32 s7, v251, 17
	s_add_u32 s6, s6, 0x400
	s_addc_u32 s7, s7, 0
	s_cmp_ge_u32 s5, 0x4000
	s_cbranch_scc0 .Lp3a_u1
	s_add_u32 m0, s5, 0xffffc000
	s_nop 0
	global_load_lds_dwordx4 v128, s[0:1]
	global_load_lds_dwordx4 v129, s[0:1] offset:1024
	global_load_lds_dwordx4 v130, s[0:1] offset:2048
	global_load_lds_dwordx4 v131, s[0:1] offset:3072
	s_add_u32 m0, s5, 0xc000
	s_nop 0
	global_load_lds_dwordx4 v132, s[6:7]
	global_load_lds_dwordx4 v133, s[6:7] offset:1024
	global_load_lds_dwordx4 v134, s[6:7] offset:2048
	global_load_lds_dwordx4 v135, s[6:7] offset:3072
	s_add_u32 m0, s5, 0x0
	s_nop 0
	global_load_lds_dwordx4 v136, s[0:1]
	global_load_lds_dwordx4 v137, s[0:1] offset:1024
	global_load_lds_dwordx4 v138, s[0:1] offset:2048
	global_load_lds_dwordx4 v139, s[0:1] offset:3072
	s_add_u32 m0, s5, 0x10000
	s_nop 0
	global_load_lds_dwordx4 v140, s[6:7]
	global_load_lds_dwordx4 v141, s[6:7] offset:1024
	global_load_lds_dwordx4 v142, s[6:7] offset:2048
	global_load_lds_dwordx4 v143, s[6:7] offset:3072

; template <class AL, class BL>
; DEV void gemm_ktile(Acc& acc, const char* A, const char* B, int wm, int wn, int lr, int lh, const AL& al, const BL& bl,
;                     int tid, int m0, int n0, int knext, char* nxt, R4& ra, R4& rb) {
;     ...
;     if (ks == 1) {
;       al.store(tid, nxt, ra);
;       bl.store(tid, nxt + TILE_BYTES, rb);
;       __builtin_amdgcn_sched_barrier(0);
;       ra = al.load(tid, m0, knext);
;       rb = bl.load(tid, n0, knext);
;       __builtin_amdgcn_sched_barrier(0);
.Lp3a_k2loop:
	s_cmp_ge_u32 s5, 0x4000
	s_cbranch_scc0 .Lp3a_u2
	s_add_u32 m0, s5, 0x4000
	s_nop 0
	global_load_lds_dwordx4 v128, s[0:1]
	global_load_lds_dwordx4 v129, s[0:1] offset:1024
	global_load_lds_dwordx4 v130, s[0:1] offset:2048
	global_load_lds_dwordx4 v131, s[0:1] offset:3072
	s_add_u32 m0, s5, 0x14000
	s_nop 0
	global_load_lds_dwordx4 v132, s[6:7]
	global_load_lds_dwordx4 v133, s[6:7] offset:1024
	global_load_lds_dwordx4 v134, s[6:7] offset:2048
	global_load_lds_dwordx4 v135, s[6:7] offset:3072
	s_add_u32 m0, s5, 0x8000
	s_nop 0
	global_load_lds_dwordx4 v136, s[0:1]
	global_load_lds_dwordx4 v137, s[0:1] offset:1024
	global_load_lds_dwordx4 v138, s[0:1] offset:2048
	global_load_lds_dwordx4 v139, s[0:1] offset:3072
	s_add_u32 m0, s5, 0x18000
	s_nop 0
	global_load_lds_dwordx4 v140, s[6:7]
	global_load_lds_dwordx4 v141, s[6:7] offset:1024
	global_load_lds_dwordx4 v142, s[6:7] offset:2048
	global_load_lds_dwordx4 v143, s[6:7] offset:3072
; template <class AL, class BL>
; DEV void gemm_ktile(Acc& acc, const char* A, const char* B, int wm, int wn, int lr, int lh, const AL& al, const BL& bl,
;                     int tid, int m0, int n0, int knext, char* nxt, R4& ra, R4& rb) {
;   bf16x8 a[2][4], b[2][2];
;   const char* pa = A + (wm + lr) * LDSROW + lh * 16;
;   const char* pb = B + (wn + lr) * LDSROW + lh * 16;
; #pragma unroll
;   for (int i = 0; i < 4; ++i) a[0][i] = *(const bf16x8*)(pa + 32 * i * LDSROW);
; #pragma unroll
;   for (int j = 0; j < 2; ++j) b[0][j] = *(const bf16x8*)(pb + 32 * j * LDSROW);
; #pragma unroll
;   for (int ks = 0; ks < 4; ++ks) {
;     const int cur = ks & 1, nx = cur ^ 1;
;     if (ks < 3) {
; #pragma unroll
;       for (int i = 0; i < 4; ++i) a[nx][i] = *(const bf16x8*)(pa + 32 * i * LDSROW + (ks + 1) * 32);
; #pragma unroll
;       for (int j = 0; j < 2; ++j) b[nx][j] = *(const bf16x8*)(pb + 32 * j * LDSROW + (ks + 1) * 32);
;     }
;     __builtin_amdgcn_sched_barrier(0);
; #pragma unroll
;     for (int i = 0; i < 4; ++i)
; #pragma unroll
;       for (int j = 0; j < 2; ++j)
;         acc[i][j] = __builtin_amdgcn_mfma_f32_32x32x16_bf16(a[cur][i], b[cur][j], acc[i][j], 0, 0, 0);
;     __builtin_amdgcn_sched_barrier(0);
;     if (ks == 1) {
;       al.store(tid, nxt, ra);
;       bl.store(tid, nxt + TILE_BYTES, rb);
;       __builtin_amdgcn_sched_barrier(0);
;       ra = al.load(tid, m0, knext);
;       rb = bl.load(tid, n0, knext);
;       __builtin_amdgcn_sched_barrier(0);
;     }
;   }
; }
.Lp3a_u2:
	s_add_u32 s0, s0, 0x80
	s_addc_u32 s1, s1, 0
	s_add_u32 s6, s6, 0x80
	s_addc_u32 s7, s7, 0
	ds_read_b128 v[166:169], v146
	ds_read_b128 v[170:173], v146 offset:2048
	ds_read_b128 v[174:177], v146 offset:4096
	ds_read_b128 v[178:181], v146 offset:6144
	ds_read_b128 v[222:225], v144
	ds_read_b128 v[226:229], v144 offset:2048
	ds_read_b128 v[230:233], v144 offset:4096
	ds_read_b128 v[234:237], v144 offset:6144
	ds_read_b128 v[238:241], v144 offset:8192
	ds_read_b128 v[198:201], v144 offset:10240
	ds_read_b128 v[152:155], v144 offset:12288
	ds_read_b128 v[156:159], v144 offset:14336
	ds_read_b128 v[182:185], v147
	ds_read_b128 v[186:189], v147 offset:2048
	ds_read_b128 v[190:193], v147 offset:4096
	ds_read_b128 v[194:197], v147 offset:6144
	s_waitcnt lgkmcnt(8)
	v_mfma_f32_16x16x32_bf16 v[0:3], v[166:169], v[222:225], v[0:3]
	v_mfma_f32_16x16x32_bf16 v[4:7], v[170:173], v[222:225], v[4:7]
	v_mfma_f32_16x16x32_bf16 v[8:11], v[174:177], v[222:225], v[8:11]
	v_mfma_f32_16x16x32_bf16 v[12:15], v[178:181], v[222:225], v[12:15]
	v_mfma_f32_16x16x32_bf16 v[16:19], v[166:169], v[226:229], v[16:19]
	v_mfma_f32_16x16x32_bf16 v[20:23], v[170:173], v[226:229], v[20:23]
	v_mfma_f32_16x16x32_bf16 v[24:27], v[174:177], v[226:229], v[24:27]
	v_mfma_f32_16x16x32_bf16 v[28:31], v[178:181], v[226:229], v[28:31]
	v_mfma_f32_16x16x32_bf16 v[32:35], v[166:169], v[230:233], v[32:35]
	v_mfma_f32_16x16x32_bf16 v[36:39], v[170:173], v[230:233], v[36:39]
	v_mfma_f32_16x16x32_bf16 v[40:43], v[174:177], v[230:233], v[40:43]
	v_mfma_f32_16x16x32_bf16 v[44:47], v[178:181], v[230:233], v[44:47]
	v_mfma_f32_16x16x32_bf16 v[48:51], v[166:169], v[234:237], v[48:51]
	v_mfma_f32_16x16x32_bf16 v[52:55], v[170:173], v[234:237], v[52:55]
	v_mfma_f32_16x16x32_bf16 v[56:59], v[174:177], v[234:237], v[56:59]
	v_mfma_f32_16x16x32_bf16 v[60:63], v[178:181], v[234:237], v[60:63]
	ds_read_b128 v[222:225], v145
	ds_read_b128 v[226:229], v145 offset:2048
	ds_read_b128 v[230:233], v145 offset:4096
	ds_read_b128 v[234:237], v145 offset:6144
	s_waitcnt lgkmcnt(8)
	v_mfma_f32_16x16x32_bf16 v[64:67], v[166:169], v[238:241], v[64:67]
	v_mfma_f32_16x16x32_bf16 v[68:71], v[170:173], v[238:241], v[68:71]
	v_mfma_f32_16x16x32_bf16 v[72:75], v[174:177], v[238:241], v[72:75]
	v_mfma_f32_16x16x32_bf16 v[76:79], v[178:181], v[238:241], v[76:79]
	v_mfma_f32_16x16x32_bf16 v[80:83], v[166:169], v[198:201], v[80:83]
	v_mfma_f32_16x16x32_bf16 v[84:87], v[170:173], v[198:201], v[84:87]
	v_mfma_f32_16x16x32_bf16 v[88:91], v[174:177], v[198:201], v[88:91]
	v_mfma_f32_16x16x32_bf16 v[92:95], v[178:181], v[198:201], v[92:95]
	v_mfma_f32_16x16x32_bf16 v[96:99], v[166:169], v[152:155], v[96:99]
	v_mfma_f32_16x16x32_bf16 v[100:103], v[170:173], v[152:155], v[100:103]
	v_mfma_f32_16x16x32_bf16 v[104:107], v[174:177], v[152:155], v[104:107]
	v_mfma_f32_16x16x32_bf16 v[108:111], v[178:181], v[152:155], v[108:111]
	v_mfma_f32_16x16x32_bf16 v[112:115], v[166:169], v[156:159], v[112:115]
	v_mfma_f32_16x16x32_bf16 v[116:119], v[170:173], v[156:159], v[116:119]
	v_mfma_f32_16x16x32_bf16 v[120:123], v[174:177], v[156:159], v[120:123]
	v_mfma_f32_16x16x32_bf16 v[124:127], v[178:181], v[156:159], v[124:127]
	ds_read_b128 v[238:241], v145 offset:8192
	ds_read_b128 v[198:201], v145 offset:10240
	ds_read_b128 v[152:155], v145 offset:12288
	ds_read_b128 v[156:159], v145 offset:14336
	s_waitcnt lgkmcnt(4)
	v_mfma_f32_16x16x32_bf16 v[0:3], v[182:185], v[222:225], v[0:3]
	v_mfma_f32_16x16x32_bf16 v[4:7], v[186:189], v[222:225], v[4:7]
	v_mfma_f32_16x16x32_bf16 v[8:11], v[190:193], v[222:225], v[8:11]
	v_mfma_f32_16x16x32_bf16 v[12:15], v[194:197], v[222:225], v[12:15]
	v_mfma_f32_16x16x32_bf16 v[16:19], v[182:185], v[226:229], v[16:19]
	v_mfma_f32_16x16x32_bf16 v[20:23], v[186:189], v[226:229], v[20:23]
	v_mfma_f32_16x16x32_bf16 v[24:27], v[190:193], v[226:229], v[24:27]
	v_mfma_f32_16x16x32_bf16 v[28:31], v[194:197], v[226:229], v[28:31]
	v_mfma_f32_16x16x32_bf16 v[32:35], v[182:185], v[230:233], v[32:35]
	v_mfma_f32_16x16x32_bf16 v[36:39], v[186:189], v[230:233], v[36:39]
	v_mfma_f32_16x16x32_bf16 v[40:43], v[190:193], v[230:233], v[40:43]
	v_mfma_f32_16x16x32_bf16 v[44:47], v[194:197], v[230:233], v[44:47]
	v_mfma_f32_16x16x32_bf16 v[48:51], v[182:185], v[234:237], v[48:51]
	v_mfma_f32_16x16x32_bf16 v[52:55], v[186:189], v[234:237], v[52:55]
	v_mfma_f32_16x16x32_bf16 v[56:59], v[190:193], v[234:237], v[56:59]
	v_mfma_f32_16x16x32_bf16 v[60:63], v[194:197], v[234:237], v[60:63]
	s_waitcnt lgkmcnt(0)
	v_mfma_f32_16x16x32_bf16 v[64:67], v[182:185], v[238:241], v[64:67]
	v_mfma_f32_16x16x32_bf16 v[68:71], v[186:189], v[238:241], v[68:71]
	v_mfma_f32_16x16x32_bf16 v[72:75], v[190:193], v[238:241], v[72:75]
	v_mfma_f32_16x16x32_bf16 v[76:79], v[194:197], v[238:241], v[76:79]
	v_mfma_f32_16x16x32_bf16 v[80:83], v[182:185], v[198:201], v[80:83]
	v_mfma_f32_16x16x32_bf16 v[84:87], v[186:189], v[198:201], v[84:87]
	v_mfma_f32_16x16x32_bf16 v[88:91], v[190:193], v[198:201], v[88:91]
	v_mfma_f32_16x16x32_bf16 v[92:95], v[194:197], v[198:201], v[92:95]
	v_mfma_f32_16x16x32_bf16 v[96:99], v[182:185], v[152:155], v[96:99]
	v_mfma_f32_16x16x32_bf16 v[100:103], v[186:189], v[152:155], v[100:103]
	v_mfma_f32_16x16x32_bf16 v[104:107], v[190:193], v[152:155], v[104:107]
	v_mfma_f32_16x16x32_bf16 v[108:111], v[194:197], v[152:155], v[108:111]
	v_mfma_f32_16x16x32_bf16 v[112:115], v[182:185], v[156:159], v[112:115]
	v_mfma_f32_16x16x32_bf16 v[116:119], v[186:189], v[156:159], v[116:119]
	v_mfma_f32_16x16x32_bf16 v[120:123], v[190:193], v[156:159], v[120:123]
	v_mfma_f32_16x16x32_bf16 v[124:127], v[194:197], v[156:159], v[124:127]
	s_waitcnt vmcnt(0)
	s_barrier
	s_cmp_eq_u32 s8, 3
	s_cbranch_scc1 .Lp3a_k2last
	s_cmp_ge_u32 s5, 0x4000
	s_cbranch_scc0 .Lp3a_u3
	s_add_u32 m0, s5, 0xffffc000
	s_nop 0
	global_load_lds_dwordx4 v128, s[0:1]
	global_load_lds_dwordx4 v129, s[0:1] offset:1024
	global_load_lds_dwordx4 v130, s[0:1] offset:2048
	global_load_lds_dwordx4 v131, s[0:1] offset:3072
	s_add_u32 m0, s5, 0xc000
	s_nop 0
	global_load_lds_dwordx4 v132, s[6:7]
	global_load_lds_dwordx4 v133, s[6:7] offset:1024
	global_load_lds_dwordx4 v134, s[6:7] offset:2048
	global_load_lds_dwordx4 v135, s[6:7] offset:3072
	s_add_u32 m0, s5, 0x0
	s_nop 0
	global_load_lds_dwordx4 v136, s[0:1]
	global_load_lds_dwordx4 v137, s[0:1] offset:1024
	global_load_lds_dwordx4 v138, s[0:1] offset:2048
	global_load_lds_dwordx4 v139, s[0:1] offset:3072
	s_add_u32 m0, s5, 0x10000
	s_nop 0
	global_load_lds_dwordx4 v140, s[6:7]
	global_load_lds_dwordx4 v141, s[6:7] offset:1024
	global_load_lds_dwordx4 v142, s[6:7] offset:2048
	global_load_lds_dwordx4 v143, s[6:7] offset:3072

; template <class AL, class BL>
; DEV void gemm_mainloop(Acc& acc, const AL& al, const BL& bl, int m0, int n0, int kbeg, int kend, char* lds) {
;   const int tid = tidx_full();
;   const int wave = tid >> 6, lane = tid & 63;
;   const int wm = (wave >> 2) * 128, wn = (wave & 3) * 64;
;   const int lr = lane & 31, lh = lane >> 5;
;   const int nk = (kend - kbeg) / BK;
;   R4 a0 = al.load(tid, m0, kbeg);
;   R4 b0 = bl.load(tid, n0, kbeg);
;   __syncthreads();
;   al.store(tid, lds, a0);
;   bl.store(tid, lds + TILE_BYTES, b0);
;   a0 = al.load(tid, m0, kbeg + BK);
;   b0 = bl.load(tid, n0, kbeg + BK);
;   __syncthreads();
; DEV void phase_p3b(const Params& p, int g, char* smem) {
;     ...
;   for (int iter = 0;; ++iter) {
;     int mt, nt;
;     if (!tile_map(iter, 128, 4, mt, nt)) break;
;     const int m0 = mt * 256, n0 = nt * 256;
;     Acc acc;
;     acc_zero(acc);
;     RowLoader al{PHG + 1024, 2560}, bl{WoutT, 1024};
;     gemm_mainloop(acc, al, bl, m0, n0, 0, 1024, smem);
.LBB0_1001:
	v_readlane_b32 s2, v251, 23
	v_readlane_b32 s3, v251, 24
	v_readlane_b32 s10, v251, 21
	v_readlane_b32 s11, v251, 22
	s_lshl_b32 s5, s7, 8
	s_lshl_b32 s4, s8, 8
	v_lshrrev_b32_e32 v149, 6, v202
	v_and_b32_e32 v148, 63, v202
	s_nop 0
	v_readfirstlane_b32 s9, v149
	v_lshrrev_b32_e32 v150, 3, v148
	v_and_b32_e32 v151, 3, v149
	v_lshl_add_u32 v150, v151, 5, v150
	v_and_b32_e32 v151, 7, v148
	v_lshrrev_b32_e32 v128, 4, v148
	v_xor_b32_e32 v151, v128, v151
	v_lshlrev_b32_e32 v151, 4, v151
	s_lshl_b32 s9, s9, 12
	v_add_u32_e32 v128, s5, v150
	v_mul_u32_u24_e32 v128, 0x1400, v128
	v_add_u32_e32 v128, v128, v151
	v_add_u32_e32 v129, 0x9c00, v128
	v_add_u32_e32 v130, 0x13800, v128
	v_add_u32_e32 v131, 0x1d400, v128
	v_xor_b32_e32 v129, 0x40, v129
	v_xor_b32_e32 v131, 0x40, v131
	v_add_u32_e32 v136, 0xa0000, v128
	v_add_u32_e32 v137, 0xa0000, v129
	v_add_u32_e32 v138, 0xa0000, v130
	v_add_u32_e32 v139, 0xa0000, v131
	v_add_u32_e32 v132, s4, v150
	v_lshlrev_b32_e32 v132, 11, v132
	v_add_u32_e32 v132, v132, v151
	v_add_u32_e32 v133, 0x3c00, v132
	v_add_u32_e32 v134, 0x7800, v132
	v_add_u32_e32 v135, 0xb400, v132
	v_xor_b32_e32 v133, 0x40, v133
	v_xor_b32_e32 v135, 0x40, v135
	v_add_u32_e32 v140, 0x40000, v132
	v_add_u32_e32 v141, 0x40000, v133
	v_add_u32_e32 v142, 0x40000, v134
	v_add_u32_e32 v143, 0x40000, v135
	v_lshrrev_b32_e32 v161, 6, v202
	v_and_b32_e32 v160, 63, v202
	v_bfe_u32 v164, v160, 1, 3
	v_lshrrev_b32_e32 v199, 4, v160
	v_xor_b32_e32 v164, v164, v199
	v_lshlrev_b32_e32 v164, 4, v164
	v_and_b32_e32 v199, 15, v160
	v_lshlrev_b32_e32 v199, 7, v199
	v_lshrrev_b32_e32 v144, 2, v161
	v_lshl_add_u32 v144, v144, 14, v199
	v_and_b32_e32 v146, 3, v161
	v_lshl_add_u32 v146, v146, 13, v199
	v_add_u32_e32 v146, 0x10000, v146
	v_xor_b32_e32 v145, 0x40, v164
	v_add_u32_e32 v145, v144, v145
	v_add_u32_e32 v144, v144, v164
	v_xor_b32_e32 v147, 0x40, v164
	v_add_u32_e32 v147, v146, v147
	v_add_u32_e32 v146, v146, v164
	s_mov_b64 s[12:13], s[2:3]
	s_mov_b64 s[14:15], s[10:11]
	s_cmp_ge_u32 s9, 0x4000
	s_cbranch_scc0 .Lp3b_d1
	s_add_u32 m0, s9, 0xffffc000
	s_nop 0
	global_load_lds_dwordx4 v128, s[12:13]
	global_load_lds_dwordx4 v129, s[12:13] offset:1024
	global_load_lds_dwordx4 v130, s[12:13] offset:2048
	global_load_lds_dwordx4 v131, s[12:13] offset:3072
	s_add_u32 m0, s9, 0xc000
	s_nop 0
	global_load_lds_dwordx4 v132, s[14:15]
	global_load_lds_dwordx4 v133, s[14:15] offset:1024
	global_load_lds_dwordx4 v134, s[14:15] offset:2048
	global_load_lds_dwordx4 v135, s[14:15] offset:3072
	s_add_u32 m0, s9, 0x0
	s_nop 0
	global_load_lds_dwordx4 v136, s[12:13]
	global_load_lds_dwordx4 v137, s[12:13] offset:1024
	global_load_lds_dwordx4 v138, s[12:13] offset:2048
	global_load_lds_dwordx4 v139, s[12:13] offset:3072
	s_add_u32 m0, s9, 0x10000
	s_nop 0
	global_load_lds_dwordx4 v140, s[14:15]
	global_load_lds_dwordx4 v141, s[14:15] offset:1024
	global_load_lds_dwordx4 v142, s[14:15] offset:2048
	global_load_lds_dwordx4 v143, s[14:15] offset:3072

; template <class AL, class BL>
; DEV void gemm_ktile(Acc& acc, const char* A, const char* B, int wm, int wn, int lr, int lh, const AL& al, const BL& bl,
;                     int tid, int m0, int n0, int knext, char* nxt, R4& ra, R4& rb) {
;     ...
;     if (ks == 1) {
;       al.store(tid, nxt, ra);
;       bl.store(tid, nxt + TILE_BYTES, rb);
;       __builtin_amdgcn_sched_barrier(0);
;       ra = al.load(tid, m0, knext);
;       rb = bl.load(tid, n0, knext);
;       __builtin_amdgcn_sched_barrier(0);
.Lp3b_kloop:
	s_cmp_ge_u32 s9, 0x4000
	s_cbranch_scc0 .Lp3b_d2
	s_add_u32 m0, s9, 0x4000
	s_nop 0
	global_load_lds_dwordx4 v128, s[12:13]
	global_load_lds_dwordx4 v129, s[12:13] offset:1024
	global_load_lds_dwordx4 v130, s[12:13] offset:2048
	global_load_lds_dwordx4 v131, s[12:13] offset:3072
	s_add_u32 m0, s9, 0x14000
	s_nop 0
	global_load_lds_dwordx4 v132, s[14:15]
	global_load_lds_dwordx4 v133, s[14:15] offset:1024
	global_load_lds_dwordx4 v134, s[14:15] offset:2048
	global_load_lds_dwordx4 v135, s[14:15] offset:3072
	s_add_u32 m0, s9, 0x8000
	s_nop 0
	global_load_lds_dwordx4 v136, s[12:13]
	global_load_lds_dwordx4 v137, s[12:13] offset:1024
	global_load_lds_dwordx4 v138, s[12:13] offset:2048
	global_load_lds_dwordx4 v139, s[12:13] offset:3072
	s_add_u32 m0, s9, 0x18000
	s_nop 0
	global_load_lds_dwordx4 v140, s[14:15]
	global_load_lds_dwordx4 v141, s[14:15] offset:1024
	global_load_lds_dwordx4 v142, s[14:15] offset:2048
	global_load_lds_dwordx4 v143, s[14:15] offset:3072
; template <class AL, class BL>
; DEV void gemm_ktile(Acc& acc, const char* A, const char* B, int wm, int wn, int lr, int lh, const AL& al, const BL& bl,
;                     int tid, int m0, int n0, int knext, char* nxt, R4& ra, R4& rb) {
;   bf16x8 a[2][4], b[2][2];
;   const char* pa = A + (wm + lr) * LDSROW + lh * 16;
;   const char* pb = B + (wn + lr) * LDSROW + lh * 16;
; #pragma unroll
;   for (int i = 0; i < 4; ++i) a[0][i] = *(const bf16x8*)(pa + 32 * i * LDSROW);
; #pragma unroll
;   for (int j = 0; j < 2; ++j) b[0][j] = *(const bf16x8*)(pb + 32 * j * LDSROW);
; #pragma unroll
;   for (int ks = 0; ks < 4; ++ks) {
;     const int cur = ks & 1, nx = cur ^ 1;
;     if (ks < 3) {
; #pragma unroll
;       for (int i = 0; i < 4; ++i) a[nx][i] = *(const bf16x8*)(pa + 32 * i * LDSROW + (ks + 1) * 32);
; #pragma unroll
;       for (int j = 0; j < 2; ++j) b[nx][j] = *(const bf16x8*)(pb + 32 * j * LDSROW + (ks + 1) * 32);
;     }
;     __builtin_amdgcn_sched_barrier(0);
; #pragma unroll
;     for (int i = 0; i < 4; ++i)
; #pragma unroll
;       for (int j = 0; j < 2; ++j)
;         acc[i][j] = __builtin_amdgcn_mfma_f32_32x32x16_bf16(a[cur][i], b[cur][j], acc[i][j], 0, 0, 0);
;     __builtin_amdgcn_sched_barrier(0);
;     if (ks == 1) {
;       al.store(tid, nxt, ra);
;       bl.store(tid, nxt + TILE_BYTES, rb);
;       __builtin_amdgcn_sched_barrier(0);
;       ra = al.load(tid, m0, knext);
;       rb = bl.load(tid, n0, knext);
;       __builtin_amdgcn_sched_barrier(0);
;     }
;   }
; }
.Lp3b_d2:
	s_add_u32 s12, s12, 0x80
	s_addc_u32 s13, s13, 0
	s_add_u32 s14, s14, 0x80
	s_addc_u32 s15, s15, 0
	ds_read_b128 v[166:169], v146
	ds_read_b128 v[170:173], v146 offset:2048
	ds_read_b128 v[174:177], v146 offset:4096
	ds_read_b128 v[178:181], v146 offset:6144
	ds_read_b128 v[222:225], v144
	ds_read_b128 v[226:229], v144 offset:2048
	ds_read_b128 v[230:233], v144 offset:4096
	ds_read_b128 v[234:237], v144 offset:6144
	ds_read_b128 v[238:241], v144 offset:8192
	ds_read_b128 v[198:201], v144 offset:10240
	ds_read_b128 v[152:155], v144 offset:12288
	ds_read_b128 v[156:159], v144 offset:14336
	ds_read_b128 v[182:185], v147
	ds_read_b128 v[186:189], v147 offset:2048
	ds_read_b128 v[190:193], v147 offset:4096
	ds_read_b128 v[194:197], v147 offset:6144
	s_waitcnt lgkmcnt(8)
	v_mfma_f32_16x16x32_bf16 v[0:3], v[166:169], v[222:225], v[0:3]
	v_mfma_f32_16x16x32_bf16 v[4:7], v[170:173], v[222:225], v[4:7]
	v_mfma_f32_16x16x32_bf16 v[8:11], v[174:177], v[222:225], v[8:11]
	v_mfma_f32_16x16x32_bf16 v[12:15], v[178:181], v[222:225], v[12:15]
	v_mfma_f32_16x16x32_bf16 v[16:19], v[166:169], v[226:229], v[16:19]
	v_mfma_f32_16x16x32_bf16 v[20:23], v[170:173], v[226:229], v[20:23]
	v_mfma_f32_16x16x32_bf16 v[24:27], v[174:177], v[226:229], v[24:27]
	v_mfma_f32_16x16x32_bf16 v[28:31], v[178:181], v[226:229], v[28:31]
	v_mfma_f32_16x16x32_bf16 v[32:35], v[166:169], v[230:233], v[32:35]
	v_mfma_f32_16x16x32_bf16 v[36:39], v[170:173], v[230:233], v[36:39]
	v_mfma_f32_16x16x32_bf16 v[40:43], v[174:177], v[230:233], v[40:43]
	v_mfma_f32_16x16x32_bf16 v[44:47], v[178:181], v[230:233], v[44:47]
	v_mfma_f32_16x16x32_bf16 v[48:51], v[166:169], v[234:237], v[48:51]
	v_mfma_f32_16x16x32_bf16 v[52:55], v[170:173], v[234:237], v[52:55]
	v_mfma_f32_16x16x32_bf16 v[56:59], v[174:177], v[234:237], v[56:59]
	v_mfma_f32_16x16x32_bf16 v[60:63], v[178:181], v[234:237], v[60:63]
	ds_read_b128 v[222:225], v145
	ds_read_b128 v[226:229], v145 offset:2048
	ds_read_b128 v[230:233], v145 offset:4096
	ds_read_b128 v[234:237], v145 offset:6144
	s_waitcnt lgkmcnt(8)
	v_mfma_f32_16x16x32_bf16 v[64:67], v[166:169], v[238:241], v[64:67]
	v_mfma_f32_16x16x32_bf16 v[68:71], v[170:173], v[238:241], v[68:71]
	v_mfma_f32_16x16x32_bf16 v[72:75], v[174:177], v[238:241], v[72:75]
	v_mfma_f32_16x16x32_bf16 v[76:79], v[178:181], v[238:241], v[76:79]
	v_mfma_f32_16x16x32_bf16 v[80:83], v[166:169], v[198:201], v[80:83]
	v_mfma_f32_16x16x32_bf16 v[84:87], v[170:173], v[198:201], v[84:87]
	v_mfma_f32_16x16x32_bf16 v[88:91], v[174:177], v[198:201], v[88:91]
	v_mfma_f32_16x16x32_bf16 v[92:95], v[178:181], v[198:201], v[92:95]
	v_mfma_f32_16x16x32_bf16 v[96:99], v[166:169], v[152:155], v[96:99]
	v_mfma_f32_16x16x32_bf16 v[100:103], v[170:173], v[152:155], v[100:103]
	v_mfma_f32_16x16x32_bf16 v[104:107], v[174:177], v[152:155], v[104:107]
	v_mfma_f32_16x16x32_bf16 v[108:111], v[178:181], v[152:155], v[108:111]
	v_mfma_f32_16x16x32_bf16 v[112:115], v[166:169], v[156:159], v[112:115]
	v_mfma_f32_16x16x32_bf16 v[116:119], v[170:173], v[156:159], v[116:119]
	v_mfma_f32_16x16x32_bf16 v[120:123], v[174:177], v[156:159], v[120:123]
	v_mfma_f32_16x16x32_bf16 v[124:127], v[178:181], v[156:159], v[124:127]
	ds_read_b128 v[238:241], v145 offset:8192
	ds_read_b128 v[198:201], v145 offset:10240
	ds_read_b128 v[152:155], v145 offset:12288
	ds_read_b128 v[156:159], v145 offset:14336
	s_waitcnt lgkmcnt(4)
	v_mfma_f32_16x16x32_bf16 v[0:3], v[182:185], v[222:225], v[0:3]
	v_mfma_f32_16x16x32_bf16 v[4:7], v[186:189], v[222:225], v[4:7]
	v_mfma_f32_16x16x32_bf16 v[8:11], v[190:193], v[222:225], v[8:11]
	v_mfma_f32_16x16x32_bf16 v[12:15], v[194:197], v[222:225], v[12:15]
	v_mfma_f32_16x16x32_bf16 v[16:19], v[182:185], v[226:229], v[16:19]
	v_mfma_f32_16x16x32_bf16 v[20:23], v[186:189], v[226:229], v[20:23]
	v_mfma_f32_16x16x32_bf16 v[24:27], v[190:193], v[226:229], v[24:27]
	v_mfma_f32_16x16x32_bf16 v[28:31], v[194:197], v[226:229], v[28:31]
	v_mfma_f32_16x16x32_bf16 v[32:35], v[182:185], v[230:233], v[32:35]
	v_mfma_f32_16x16x32_bf16 v[36:39], v[186:189], v[230:233], v[36:39]
	v_mfma_f32_16x16x32_bf16 v[40:43], v[190:193], v[230:233], v[40:43]
	v_mfma_f32_16x16x32_bf16 v[44:47], v[194:197], v[230:233], v[44:47]
	v_mfma_f32_16x16x32_bf16 v[48:51], v[182:185], v[234:237], v[48:51]
	v_mfma_f32_16x16x32_bf16 v[52:55], v[186:189], v[234:237], v[52:55]
	v_mfma_f32_16x16x32_bf16 v[56:59], v[190:193], v[234:237], v[56:59]
	v_mfma_f32_16x16x32_bf16 v[60:63], v[194:197], v[234:237], v[60:63]
	s_waitcnt lgkmcnt(0)
	v_mfma_f32_16x16x32_bf16 v[64:67], v[182:185], v[238:241], v[64:67]
	v_mfma_f32_16x16x32_bf16 v[68:71], v[186:189], v[238:241], v[68:71]
	v_mfma_f32_16x16x32_bf16 v[72:75], v[190:193], v[238:241], v[72:75]
	v_mfma_f32_16x16x32_bf16 v[76:79], v[194:197], v[238:241], v[76:79]
	v_mfma_f32_16x16x32_bf16 v[80:83], v[182:185], v[198:201], v[80:83]
	v_mfma_f32_16x16x32_bf16 v[84:87], v[186:189], v[198:201], v[84:87]
	v_mfma_f32_16x16x32_bf16 v[88:91], v[190:193], v[198:201], v[88:91]
	v_mfma_f32_16x16x32_bf16 v[92:95], v[194:197], v[198:201], v[92:95]
	v_mfma_f32_16x16x32_bf16 v[96:99], v[182:185], v[152:155], v[96:99]
	v_mfma_f32_16x16x32_bf16 v[100:103], v[186:189], v[152:155], v[100:103]
	v_mfma_f32_16x16x32_bf16 v[104:107], v[190:193], v[152:155], v[104:107]
	v_mfma_f32_16x16x32_bf16 v[108:111], v[194:197], v[152:155], v[108:111]
	v_mfma_f32_16x16x32_bf16 v[112:115], v[182:185], v[156:159], v[112:115]
	v_mfma_f32_16x16x32_bf16 v[116:119], v[186:189], v[156:159], v[116:119]
	v_mfma_f32_16x16x32_bf16 v[120:123], v[190:193], v[156:159], v[120:123]
	v_mfma_f32_16x16x32_bf16 v[124:127], v[194:197], v[156:159], v[124:127]
	s_waitcnt vmcnt(0)
	s_barrier
	s_cmp_eq_u32 s7, 7
	s_cbranch_scc1 .Lp3b_last
	s_cmp_ge_u32 s9, 0x4000
	s_cbranch_scc0 .Lp3b_d3
	s_add_u32 m0, s9, 0xffffc000
	s_nop 0
	global_load_lds_dwordx4 v128, s[12:13]
	global_load_lds_dwordx4 v129, s[12:13] offset:1024
	global_load_lds_dwordx4 v130, s[12:13] offset:2048
	global_load_lds_dwordx4 v131, s[12:13] offset:3072
	s_add_u32 m0, s9, 0xc000
	s_nop 0
	global_load_lds_dwordx4 v132, s[14:15]
	global_load_lds_dwordx4 v133, s[14:15] offset:1024
	global_load_lds_dwordx4 v134, s[14:15] offset:2048
	global_load_lds_dwordx4 v135, s[14:15] offset:3072
	s_add_u32 m0, s9, 0x0
	s_nop 0
	global_load_lds_dwordx4 v136, s[12:13]
	global_load_lds_dwordx4 v137, s[12:13] offset:1024
	global_load_lds_dwordx4 v138, s[12:13] offset:2048
	global_load_lds_dwordx4 v139, s[12:13] offset:3072
	s_add_u32 m0, s9, 0x10000
	s_nop 0
	global_load_lds_dwordx4 v140, s[14:15]
	global_load_lds_dwordx4 v141, s[14:15] offset:1024
	global_load_lds_dwordx4 v142, s[14:15] offset:2048
	global_load_lds_dwordx4 v143, s[14:15] offset:3072

; template <class AL, class BL>
; DEV void gemm_mainloop_p(Acc& acc, const AL& al, const BL& bl, int m0, int n0, int m0n, int n0n, int K, char* lds,
;                          GemmPipe& gp) {
;   const int tid = tidx_full();
;   const int wave = tid >> 6, lane = tid & 63;
;   const int wm = (wave >> 2) * 128, wn = (wave & 3) * 64;
;   const int lr = lane & 31, lh = lane >> 5;
;   const int nk = K / BK;
;   if (!gp.primed) {
;     gp.ra = al.load(tid, m0, 0);
;     gp.rb = bl.load(tid, n0, 0);
;     __syncthreads();
;     al.store(tid, lds, gp.ra);
;     bl.store(tid, lds + TILE_BYTES, gp.rb);
;     gp.ra = al.load(tid, m0, BK);
;     gp.rb = bl.load(tid, n0, BK);
;     __syncthreads();
;   }
; DEV void phase_ff1(const Params& p, int g, char* smem) {
;     ...
;   for (int iter = 0;; ++iter) {
;     int mt, nt, mtn, ntn;
;     if (!tile_map(iter, 128, 16, mt, nt)) break;
;     const bool more = tile_map(iter + 1, 128, 16, mtn, ntn);
;     if (!more) { mtn = mt; ntn = nt; }
;     const int m0 = mt * 256, n0 = nt * 256;
;     Acc acc;
;     acc_zero(acc);
;     RowLoader al{H2, 1024}, bl{W, 1024};
;     gemm_mainloop_p(acc, al, bl, m0, n0, mtn * 256, ntn * 256, 1024, smem, gp);
.LBB0_1126:
	v_readlane_b32 s18, v249, 48
	v_readlane_b32 s19, v249, 49
	v_readlane_b32 s20, v251, 25
	v_readlane_b32 s21, v251, 26
	s_and_b64 vcc, exec, s[2:3]
	s_lshl_b32 s5, s9, 8
	s_lshl_b32 s4, s10, 8
	v_lshrrev_b32_e32 v149, 6, v202
	v_and_b32_e32 v148, 63, v202
	s_nop 0
	v_readfirstlane_b32 s13, v149
	v_lshrrev_b32_e32 v150, 3, v148
	v_and_b32_e32 v151, 3, v149
	v_lshl_add_u32 v150, v151, 5, v150
	v_and_b32_e32 v151, 7, v148
	v_lshrrev_b32_e32 v128, 4, v148
	v_xor_b32_e32 v151, v128, v151
	v_lshlrev_b32_e32 v151, 4, v151
	s_lshl_b32 s13, s13, 12
	v_add_u32_e32 v128, s5, v150
	v_lshlrev_b32_e32 v128, 11, v128
	v_add_u32_e32 v128, v128, v151
	v_add_u32_e32 v129, 0x3c00, v128
	v_add_u32_e32 v130, 0x7800, v128
	v_add_u32_e32 v131, 0xb400, v128
	v_xor_b32_e32 v129, 0x40, v129
	v_xor_b32_e32 v131, 0x40, v131
	v_add_u32_e32 v132, s4, v150
	v_lshlrev_b32_e32 v132, 11, v132
	v_add_u32_e32 v132, v132, v151
	v_add_u32_e32 v133, 0x3c00, v132
	v_add_u32_e32 v134, 0x7800, v132
	v_add_u32_e32 v135, 0xb400, v132
	v_xor_b32_e32 v133, 0x40, v133
	v_xor_b32_e32 v135, 0x40, v135
	v_add_u32_e32 v136, 0x40000, v128
	v_add_u32_e32 v137, 0x40000, v129
	v_add_u32_e32 v138, 0x40000, v130
	v_add_u32_e32 v139, 0x40000, v131
	v_add_u32_e32 v140, 0x40000, v132
	v_add_u32_e32 v141, 0x40000, v133
	v_add_u32_e32 v142, 0x40000, v134
	v_add_u32_e32 v143, 0x40000, v135
	v_lshrrev_b32_e32 v161, 6, v202
	v_and_b32_e32 v160, 63, v202
	v_bfe_u32 v242, v160, 1, 3
	v_lshrrev_b32_e32 v243, 4, v160
	v_xor_b32_e32 v242, v242, v243
	v_lshlrev_b32_e32 v242, 4, v242
	v_and_b32_e32 v243, 15, v160
	v_lshlrev_b32_e32 v243, 7, v243
	v_lshrrev_b32_e32 v144, 2, v161
	v_lshl_add_u32 v144, v144, 14, v243
	v_and_b32_e32 v146, 3, v161
	v_lshl_add_u32 v146, v146, 13, v243
	v_add_u32_e32 v146, 0x10000, v146
	v_xor_b32_e32 v145, 0x40, v242
	v_add_u32_e32 v145, v144, v145
	v_add_u32_e32 v144, v144, v242
	v_xor_b32_e32 v147, 0x40, v242
	v_add_u32_e32 v147, v146, v147
	v_add_u32_e32 v146, v146, v242
	s_mov_b64 s[22:23], s[18:19]
	s_mov_b64 s[14:15], s[20:21]
	s_cbranch_vccnz .Lff1_primed
	s_cmp_ge_u32 s13, 0x4000
	s_cbranch_scc0 .Lff1_d1
	s_add_u32 m0, s13, 0xffffc000
	s_nop 0
	global_load_lds_dwordx4 v128, s[22:23]
	global_load_lds_dwordx4 v129, s[22:23] offset:1024
	global_load_lds_dwordx4 v130, s[22:23] offset:2048
	global_load_lds_dwordx4 v131, s[22:23] offset:3072
	s_add_u32 m0, s13, 0xc000
	s_nop 0
	global_load_lds_dwordx4 v132, s[14:15]
	global_load_lds_dwordx4 v133, s[14:15] offset:1024
	global_load_lds_dwordx4 v134, s[14:15] offset:2048
	global_load_lds_dwordx4 v135, s[14:15] offset:3072
	s_add_u32 m0, s13, 0x0
	s_nop 0
	global_load_lds_dwordx4 v136, s[22:23]
	global_load_lds_dwordx4 v137, s[22:23] offset:1024
	global_load_lds_dwordx4 v138, s[22:23] offset:2048
	global_load_lds_dwordx4 v139, s[22:23] offset:3072
	s_add_u32 m0, s13, 0x10000
	s_nop 0
	global_load_lds_dwordx4 v140, s[14:15]
	global_load_lds_dwordx4 v141, s[14:15] offset:1024
	global_load_lds_dwordx4 v142, s[14:15] offset:2048
	global_load_lds_dwordx4 v143, s[14:15] offset:3072

; template <class AL, class BL>
; DEV void gemm_ktile(Acc& acc, const char* A, const char* B, int wm, int wn, int lr, int lh, const AL& al, const BL& bl,
;                     int tid, int m0, int n0, int knext, char* nxt, R4& ra, R4& rb) {
;     ...
;     if (ks == 1) {
;       al.store(tid, nxt, ra);
;       bl.store(tid, nxt + TILE_BYTES, rb);
;       __builtin_amdgcn_sched_barrier(0);
;       ra = al.load(tid, m0, knext);
;       rb = bl.load(tid, n0, knext);
;       __builtin_amdgcn_sched_barrier(0);
.Lff1_kloop:
	s_cmp_ge_u32 s13, 0x4000
	s_cbranch_scc0 .Lff1_d2
	s_add_u32 m0, s13, 0x4000
	s_nop 0
	global_load_lds_dwordx4 v128, s[22:23]
	global_load_lds_dwordx4 v129, s[22:23] offset:1024
	global_load_lds_dwordx4 v130, s[22:23] offset:2048
	global_load_lds_dwordx4 v131, s[22:23] offset:3072
	s_add_u32 m0, s13, 0x14000
	s_nop 0
	global_load_lds_dwordx4 v132, s[14:15]
	global_load_lds_dwordx4 v133, s[14:15] offset:1024
	global_load_lds_dwordx4 v134, s[14:15] offset:2048
	global_load_lds_dwordx4 v135, s[14:15] offset:3072
	s_add_u32 m0, s13, 0x8000
	s_nop 0
	global_load_lds_dwordx4 v136, s[22:23]
	global_load_lds_dwordx4 v137, s[22:23] offset:1024
	global_load_lds_dwordx4 v138, s[22:23] offset:2048
	global_load_lds_dwordx4 v139, s[22:23] offset:3072
	s_add_u32 m0, s13, 0x18000
	s_nop 0
	global_load_lds_dwordx4 v140, s[14:15]
	global_load_lds_dwordx4 v141, s[14:15] offset:1024
	global_load_lds_dwordx4 v142, s[14:15] offset:2048
	global_load_lds_dwordx4 v143, s[14:15] offset:3072
; template <class AL, class BL>
; DEV void gemm_ktile(Acc& acc, const char* A, const char* B, int wm, int wn, int lr, int lh, const AL& al, const BL& bl,
;                     int tid, int m0, int n0, int knext, char* nxt, R4& ra, R4& rb) {
;   bf16x8 a[2][4], b[2][2];
;   const char* pa = A + (wm + lr) * LDSROW + lh * 16;
;   const char* pb = B + (wn + lr) * LDSROW + lh * 16;
; #pragma unroll
;   for (int i = 0; i < 4; ++i) a[0][i] = *(const bf16x8*)(pa + 32 * i * LDSROW);
; #pragma unroll
;   for (int j = 0; j < 2; ++j) b[0][j] = *(const bf16x8*)(pb + 32 * j * LDSROW);
; #pragma unroll
;   for (int ks = 0; ks < 4; ++ks) {
;     const int cur = ks & 1, nx = cur ^ 1;
;     if (ks < 3) {
; #pragma unroll
;       for (int i = 0; i < 4; ++i) a[nx][i] = *(const bf16x8*)(pa + 32 * i * LDSROW + (ks + 1) * 32);
; #pragma unroll
;       for (int j = 0; j < 2; ++j) b[nx][j] = *(const bf16x8*)(pb + 32 * j * LDSROW + (ks + 1) * 32);
;     }
;     __builtin_amdgcn_sched_barrier(0);
; #pragma unroll
;     for (int i = 0; i < 4; ++i)
; #pragma unroll
;       for (int j = 0; j < 2; ++j)
;         acc[i][j] = __builtin_amdgcn_mfma_f32_32x32x16_bf16(a[cur][i], b[cur][j], acc[i][j], 0, 0, 0);
;     __builtin_amdgcn_sched_barrier(0);
;     if (ks == 1) {
;       al.store(tid, nxt, ra);
;       bl.store(tid, nxt + TILE_BYTES, rb);
;       __builtin_amdgcn_sched_barrier(0);
;       ra = al.load(tid, m0, knext);
;       rb = bl.load(tid, n0, knext);
;       __builtin_amdgcn_sched_barrier(0);
;     }
;   }
; }
.Lff1_d2:
	s_add_u32 s22, s22, 0x80
	s_addc_u32 s23, s23, 0
	s_add_u32 s14, s14, 0x80
	s_addc_u32 s15, s15, 0
	ds_read_b128 v[166:169], v146
	ds_read_b128 v[170:173], v146 offset:2048
	ds_read_b128 v[174:177], v146 offset:4096
	ds_read_b128 v[178:181], v146 offset:6144
	ds_read_b128 v[222:225], v144
	ds_read_b128 v[226:229], v144 offset:2048
	ds_read_b128 v[230:233], v144 offset:4096
	ds_read_b128 v[234:237], v144 offset:6144
	ds_read_b128 v[238:241], v144 offset:8192
	ds_read_b128 v[198:201], v144 offset:10240
	ds_read_b128 v[152:155], v144 offset:12288
	ds_read_b128 v[156:159], v144 offset:14336
	ds_read_b128 v[182:185], v147
	ds_read_b128 v[186:189], v147 offset:2048
	ds_read_b128 v[190:193], v147 offset:4096
	ds_read_b128 v[194:197], v147 offset:6144
	s_waitcnt lgkmcnt(8)
	v_mfma_f32_16x16x32_bf16 v[0:3], v[166:169], v[222:225], v[0:3]
	v_mfma_f32_16x16x32_bf16 v[4:7], v[170:173], v[222:225], v[4:7]
	v_mfma_f32_16x16x32_bf16 v[8:11], v[174:177], v[222:225], v[8:11]
	v_mfma_f32_16x16x32_bf16 v[12:15], v[178:181], v[222:225], v[12:15]
	v_mfma_f32_16x16x32_bf16 v[16:19], v[166:169], v[226:229], v[16:19]
	v_mfma_f32_16x16x32_bf16 v[20:23], v[170:173], v[226:229], v[20:23]
	v_mfma_f32_16x16x32_bf16 v[24:27], v[174:177], v[226:229], v[24:27]
	v_mfma_f32_16x16x32_bf16 v[28:31], v[178:181], v[226:229], v[28:31]
	v_mfma_f32_16x16x32_bf16 v[32:35], v[166:169], v[230:233], v[32:35]
	v_mfma_f32_16x16x32_bf16 v[36:39], v[170:173], v[230:233], v[36:39]
	v_mfma_f32_16x16x32_bf16 v[40:43], v[174:177], v[230:233], v[40:43]
	v_mfma_f32_16x16x32_bf16 v[44:47], v[178:181], v[230:233], v[44:47]
	v_mfma_f32_16x16x32_bf16 v[48:51], v[166:169], v[234:237], v[48:51]
	v_mfma_f32_16x16x32_bf16 v[52:55], v[170:173], v[234:237], v[52:55]
	v_mfma_f32_16x16x32_bf16 v[56:59], v[174:177], v[234:237], v[56:59]
	v_mfma_f32_16x16x32_bf16 v[60:63], v[178:181], v[234:237], v[60:63]
	ds_read_b128 v[222:225], v145
	ds_read_b128 v[226:229], v145 offset:2048
	ds_read_b128 v[230:233], v145 offset:4096
	ds_read_b128 v[234:237], v145 offset:6144
	s_waitcnt lgkmcnt(8)
	v_mfma_f32_16x16x32_bf16 v[64:67], v[166:169], v[238:241], v[64:67]
	v_mfma_f32_16x16x32_bf16 v[68:71], v[170:173], v[238:241], v[68:71]
	v_mfma_f32_16x16x32_bf16 v[72:75], v[174:177], v[238:241], v[72:75]
	v_mfma_f32_16x16x32_bf16 v[76:79], v[178:181], v[238:241], v[76:79]
	v_mfma_f32_16x16x32_bf16 v[80:83], v[166:169], v[198:201], v[80:83]
	v_mfma_f32_16x16x32_bf16 v[84:87], v[170:173], v[198:201], v[84:87]
	v_mfma_f32_16x16x32_bf16 v[88:91], v[174:177], v[198:201], v[88:91]
	v_mfma_f32_16x16x32_bf16 v[92:95], v[178:181], v[198:201], v[92:95]
	v_mfma_f32_16x16x32_bf16 v[96:99], v[166:169], v[152:155], v[96:99]
	v_mfma_f32_16x16x32_bf16 v[100:103], v[170:173], v[152:155], v[100:103]
	v_mfma_f32_16x16x32_bf16 v[104:107], v[174:177], v[152:155], v[104:107]
	v_mfma_f32_16x16x32_bf16 v[108:111], v[178:181], v[152:155], v[108:111]
	v_mfma_f32_16x16x32_bf16 v[112:115], v[166:169], v[156:159], v[112:115]
	v_mfma_f32_16x16x32_bf16 v[116:119], v[170:173], v[156:159], v[116:119]
	v_mfma_f32_16x16x32_bf16 v[120:123], v[174:177], v[156:159], v[120:123]
	v_mfma_f32_16x16x32_bf16 v[124:127], v[178:181], v[156:159], v[124:127]
	ds_read_b128 v[238:241], v145 offset:8192
	ds_read_b128 v[198:201], v145 offset:10240
	ds_read_b128 v[152:155], v145 offset:12288
	ds_read_b128 v[156:159], v145 offset:14336
	s_waitcnt lgkmcnt(4)
	v_mfma_f32_16x16x32_bf16 v[0:3], v[182:185], v[222:225], v[0:3]
	v_mfma_f32_16x16x32_bf16 v[4:7], v[186:189], v[222:225], v[4:7]
	v_mfma_f32_16x16x32_bf16 v[8:11], v[190:193], v[222:225], v[8:11]
	v_mfma_f32_16x16x32_bf16 v[12:15], v[194:197], v[222:225], v[12:15]
	v_mfma_f32_16x16x32_bf16 v[16:19], v[182:185], v[226:229], v[16:19]
	v_mfma_f32_16x16x32_bf16 v[20:23], v[186:189], v[226:229], v[20:23]
	v_mfma_f32_16x16x32_bf16 v[24:27], v[190:193], v[226:229], v[24:27]
	v_mfma_f32_16x16x32_bf16 v[28:31], v[194:197], v[226:229], v[28:31]
	v_mfma_f32_16x16x32_bf16 v[32:35], v[182:185], v[230:233], v[32:35]
	v_mfma_f32_16x16x32_bf16 v[36:39], v[186:189], v[230:233], v[36:39]
	v_mfma_f32_16x16x32_bf16 v[40:43], v[190:193], v[230:233], v[40:43]
	v_mfma_f32_16x16x32_bf16 v[44:47], v[194:197], v[230:233], v[44:47]
	v_mfma_f32_16x16x32_bf16 v[48:51], v[182:185], v[234:237], v[48:51]
	v_mfma_f32_16x16x32_bf16 v[52:55], v[186:189], v[234:237], v[52:55]
	v_mfma_f32_16x16x32_bf16 v[56:59], v[190:193], v[234:237], v[56:59]
	v_mfma_f32_16x16x32_bf16 v[60:63], v[194:197], v[234:237], v[60:63]
	s_waitcnt lgkmcnt(0)
	v_mfma_f32_16x16x32_bf16 v[64:67], v[182:185], v[238:241], v[64:67]
	v_mfma_f32_16x16x32_bf16 v[68:71], v[186:189], v[238:241], v[68:71]
	v_mfma_f32_16x16x32_bf16 v[72:75], v[190:193], v[238:241], v[72:75]
	v_mfma_f32_16x16x32_bf16 v[76:79], v[194:197], v[238:241], v[76:79]
	v_mfma_f32_16x16x32_bf16 v[80:83], v[182:185], v[198:201], v[80:83]
	v_mfma_f32_16x16x32_bf16 v[84:87], v[186:189], v[198:201], v[84:87]
	v_mfma_f32_16x16x32_bf16 v[88:91], v[190:193], v[198:201], v[88:91]
	v_mfma_f32_16x16x32_bf16 v[92:95], v[194:197], v[198:201], v[92:95]
	v_mfma_f32_16x16x32_bf16 v[96:99], v[182:185], v[152:155], v[96:99]
	v_mfma_f32_16x16x32_bf16 v[100:103], v[186:189], v[152:155], v[100:103]
	v_mfma_f32_16x16x32_bf16 v[104:107], v[190:193], v[152:155], v[104:107]
	v_mfma_f32_16x16x32_bf16 v[108:111], v[194:197], v[152:155], v[108:111]
	v_mfma_f32_16x16x32_bf16 v[112:115], v[182:185], v[156:159], v[112:115]
	v_mfma_f32_16x16x32_bf16 v[116:119], v[186:189], v[156:159], v[116:119]
	v_mfma_f32_16x16x32_bf16 v[120:123], v[190:193], v[156:159], v[120:123]
	v_mfma_f32_16x16x32_bf16 v[124:127], v[194:197], v[156:159], v[124:127]
	s_waitcnt vmcnt(0)
	s_barrier
	s_cmp_eq_u32 s17, 7
	s_cbranch_scc1 .Lff1_last
	s_cmp_ge_u32 s13, 0x4000
	s_cbranch_scc0 .Lff1_d3
	s_add_u32 m0, s13, 0xffffc000
	s_nop 0
	global_load_lds_dwordx4 v128, s[22:23]
	global_load_lds_dwordx4 v129, s[22:23] offset:1024
	global_load_lds_dwordx4 v130, s[22:23] offset:2048
	global_load_lds_dwordx4 v131, s[22:23] offset:3072
	s_add_u32 m0, s13, 0xc000
	s_nop 0
	global_load_lds_dwordx4 v132, s[14:15]
	global_load_lds_dwordx4 v133, s[14:15] offset:1024
	global_load_lds_dwordx4 v134, s[14:15] offset:2048
	global_load_lds_dwordx4 v135, s[14:15] offset:3072
	s_add_u32 m0, s13, 0x0
	s_nop 0
	global_load_lds_dwordx4 v136, s[22:23]
	global_load_lds_dwordx4 v137, s[22:23] offset:1024
	global_load_lds_dwordx4 v138, s[22:23] offset:2048
	global_load_lds_dwordx4 v139, s[22:23] offset:3072
	s_add_u32 m0, s13, 0x10000
	s_nop 0
	global_load_lds_dwordx4 v140, s[14:15]
	global_load_lds_dwordx4 v141, s[14:15] offset:1024
	global_load_lds_dwordx4 v142, s[14:15] offset:2048
	global_load_lds_dwordx4 v143, s[14:15] offset:3072

; template <class AL, class BL>
; DEV void gemm_ktile(Acc& acc, const char* A, const char* B, int wm, int wn, int lr, int lh, const AL& al, const BL& bl,
;                     int tid, int m0, int n0, int knext, char* nxt, R4& ra, R4& rb) {
;   bf16x8 a[2][4], b[2][2];
;   const char* pa = A + (wm + lr) * LDSROW + lh * 16;
;   const char* pb = B + (wn + lr) * LDSROW + lh * 16;
; #pragma unroll
;   for (int i = 0; i < 4; ++i) a[0][i] = *(const bf16x8*)(pa + 32 * i * LDSROW);
; #pragma unroll
;   for (int j = 0; j < 2; ++j) b[0][j] = *(const bf16x8*)(pb + 32 * j * LDSROW);
; #pragma unroll
;   for (int ks = 0; ks < 4; ++ks) {
;     const int cur = ks & 1, nx = cur ^ 1;
;     if (ks < 3) {
; #pragma unroll
;       for (int i = 0; i < 4; ++i) a[nx][i] = *(const bf16x8*)(pa + 32 * i * LDSROW + (ks + 1) * 32);
; #pragma unroll
;       for (int j = 0; j < 2; ++j) b[nx][j] = *(const bf16x8*)(pb + 32 * j * LDSROW + (ks + 1) * 32);
;     }
;     __builtin_amdgcn_sched_barrier(0);
; #pragma unroll
;     for (int i = 0; i < 4; ++i)
; #pragma unroll
;       for (int j = 0; j < 2; ++j)
;         acc[i][j] = __builtin_amdgcn_mfma_f32_32x32x16_bf16(a[cur][i], b[cur][j], acc[i][j], 0, 0, 0);
;     __builtin_amdgcn_sched_barrier(0);
; template <class AL, class BL>
; DEV void gemm_mainloop_p(Acc& acc, const AL& al, const BL& bl, int m0, int n0, int m0n, int n0n, int K, char* lds,
;                          GemmPipe& gp) {
;     ...
;   for (int kt = 0; kt < nk; ++kt) {
;     const char* cur = lds + (kt & 1) * 2 * TILE_BYTES;
;     char* nxt = lds + ((kt + 1) & 1) * 2 * TILE_BYTES;
;     const bool wrap = (kt + 2 >= nk);
;     const int kk = (wrap ? kt + 2 - nk : kt + 2) * BK;
;     const int mr = wrap ? m0n : m0, nr = wrap ? n0n : n0;
;     __builtin_amdgcn_sched_barrier(0);
;     gemm_ktile(acc, cur, cur + TILE_BYTES, wm, wn, lr, lh, al, bl, tid, mr, nr, kk, nxt, gp.ra, gp.rb);
;     __builtin_amdgcn_sched_barrier(0);
;     __syncthreads();
;   }
.Lff1_last:
	ds_read_b128 v[166:169], v146 offset:32768
	ds_read_b128 v[170:173], v146 offset:34816
	ds_read_b128 v[174:177], v146 offset:36864
	ds_read_b128 v[178:181], v146 offset:38912
	ds_read_b128 v[222:225], v144 offset:32768
	ds_read_b128 v[226:229], v144 offset:34816
	ds_read_b128 v[230:233], v144 offset:36864
	ds_read_b128 v[234:237], v144 offset:38912
	ds_read_b128 v[238:241], v144 offset:40960
	ds_read_b128 v[198:201], v144 offset:43008
	ds_read_b128 v[152:155], v144 offset:45056
	ds_read_b128 v[156:159], v144 offset:47104
	ds_read_b128 v[182:185], v147 offset:32768
	ds_read_b128 v[186:189], v147 offset:34816
	ds_read_b128 v[190:193], v147 offset:36864
	ds_read_b128 v[194:197], v147 offset:38912
	s_waitcnt lgkmcnt(8)
	v_mfma_f32_16x16x32_bf16 v[0:3], v[166:169], v[222:225], v[0:3]
	v_mfma_f32_16x16x32_bf16 v[4:7], v[170:173], v[222:225], v[4:7]
	v_mfma_f32_16x16x32_bf16 v[8:11], v[174:177], v[222:225], v[8:11]
	v_mfma_f32_16x16x32_bf16 v[12:15], v[178:181], v[222:225], v[12:15]
	v_mfma_f32_16x16x32_bf16 v[16:19], v[166:169], v[226:229], v[16:19]
	v_mfma_f32_16x16x32_bf16 v[20:23], v[170:173], v[226:229], v[20:23]
	v_mfma_f32_16x16x32_bf16 v[24:27], v[174:177], v[226:229], v[24:27]
	v_mfma_f32_16x16x32_bf16 v[28:31], v[178:181], v[226:229], v[28:31]
	v_mfma_f32_16x16x32_bf16 v[32:35], v[166:169], v[230:233], v[32:35]
	v_mfma_f32_16x16x32_bf16 v[36:39], v[170:173], v[230:233], v[36:39]
	v_mfma_f32_16x16x32_bf16 v[40:43], v[174:177], v[230:233], v[40:43]
	v_mfma_f32_16x16x32_bf16 v[44:47], v[178:181], v[230:233], v[44:47]
	v_mfma_f32_16x16x32_bf16 v[48:51], v[166:169], v[234:237], v[48:51]
	v_mfma_f32_16x16x32_bf16 v[52:55], v[170:173], v[234:237], v[52:55]
	v_mfma_f32_16x16x32_bf16 v[56:59], v[174:177], v[234:237], v[56:59]
	v_mfma_f32_16x16x32_bf16 v[60:63], v[178:181], v[234:237], v[60:63]
	ds_read_b128 v[222:225], v145 offset:32768
	ds_read_b128 v[226:229], v145 offset:34816
	ds_read_b128 v[230:233], v145 offset:36864
	ds_read_b128 v[234:237], v145 offset:38912
	s_waitcnt lgkmcnt(8)
	v_mfma_f32_16x16x32_bf16 v[64:67], v[166:169], v[238:241], v[64:67]
	v_mfma_f32_16x16x32_bf16 v[68:71], v[170:173], v[238:241], v[68:71]
	v_mfma_f32_16x16x32_bf16 v[72:75], v[174:177], v[238:241], v[72:75]
	v_mfma_f32_16x16x32_bf16 v[76:79], v[178:181], v[238:241], v[76:79]
	v_mfma_f32_16x16x32_bf16 v[80:83], v[166:169], v[198:201], v[80:83]
	v_mfma_f32_16x16x32_bf16 v[84:87], v[170:173], v[198:201], v[84:87]
	v_mfma_f32_16x16x32_bf16 v[88:91], v[174:177], v[198:201], v[88:91]
	v_mfma_f32_16x16x32_bf16 v[92:95], v[178:181], v[198:201], v[92:95]
	v_mfma_f32_16x16x32_bf16 v[96:99], v[166:169], v[152:155], v[96:99]
	v_mfma_f32_16x16x32_bf16 v[100:103], v[170:173], v[152:155], v[100:103]
	v_mfma_f32_16x16x32_bf16 v[104:107], v[174:177], v[152:155], v[104:107]
	v_mfma_f32_16x16x32_bf16 v[108:111], v[178:181], v[152:155], v[108:111]
	v_mfma_f32_16x16x32_bf16 v[112:115], v[166:169], v[156:159], v[112:115]
	v_mfma_f32_16x16x32_bf16 v[116:119], v[170:173], v[156:159], v[116:119]
	v_mfma_f32_16x16x32_bf16 v[120:123], v[174:177], v[156:159], v[120:123]
	v_mfma_f32_16x16x32_bf16 v[124:127], v[178:181], v[156:159], v[124:127]
	ds_read_b128 v[238:241], v145 offset:40960
	ds_read_b128 v[198:201], v145 offset:43008
	ds_read_b128 v[152:155], v145 offset:45056
	ds_read_b128 v[156:159], v145 offset:47104
	s_waitcnt lgkmcnt(4)
	v_mfma_f32_16x16x32_bf16 v[0:3], v[182:185], v[222:225], v[0:3]
	v_mfma_f32_16x16x32_bf16 v[4:7], v[186:189], v[222:225], v[4:7]
	v_mfma_f32_16x16x32_bf16 v[8:11], v[190:193], v[222:225], v[8:11]
	v_mfma_f32_16x16x32_bf16 v[12:15], v[194:197], v[222:225], v[12:15]
	v_mfma_f32_16x16x32_bf16 v[16:19], v[182:185], v[226:229], v[16:19]
	v_mfma_f32_16x16x32_bf16 v[20:23], v[186:189], v[226:229], v[20:23]
	v_mfma_f32_16x16x32_bf16 v[24:27], v[190:193], v[226:229], v[24:27]
	v_mfma_f32_16x16x32_bf16 v[28:31], v[194:197], v[226:229], v[28:31]
	v_mfma_f32_16x16x32_bf16 v[32:35], v[182:185], v[230:233], v[32:35]
	v_mfma_f32_16x16x32_bf16 v[36:39], v[186:189], v[230:233], v[36:39]
	v_mfma_f32_16x16x32_bf16 v[40:43], v[190:193], v[230:233], v[40:43]
	v_mfma_f32_16x16x32_bf16 v[44:47], v[194:197], v[230:233], v[44:47]
	v_mfma_f32_16x16x32_bf16 v[48:51], v[182:185], v[234:237], v[48:51]
	v_mfma_f32_16x16x32_bf16 v[52:55], v[186:189], v[234:237], v[52:55]
	v_mfma_f32_16x16x32_bf16 v[56:59], v[190:193], v[234:237], v[56:59]
	v_mfma_f32_16x16x32_bf16 v[60:63], v[194:197], v[234:237], v[60:63]
	s_waitcnt lgkmcnt(0)
	v_mfma_f32_16x16x32_bf16 v[64:67], v[182:185], v[238:241], v[64:67]
	v_mfma_f32_16x16x32_bf16 v[68:71], v[186:189], v[238:241], v[68:71]
	v_mfma_f32_16x16x32_bf16 v[72:75], v[190:193], v[238:241], v[72:75]
	v_mfma_f32_16x16x32_bf16 v[76:79], v[194:197], v[238:241], v[76:79]
	v_mfma_f32_16x16x32_bf16 v[80:83], v[182:185], v[198:201], v[80:83]
	v_mfma_f32_16x16x32_bf16 v[84:87], v[186:189], v[198:201], v[84:87]
	v_mfma_f32_16x16x32_bf16 v[88:91], v[190:193], v[198:201], v[88:91]
	v_mfma_f32_16x16x32_bf16 v[92:95], v[194:197], v[198:201], v[92:95]
	v_mfma_f32_16x16x32_bf16 v[96:99], v[182:185], v[152:155], v[96:99]
	v_mfma_f32_16x16x32_bf16 v[100:103], v[186:189], v[152:155], v[100:103]
	v_mfma_f32_16x16x32_bf16 v[104:107], v[190:193], v[152:155], v[104:107]
	v_mfma_f32_16x16x32_bf16 v[108:111], v[194:197], v[152:155], v[108:111]
	v_mfma_f32_16x16x32_bf16 v[112:115], v[182:185], v[156:159], v[112:115]
	v_mfma_f32_16x16x32_bf16 v[116:119], v[186:189], v[156:159], v[116:119]
	v_mfma_f32_16x16x32_bf16 v[120:123], v[190:193], v[156:159], v[120:123]
	v_mfma_f32_16x16x32_bf16 v[124:127], v[194:197], v[156:159], v[124:127]
	s_barrier
; template <class AL, class BL>
; DEV void gemm_mainloop_p(Acc& acc, const AL& al, const BL& bl, int m0, int n0, int m0n, int n0n, int K, char* lds,
;                          GemmPipe& gp) {
;     ...
;     const bool wrap = (kt + 2 >= nk);
;     const int kk = (wrap ? kt + 2 - nk : kt + 2) * BK;
;     const int mr = wrap ? m0n : m0, nr = wrap ? n0n : n0;
;     __builtin_amdgcn_sched_barrier(0);
;     gemm_ktile(acc, cur, cur + TILE_BYTES, wm, wn, lr, lh, al, bl, tid, mr, nr, kk, nxt, gp.ra, gp.rb);
	s_and_b64 vcc, exec, s[0:1]
	s_cbranch_vccz .Lff1_nomore
	s_lshl_b32 s7, s11, 8
	s_lshl_b32 s8, s12, 8
	v_add_u32_e32 v128, s7, v150
	v_lshlrev_b32_e32 v128, 11, v128
	v_add_u32_e32 v128, v128, v151
	v_add_u32_e32 v129, 0x3c00, v128
	v_add_u32_e32 v130, 0x7800, v128
	v_add_u32_e32 v131, 0xb400, v128
	v_xor_b32_e32 v129, 0x40, v129
	v_xor_b32_e32 v131, 0x40, v131
	v_add_u32_e32 v132, s8, v150
	v_lshlrev_b32_e32 v132, 11, v132
	v_add_u32_e32 v132, v132, v151
	v_add_u32_e32 v133, 0x3c00, v132
	v_add_u32_e32 v134, 0x7800, v132
	v_add_u32_e32 v135, 0xb400, v132
	v_xor_b32_e32 v133, 0x40, v133
	v_xor_b32_e32 v135, 0x40, v135
	v_add_u32_e32 v136, 0x40000, v128
	v_add_u32_e32 v137, 0x40000, v129
	v_add_u32_e32 v138, 0x40000, v130
	v_add_u32_e32 v139, 0x40000, v131
	v_add_u32_e32 v140, 0x40000, v132
	v_add_u32_e32 v141, 0x40000, v133
	v_add_u32_e32 v142, 0x40000, v134
	v_add_u32_e32 v143, 0x40000, v135
	s_mov_b64 s[22:23], s[18:19]
	s_mov_b64 s[14:15], s[20:21]
	s_cmp_ge_u32 s13, 0x4000
	s_cbranch_scc0 .Lff1_d4
	s_add_u32 m0, s13, 0xffffc000
	s_nop 0
	global_load_lds_dwordx4 v128, s[22:23]
	global_load_lds_dwordx4 v129, s[22:23] offset:1024
	global_load_lds_dwordx4 v130, s[22:23] offset:2048
	global_load_lds_dwordx4 v131, s[22:23] offset:3072
	s_add_u32 m0, s13, 0xc000
	s_nop 0
	global_load_lds_dwordx4 v132, s[14:15]
	global_load_lds_dwordx4 v133, s[14:15] offset:1024
	global_load_lds_dwordx4 v134, s[14:15] offset:2048
	global_load_lds_dwordx4 v135, s[14:15] offset:3072
	s_add_u32 m0, s13, 0x0
	s_nop 0
	global_load_lds_dwordx4 v136, s[22:23]
	global_load_lds_dwordx4 v137, s[22:23] offset:1024
	global_load_lds_dwordx4 v138, s[22:23] offset:2048
	global_load_lds_dwordx4 v139, s[22:23] offset:3072
	s_add_u32 m0, s13, 0x10000
	s_nop 0
	global_load_lds_dwordx4 v140, s[14:15]
	global_load_lds_dwordx4 v141, s[14:15] offset:1024
	global_load_lds_dwordx4 v142, s[14:15] offset:2048
	global_load_lds_dwordx4 v143, s[14:15] offset:3072

; template <class AL, class BL>
; DEV void gemm_mainloop(Acc& acc, const AL& al, const BL& bl, int m0, int n0, int kbeg, int kend, char* lds) {
;   const int tid = tidx_full();
;   const int wave = tid >> 6, lane = tid & 63;
;   const int wm = (wave >> 2) * 128, wn = (wave & 3) * 64;
;   const int lr = lane & 31, lh = lane >> 5;
;   const int nk = (kend - kbeg) / BK;
;   R4 a0 = al.load(tid, m0, kbeg);
;   R4 b0 = bl.load(tid, n0, kbeg);
;   __syncthreads();
;   al.store(tid, lds, a0);
;   bl.store(tid, lds + TILE_BYTES, b0);
;   a0 = al.load(tid, m0, kbeg + BK);
;   b0 = bl.load(tid, n0, kbeg + BK);
;   __syncthreads();
; DEV void phase_ff2(const Params& p, int g, char* smem) {
;     ...
;     const int m0 = mt * 256, n0 = nt * 256;
;     Acc acc;
;     acc_zero(acc);
;     RowLoader al{AB, 4096}, bl{W, 4096};
;     gemm_mainloop(acc, al, bl, m0, n0, 0, 4096, smem);
.LBB0_1192:
	s_lshl_b32 s3, s5, 8
	s_lshl_b32 s2, s6, 8
	v_readlane_b32 s0, v251, 30
	v_readlane_b32 s1, v251, 31
	s_mov_b64 s[6:7], s[74:75]
	v_lshrrev_b32_e32 v149, 6, v202
	v_and_b32_e32 v148, 63, v202
	s_nop 0
	v_readfirstlane_b32 s8, v149
	v_lshrrev_b32_e32 v150, 3, v148
	v_and_b32_e32 v151, 3, v149
	v_lshl_add_u32 v150, v151, 5, v150
	v_and_b32_e32 v151, 7, v148
	v_lshrrev_b32_e32 v128, 4, v148
	v_xor_b32_e32 v151, v128, v151
	v_lshlrev_b32_e32 v151, 4, v151
	s_lshl_b32 s8, s8, 12
	v_add_u32_e32 v128, s3, v150
	v_lshlrev_b32_e32 v128, 13, v128
	v_add_u32_e32 v128, v128, v151
	v_add_u32_e32 v129, 0xfc00, v128
	v_add_u32_e32 v130, 0x1f800, v128
	v_add_u32_e32 v131, 0x2f400, v128
	v_xor_b32_e32 v129, 0x40, v129
	v_xor_b32_e32 v131, 0x40, v131
	v_add_u32_e32 v132, s2, v150
	v_lshlrev_b32_e32 v132, 13, v132
	v_add_u32_e32 v132, v132, v151
	v_add_u32_e32 v133, 0xfc00, v132
	v_add_u32_e32 v134, 0x1f800, v132
	v_add_u32_e32 v135, 0x2f400, v132
	v_xor_b32_e32 v133, 0x40, v133
	v_xor_b32_e32 v135, 0x40, v135
	v_lshrrev_b32_e32 v150, 1, v148
	v_and_b32_e32 v150, 7, v150
	v_lshrrev_b32_e32 v151, 5, v148
	v_xor_b32_e32 v150, v150, v151
	v_lshlrev_b32_e32 v150, 4, v150
	v_and_b32_e32 v151, 31, v148
	v_lshlrev_b32_e32 v151, 7, v151
	v_lshrrev_b32_e32 v156, 2, v149
	v_lshl_add_u32 v156, v156, 14, v151
	v_and_b32_e32 v207, 3, v149
	v_lshl_add_u32 v207, v207, 13, v151
	v_add_u32_e32 v207, 0x10000, v207
	v_xor_b32_e32 v159, 0x60, v150
	v_add_u32_e32 v159, v156, v159
	v_xor_b32_e32 v158, 0x40, v150
	v_add_u32_e32 v158, v156, v158
	v_xor_b32_e32 v157, 0x20, v150
	v_add_u32_e32 v157, v156, v157
	v_add_u32_e32 v156, v156, v150
	v_xor_b32_e32 v210, 0x60, v150
	v_add_u32_e32 v210, v207, v210
	v_xor_b32_e32 v209, 0x40, v150
	v_add_u32_e32 v209, v207, v209
	v_xor_b32_e32 v208, 0x20, v150
	v_add_u32_e32 v208, v207, v208
	v_add_u32_e32 v207, v207, v150
	v_add_u32_e32 v136, 0x100000, v128
	v_add_u32_e32 v137, 0x100000, v129
	v_add_u32_e32 v138, 0x100000, v130
	v_add_u32_e32 v139, 0x100000, v131
	v_add_u32_e32 v140, 0x100000, v132
	v_add_u32_e32 v141, 0x100000, v133
	v_add_u32_e32 v142, 0x100000, v134
	v_add_u32_e32 v143, 0x100000, v135
	v_lshrrev_b32_e32 v149, 6, v202
	v_and_b32_e32 v148, 63, v202
	v_bfe_u32 v150, v148, 1, 3
	v_lshrrev_b32_e32 v151, 4, v148
	v_xor_b32_e32 v150, v150, v151
	v_lshlrev_b32_e32 v150, 4, v150
	v_and_b32_e32 v151, 15, v148
	v_lshlrev_b32_e32 v151, 7, v151
	v_lshrrev_b32_e32 v144, 2, v149
	v_lshl_add_u32 v144, v144, 14, v151
	v_and_b32_e32 v146, 3, v149
	v_lshl_add_u32 v146, v146, 13, v151
	v_add_u32_e32 v146, 0x10000, v146
	v_xor_b32_e32 v145, 0x40, v150
	v_add_u32_e32 v145, v144, v145
	v_add_u32_e32 v144, v144, v150
	v_xor_b32_e32 v147, 0x40, v150
	v_add_u32_e32 v147, v146, v147
	v_add_u32_e32 v146, v146, v150
	v_mov_b32_e32 v0, 0
	v_mov_b32_e32 v1, 0
	v_mov_b64_e32 v[2:3], v[0:1]
	v_mov_b64_e32 v[4:5], v[0:1]
	v_mov_b64_e32 v[6:7], v[0:1]
	v_mov_b64_e32 v[8:9], v[0:1]
	v_mov_b64_e32 v[10:11], v[0:1]
	v_mov_b64_e32 v[12:13], v[0:1]
	v_mov_b64_e32 v[14:15], v[0:1]
	v_mov_b64_e32 v[16:17], v[0:1]
	v_mov_b64_e32 v[18:19], v[0:1]
	v_mov_b64_e32 v[20:21], v[0:1]
	v_mov_b64_e32 v[22:23], v[0:1]
	v_mov_b64_e32 v[24:25], v[0:1]
	v_mov_b64_e32 v[26:27], v[0:1]
	v_mov_b64_e32 v[28:29], v[0:1]
	v_mov_b64_e32 v[30:31], v[0:1]
	v_mov_b64_e32 v[32:33], v[0:1]
	v_mov_b64_e32 v[34:35], v[0:1]
	v_mov_b64_e32 v[36:37], v[0:1]
	v_mov_b64_e32 v[38:39], v[0:1]
	v_mov_b64_e32 v[40:41], v[0:1]
	v_mov_b64_e32 v[42:43], v[0:1]
	v_mov_b64_e32 v[44:45], v[0:1]
	v_mov_b64_e32 v[46:47], v[0:1]
	v_mov_b64_e32 v[48:49], v[0:1]
	v_mov_b64_e32 v[50:51], v[0:1]
	v_mov_b64_e32 v[52:53], v[0:1]
	v_mov_b64_e32 v[54:55], v[0:1]
	v_mov_b64_e32 v[56:57], v[0:1]
	v_mov_b64_e32 v[58:59], v[0:1]
	v_mov_b64_e32 v[60:61], v[0:1]
	v_mov_b64_e32 v[62:63], v[0:1]
	v_mov_b64_e32 v[64:65], v[0:1]
	v_mov_b64_e32 v[66:67], v[0:1]
	v_mov_b64_e32 v[68:69], v[0:1]
	v_mov_b64_e32 v[70:71], v[0:1]
	v_mov_b64_e32 v[72:73], v[0:1]
	v_mov_b64_e32 v[74:75], v[0:1]
	v_mov_b64_e32 v[76:77], v[0:1]
	v_mov_b64_e32 v[78:79], v[0:1]
	v_mov_b64_e32 v[80:81], v[0:1]
	v_mov_b64_e32 v[82:83], v[0:1]
	v_mov_b64_e32 v[84:85], v[0:1]
	v_mov_b64_e32 v[86:87], v[0:1]
	v_mov_b64_e32 v[88:89], v[0:1]
	v_mov_b64_e32 v[90:91], v[0:1]
	v_mov_b64_e32 v[92:93], v[0:1]
	v_mov_b64_e32 v[94:95], v[0:1]
	v_mov_b64_e32 v[96:97], v[0:1]
	v_mov_b64_e32 v[98:99], v[0:1]
	v_mov_b64_e32 v[100:101], v[0:1]
	v_mov_b64_e32 v[102:103], v[0:1]
	v_mov_b64_e32 v[104:105], v[0:1]
	v_mov_b64_e32 v[106:107], v[0:1]
	v_mov_b64_e32 v[108:109], v[0:1]
	v_mov_b64_e32 v[110:111], v[0:1]
	v_mov_b64_e32 v[112:113], v[0:1]
	v_mov_b64_e32 v[114:115], v[0:1]
	v_mov_b64_e32 v[116:117], v[0:1]
	v_mov_b64_e32 v[118:119], v[0:1]
	v_mov_b64_e32 v[120:121], v[0:1]
	v_mov_b64_e32 v[122:123], v[0:1]
	v_mov_b64_e32 v[124:125], v[0:1]
	v_mov_b64_e32 v[126:127], v[0:1]
	s_cmp_ge_u32 s8, 0x4000
	s_cbranch_scc0 .Lff2_d1
	s_add_u32 m0, s8, 0xffffc000
	s_nop 0
	global_load_lds_dwordx4 v128, s[6:7]
	global_load_lds_dwordx4 v129, s[6:7] offset:1024
	global_load_lds_dwordx4 v130, s[6:7] offset:2048
	global_load_lds_dwordx4 v131, s[6:7] offset:3072
	s_add_u32 m0, s8, 0xc000
	s_nop 0
	global_load_lds_dwordx4 v132, s[0:1]
	global_load_lds_dwordx4 v133, s[0:1] offset:1024
	global_load_lds_dwordx4 v134, s[0:1] offset:2048
	global_load_lds_dwordx4 v135, s[0:1] offset:3072
	s_add_u32 m0, s8, 0x0
	s_nop 0
	global_load_lds_dwordx4 v136, s[6:7]
	global_load_lds_dwordx4 v137, s[6:7] offset:1024
	global_load_lds_dwordx4 v138, s[6:7] offset:2048
	global_load_lds_dwordx4 v139, s[6:7] offset:3072
	s_add_u32 m0, s8, 0x10000
	s_nop 0
	global_load_lds_dwordx4 v140, s[0:1]
	global_load_lds_dwordx4 v141, s[0:1] offset:1024
	global_load_lds_dwordx4 v142, s[0:1] offset:2048
	global_load_lds_dwordx4 v143, s[0:1] offset:3072

; template <class AL, class BL>
; DEV void gemm_ktile(Acc& acc, const char* A, const char* B, int wm, int wn, int lr, int lh, const AL& al, const BL& bl,
;                     int tid, int m0, int n0, int knext, char* nxt, R4& ra, R4& rb) {
;     ...
;     if (ks == 1) {
;       al.store(tid, nxt, ra);
;       bl.store(tid, nxt + TILE_BYTES, rb);
;       __builtin_amdgcn_sched_barrier(0);
;       ra = al.load(tid, m0, knext);
;       rb = bl.load(tid, n0, knext);
;       __builtin_amdgcn_sched_barrier(0);
.Lff2_kloop:
	s_cmp_ge_u32 s8, 0x4000
	s_cbranch_scc0 .Lff2_d2
	s_add_u32 m0, s8, 0x4000
	s_nop 0
	global_load_lds_dwordx4 v128, s[6:7]
	global_load_lds_dwordx4 v129, s[6:7] offset:1024
	global_load_lds_dwordx4 v130, s[6:7] offset:2048
	global_load_lds_dwordx4 v131, s[6:7] offset:3072
	s_add_u32 m0, s8, 0x14000
	s_nop 0
	global_load_lds_dwordx4 v132, s[0:1]
	global_load_lds_dwordx4 v133, s[0:1] offset:1024
	global_load_lds_dwordx4 v134, s[0:1] offset:2048
	global_load_lds_dwordx4 v135, s[0:1] offset:3072
	s_add_u32 m0, s8, 0x8000
	s_nop 0
	global_load_lds_dwordx4 v136, s[6:7]
	global_load_lds_dwordx4 v137, s[6:7] offset:1024
	global_load_lds_dwordx4 v138, s[6:7] offset:2048
	global_load_lds_dwordx4 v139, s[6:7] offset:3072
	s_add_u32 m0, s8, 0x18000
	s_nop 0
	global_load_lds_dwordx4 v140, s[0:1]
	global_load_lds_dwordx4 v141, s[0:1] offset:1024
	global_load_lds_dwordx4 v142, s[0:1] offset:2048
	global_load_lds_dwordx4 v143, s[0:1] offset:3072
; template <class AL, class BL>
; DEV void gemm_ktile(Acc& acc, const char* A, const char* B, int wm, int wn, int lr, int lh, const AL& al, const BL& bl,
;                     int tid, int m0, int n0, int knext, char* nxt, R4& ra, R4& rb) {
;   bf16x8 a[2][4], b[2][2];
;   const char* pa = A + (wm + lr) * LDSROW + lh * 16;
;   const char* pb = B + (wn + lr) * LDSROW + lh * 16;
; #pragma unroll
;   for (int i = 0; i < 4; ++i) a[0][i] = *(const bf16x8*)(pa + 32 * i * LDSROW);
; #pragma unroll
;   for (int j = 0; j < 2; ++j) b[0][j] = *(const bf16x8*)(pb + 32 * j * LDSROW);
; #pragma unroll
;   for (int ks = 0; ks < 4; ++ks) {
;     const int cur = ks & 1, nx = cur ^ 1;
;     if (ks < 3) {
; #pragma unroll
;       for (int i = 0; i < 4; ++i) a[nx][i] = *(const bf16x8*)(pa + 32 * i * LDSROW + (ks + 1) * 32);
; #pragma unroll
;       for (int j = 0; j < 2; ++j) b[nx][j] = *(const bf16x8*)(pb + 32 * j * LDSROW + (ks + 1) * 32);
;     }
;     __builtin_amdgcn_sched_barrier(0);
; #pragma unroll
;     for (int i = 0; i < 4; ++i)
; #pragma unroll
;       for (int j = 0; j < 2; ++j)
;         acc[i][j] = __builtin_amdgcn_mfma_f32_32x32x16_bf16(a[cur][i], b[cur][j], acc[i][j], 0, 0, 0);
;     __builtin_amdgcn_sched_barrier(0);
;     if (ks == 1) {
;       al.store(tid, nxt, ra);
;       bl.store(tid, nxt + TILE_BYTES, rb);
;       __builtin_amdgcn_sched_barrier(0);
;       ra = al.load(tid, m0, knext);
;       rb = bl.load(tid, n0, knext);
;       __builtin_amdgcn_sched_barrier(0);
;     }
;   }
; }
.Lff2_d2:
	s_add_u32 s6, s6, 0x80
	s_addc_u32 s7, s7, 0
	s_add_u32 s0, s0, 0x80
	s_addc_u32 s1, s1, 0
	ds_read_b128 v[166:169], v146
	ds_read_b128 v[170:173], v146 offset:2048
	ds_read_b128 v[174:177], v146 offset:4096
	ds_read_b128 v[178:181], v146 offset:6144
	ds_read_b128 v[222:225], v144
	ds_read_b128 v[226:229], v144 offset:2048
	ds_read_b128 v[230:233], v144 offset:4096
	ds_read_b128 v[234:237], v144 offset:6144
	ds_read_b128 v[238:241], v144 offset:8192
	ds_read_b128 v[242:245], v144 offset:10240
	ds_read_b128 v[198:201], v144 offset:12288
	ds_read_b128 v[152:155], v144 offset:14336
	ds_read_b128 v[182:185], v147
	ds_read_b128 v[186:189], v147 offset:2048
	ds_read_b128 v[190:193], v147 offset:4096
	ds_read_b128 v[194:197], v147 offset:6144
	s_waitcnt lgkmcnt(8)
	v_mfma_f32_16x16x32_bf16 v[0:3], v[166:169], v[222:225], v[0:3]
	v_mfma_f32_16x16x32_bf16 v[4:7], v[170:173], v[222:225], v[4:7]
	v_mfma_f32_16x16x32_bf16 v[8:11], v[174:177], v[222:225], v[8:11]
	v_mfma_f32_16x16x32_bf16 v[12:15], v[178:181], v[222:225], v[12:15]
	v_mfma_f32_16x16x32_bf16 v[16:19], v[166:169], v[226:229], v[16:19]
	v_mfma_f32_16x16x32_bf16 v[20:23], v[170:173], v[226:229], v[20:23]
	v_mfma_f32_16x16x32_bf16 v[24:27], v[174:177], v[226:229], v[24:27]
	v_mfma_f32_16x16x32_bf16 v[28:31], v[178:181], v[226:229], v[28:31]
	v_mfma_f32_16x16x32_bf16 v[32:35], v[166:169], v[230:233], v[32:35]
	v_mfma_f32_16x16x32_bf16 v[36:39], v[170:173], v[230:233], v[36:39]
	v_mfma_f32_16x16x32_bf16 v[40:43], v[174:177], v[230:233], v[40:43]
	v_mfma_f32_16x16x32_bf16 v[44:47], v[178:181], v[230:233], v[44:47]
	v_mfma_f32_16x16x32_bf16 v[48:51], v[166:169], v[234:237], v[48:51]
	v_mfma_f32_16x16x32_bf16 v[52:55], v[170:173], v[234:237], v[52:55]
	v_mfma_f32_16x16x32_bf16 v[56:59], v[174:177], v[234:237], v[56:59]
	v_mfma_f32_16x16x32_bf16 v[60:63], v[178:181], v[234:237], v[60:63]
	ds_read_b128 v[222:225], v145
	ds_read_b128 v[226:229], v145 offset:2048
	ds_read_b128 v[230:233], v145 offset:4096
	ds_read_b128 v[234:237], v145 offset:6144
	s_waitcnt lgkmcnt(8)
	v_mfma_f32_16x16x32_bf16 v[64:67], v[166:169], v[238:241], v[64:67]
	v_mfma_f32_16x16x32_bf16 v[68:71], v[170:173], v[238:241], v[68:71]
	v_mfma_f32_16x16x32_bf16 v[72:75], v[174:177], v[238:241], v[72:75]
	v_mfma_f32_16x16x32_bf16 v[76:79], v[178:181], v[238:241], v[76:79]
	v_mfma_f32_16x16x32_bf16 v[80:83], v[166:169], v[242:245], v[80:83]
	v_mfma_f32_16x16x32_bf16 v[84:87], v[170:173], v[242:245], v[84:87]
	v_mfma_f32_16x16x32_bf16 v[88:91], v[174:177], v[242:245], v[88:91]
	v_mfma_f32_16x16x32_bf16 v[92:95], v[178:181], v[242:245], v[92:95]
	v_mfma_f32_16x16x32_bf16 v[96:99], v[166:169], v[198:201], v[96:99]
	v_mfma_f32_16x16x32_bf16 v[100:103], v[170:173], v[198:201], v[100:103]
	v_mfma_f32_16x16x32_bf16 v[104:107], v[174:177], v[198:201], v[104:107]
	v_mfma_f32_16x16x32_bf16 v[108:111], v[178:181], v[198:201], v[108:111]
	v_mfma_f32_16x16x32_bf16 v[112:115], v[166:169], v[152:155], v[112:115]
	v_mfma_f32_16x16x32_bf16 v[116:119], v[170:173], v[152:155], v[116:119]
	v_mfma_f32_16x16x32_bf16 v[120:123], v[174:177], v[152:155], v[120:123]
	v_mfma_f32_16x16x32_bf16 v[124:127], v[178:181], v[152:155], v[124:127]
	ds_read_b128 v[238:241], v145 offset:8192
	ds_read_b128 v[242:245], v145 offset:10240
	ds_read_b128 v[198:201], v145 offset:12288
	ds_read_b128 v[152:155], v145 offset:14336
	s_waitcnt lgkmcnt(4)
	v_mfma_f32_16x16x32_bf16 v[0:3], v[182:185], v[222:225], v[0:3]
	v_mfma_f32_16x16x32_bf16 v[4:7], v[186:189], v[222:225], v[4:7]
	v_mfma_f32_16x16x32_bf16 v[8:11], v[190:193], v[222:225], v[8:11]
	v_mfma_f32_16x16x32_bf16 v[12:15], v[194:197], v[222:225], v[12:15]
	v_mfma_f32_16x16x32_bf16 v[16:19], v[182:185], v[226:229], v[16:19]
	v_mfma_f32_16x16x32_bf16 v[20:23], v[186:189], v[226:229], v[20:23]
	v_mfma_f32_16x16x32_bf16 v[24:27], v[190:193], v[226:229], v[24:27]
	v_mfma_f32_16x16x32_bf16 v[28:31], v[194:197], v[226:229], v[28:31]
	v_mfma_f32_16x16x32_bf16 v[32:35], v[182:185], v[230:233], v[32:35]
	v_mfma_f32_16x16x32_bf16 v[36:39], v[186:189], v[230:233], v[36:39]
	v_mfma_f32_16x16x32_bf16 v[40:43], v[190:193], v[230:233], v[40:43]
	v_mfma_f32_16x16x32_bf16 v[44:47], v[194:197], v[230:233], v[44:47]
	v_mfma_f32_16x16x32_bf16 v[48:51], v[182:185], v[234:237], v[48:51]
	v_mfma_f32_16x16x32_bf16 v[52:55], v[186:189], v[234:237], v[52:55]
	v_mfma_f32_16x16x32_bf16 v[56:59], v[190:193], v[234:237], v[56:59]
	v_mfma_f32_16x16x32_bf16 v[60:63], v[194:197], v[234:237], v[60:63]
	s_waitcnt lgkmcnt(0)
	v_mfma_f32_16x16x32_bf16 v[64:67], v[182:185], v[238:241], v[64:67]
	v_mfma_f32_16x16x32_bf16 v[68:71], v[186:189], v[238:241], v[68:71]
	v_mfma_f32_16x16x32_bf16 v[72:75], v[190:193], v[238:241], v[72:75]
	v_mfma_f32_16x16x32_bf16 v[76:79], v[194:197], v[238:241], v[76:79]
	v_mfma_f32_16x16x32_bf16 v[80:83], v[182:185], v[242:245], v[80:83]
	v_mfma_f32_16x16x32_bf16 v[84:87], v[186:189], v[242:245], v[84:87]
	v_mfma_f32_16x16x32_bf16 v[88:91], v[190:193], v[242:245], v[88:91]
	v_mfma_f32_16x16x32_bf16 v[92:95], v[194:197], v[242:245], v[92:95]
	v_mfma_f32_16x16x32_bf16 v[96:99], v[182:185], v[198:201], v[96:99]
	v_mfma_f32_16x16x32_bf16 v[100:103], v[186:189], v[198:201], v[100:103]
	v_mfma_f32_16x16x32_bf16 v[104:107], v[190:193], v[198:201], v[104:107]
	v_mfma_f32_16x16x32_bf16 v[108:111], v[194:197], v[198:201], v[108:111]
	v_mfma_f32_16x16x32_bf16 v[112:115], v[182:185], v[152:155], v[112:115]
	v_mfma_f32_16x16x32_bf16 v[116:119], v[186:189], v[152:155], v[116:119]
	v_mfma_f32_16x16x32_bf16 v[120:123], v[190:193], v[152:155], v[120:123]
	v_mfma_f32_16x16x32_bf16 v[124:127], v[194:197], v[152:155], v[124:127]
	s_waitcnt vmcnt(0)
	s_barrier
	s_cmp_eq_u32 s5, 31
	s_cbranch_scc1 .Lff2_last
	s_cmp_ge_u32 s8, 0x4000
	s_cbranch_scc0 .Lff2_d3
	s_add_u32 m0, s8, 0xffffc000
	s_nop 0
	global_load_lds_dwordx4 v128, s[6:7]
	global_load_lds_dwordx4 v129, s[6:7] offset:1024
	global_load_lds_dwordx4 v130, s[6:7] offset:2048
	global_load_lds_dwordx4 v131, s[6:7] offset:3072
	s_add_u32 m0, s8, 0xc000
	s_nop 0
	global_load_lds_dwordx4 v132, s[0:1]
	global_load_lds_dwordx4 v133, s[0:1] offset:1024
	global_load_lds_dwordx4 v134, s[0:1] offset:2048
	global_load_lds_dwordx4 v135, s[0:1] offset:3072
	s_add_u32 m0, s8, 0x0
	s_nop 0
	global_load_lds_dwordx4 v136, s[6:7]
	global_load_lds_dwordx4 v137, s[6:7] offset:1024
	global_load_lds_dwordx4 v138, s[6:7] offset:2048
	global_load_lds_dwordx4 v139, s[6:7] offset:3072
	s_add_u32 m0, s8, 0x10000
	s_nop 0
	global_load_lds_dwordx4 v140, s[0:1]
	global_load_lds_dwordx4 v141, s[0:1] offset:1024
	global_load_lds_dwordx4 v142, s[0:1] offset:2048
	global_load_lds_dwordx4 v143, s[0:1] offset:3072
